# speedup vs baseline: 1.0024x; 1.0024x over previous
; __device__ __forceinline__ float bflo(unsigned w) { return __uint_as_float(w << 16); }
; __device__ __forceinline__ float bfhi(unsigned w) { return __uint_as_float(w & 0xffff0000u); }
; __device__ __forceinline__ void mixer_phase(LAS unsigned char* lds, const u16* z, u16* zg, u16* ya, const float* lbp, const u16* bbt, const u16* cm, const float* Dp,
;                                             const float* cw, const float* cb, int bid, int tid_in) {
;     ...
;         const int R0 = (bid * NWAVES + wave) * 8, c0 = 8 * lane;
;         float w0[8], w1[8], w2[8], bb[8];
; #pragma unroll
;         for (int j = 0; j < 8; ++j) { w0[j] = cw[c0 + j]; w1[j] = cw[512 + c0 + j]; w2[j] = cw[1024 + c0 + j]; bb[j] = cb[c0 + j]; }
;         float vm2[8], vm1[8];
; #pragma unroll
;         for (int j = 0; j < 8; ++j) { vm2[j] = 0.f; vm1[j] = 0.f; }
;         if ((R0 & (SEQ - 1)) != 0) {
;             const u32x4 c2 = *(const u32x4*)(z + (size_t)(R0 - 2) * INC + 512 + c0), v2 = *(const u32x4*)(z + (size_t)(R0 - 2) * INC + 1024 + c0);
;             const u32x4 c1 = *(const u32x4*)(z + (size_t)(R0 - 1) * INC + 512 + c0), v1 = *(const u32x4*)(z + (size_t)(R0 - 1) * INC + 1024 + c0);
; #pragma unroll
;             for (int q = 0; q < 4; ++q) {
;                 vm2[2 * q] = bflo(c2[q]) * bflo(v2[q]); vm2[2 * q + 1] = bfhi(c2[q]) * bfhi(v2[q]);
;                 vm1[2 * q] = bflo(c1[q]) * bflo(v1[q]); vm1[2 * q + 1] = bfhi(c1[q]) * bfhi(v1[q]);
;             }
;         }
;         u32x4 zbv[8], zcv[8], zvv[8];
; #pragma unroll
;         for (int i = 0; i < 8; ++i) { const size_t row = (size_t)(R0 + i); zbv[i] = __builtin_nontemporal_load((const u32x4*)(z + row * INC + c0)); zcv[i] = __builtin_nontemporal_load((const u32x4*)(z + row * INC + 512 + c0)); zvv[i] = __builtin_nontemporal_load((const u32x4*)(z + row * INC + 1024 + c0)); }
.LBB0_642:
	s_ashr_i32 s57, s56, 31
	s_lshl_b64 s[12:13], s[56:57], 12
	s_add_u32 s12, s0, s12
	s_addc_u32 s13, s1, s13
	s_or_b32 s60, s56, 1
	s_ashr_i32 s61, s60, 31
	global_load_dwordx4 v[112:115], v0, s[12:13] offset:2048 nt
	global_load_dwordx4 v[116:119], v0, s[12:13] offset:1024 nt
	global_load_dwordx4 v[70:73], v0, s[12:13] nt
	s_lshl_b64 s[12:13], s[60:61], 12
	s_add_u32 s12, s0, s12
	s_addc_u32 s13, s1, s13
	global_load_dwordx4 v[58:61], v0, s[12:13] nt
	global_load_dwordx4 v[124:127], v0, s[12:13] offset:1024 nt
	global_load_dwordx4 v[128:131], v0, s[12:13] offset:2048 nt
	s_waitcnt vmcnt(13)
	v_mov_b32_e32 v150, v21
	s_waitcnt vmcnt(9)
	v_mov_b32_e32 v151, v53
	v_pk_mul_f32 v[202:203], v[150:151], v[138:139]
	v_and_b32_e32 v27, 64, v231
	v_xor_b32_e32 v26, 16, v231
	v_add_u32_e32 v27, 64, v27
	v_cmp_lt_i32_e32 vcc, v26, v27
	s_or_b32 s58, s56, 2
	s_ashr_i32 s59, s58, 31
	v_cndmask_b32_e32 v26, v231, v26, vcc
	v_lshlrev_b32_e32 v160, 2, v26
	v_xor_b32_e32 v26, 4, v231
	v_cmp_lt_i32_e32 vcc, v26, v27
	s_lshl_b64 s[12:13], s[58:59], 12
	s_add_u32 s12, s0, s12
	v_cndmask_b32_e32 v26, v231, v26, vcc
	v_lshlrev_b32_e32 v162, 2, v26
	v_xor_b32_e32 v26, 1, v231
	v_cmp_lt_i32_e32 vcc, v26, v27
	s_addc_u32 s13, s1, s13
	s_or_b32 s54, s56, 3
	v_cndmask_b32_e32 v26, v231, v26, vcc
	v_lshlrev_b32_e32 v165, 2, v26
	v_xor_b32_e32 v26, 32, v231
	v_cmp_lt_i32_e32 vcc, v26, v27
	s_ashr_i32 s55, s54, 31
	global_load_dwordx4 v[86:89], v0, s[12:13] nt
	global_load_dwordx4 v[98:101], v0, s[12:13] offset:1024 nt
	global_load_dwordx4 v[102:105], v0, s[12:13] offset:2048 nt
	v_cndmask_b32_e32 v26, v231, v26, vcc
	v_lshlrev_b32_e32 v161, 2, v26
	v_xor_b32_e32 v26, 8, v231
	s_lshl_b64 s[12:13], s[54:55], 12
	v_cmp_lt_i32_e32 vcc, v26, v27
	s_add_u32 s12, s0, s12
	s_addc_u32 s13, s1, s13
	v_cndmask_b32_e32 v26, v231, v26, vcc
	v_lshlrev_b32_e32 v163, 2, v26
	v_xor_b32_e32 v26, 2, v231
	global_load_dwordx4 v[82:85], v0, s[12:13] nt
	global_load_dwordx4 v[90:93], v0, s[12:13] offset:1024 nt
	global_load_dwordx4 v[94:97], v0, s[12:13] offset:2048 nt
	v_cmp_lt_i32_e32 vcc, v26, v27
	s_or_b32 s44, s56, 4
	s_ashr_i32 s45, s44, 31
	v_cndmask_b32_e32 v26, v231, v26, vcc
	v_lshlrev_b32_e32 v164, 2, v26
	s_lshl_b64 s[12:13], s[44:45], 12
	s_add_u32 s12, s0, s12
	s_addc_u32 s13, s1, s13
	s_or_b32 s42, s56, 5
	s_ashr_i32 s43, s42, 31
	global_load_dwordx4 v[46:49], v0, s[12:13] nt
	global_load_dwordx4 v[74:77], v0, s[12:13] offset:1024 nt
	global_load_dwordx4 v[78:81], v0, s[12:13] offset:2048 nt
	s_lshl_b64 s[12:13], s[42:43], 12
	s_add_u32 s12, s0, s12
	s_addc_u32 s13, s1, s13
	s_or_b32 s28, s56, 6
	s_ashr_i32 s29, s28, 31
	global_load_dwordx4 v[42:45], v0, s[12:13] nt
	global_load_dwordx4 v[62:65], v0, s[12:13] offset:1024 nt
	global_load_dwordx4 v[66:69], v0, s[12:13] offset:2048 nt
	s_lshl_b64 s[12:13], s[28:29], 12
	s_add_u32 s12, s0, s12
	s_addc_u32 s13, s1, s13
	s_or_b32 s26, s56, 7
	s_ashr_i32 s27, s26, 31
	global_load_dwordx4 v[30:33], v0, s[12:13] nt
	global_load_dwordx4 v[34:37], v0, s[12:13] offset:1024 nt
	global_load_dwordx4 v[38:41], v0, s[12:13] offset:2048 nt
	s_lshl_b64 s[12:13], s[26:27], 12
	s_add_u32 vcc_lo, s0, s12
	s_addc_u32 vcc_hi, s1, s13
	v_lshl_add_u64 v[110:111], s[8:9], 0, v[0:1]
	global_load_dwordx4 v[26:29], v0, vcc nt
	s_lshl_b64 s[12:13], s[56:57], 11
	s_lshl_b64 s[56:57], s[60:61], 11
	s_lshl_b64 s[54:55], s[54:55], 11
	s_lshl_b64 s[42:43], s[42:43], 11
	s_add_i32 s30, s30, s39
	s_waitcnt vmcnt(21)
	v_lshlrev_b32_e32 v120, 16, v112
	v_and_b32_e32 v140, 0xffff0000, v112
	v_lshlrev_b32_e32 v148, 16, v113
	v_and_b32_e32 v156, 0xffff0000, v113
	v_mov_b32_e32 v112, v22
	v_mov_b32_e32 v113, v54
	v_pk_mul_f32 v[182:183], v[112:113], v[122:123]
	v_mov_b32_e32 v112, v23
	v_mov_b32_e32 v113, v55
	v_pk_mul_f32 v[188:189], v[112:113], v[142:143]
	v_mov_b32_e32 v112, v24
	v_mov_b32_e32 v113, v56
	v_pk_mul_f32 v[190:191], v[112:113], v[134:135]
	v_mov_b32_e32 v112, v25
	v_mov_b32_e32 v113, v57
	s_waitcnt vmcnt(20)
	v_lshlrev_b32_e32 v132, 16, v116
	v_and_b32_e32 v146, 0xffff0000, v116
	v_lshlrev_b32_e32 v154, 16, v117
	v_and_b32_e32 v158, 0xffff0000, v117
	v_pk_mul_f32 v[194:195], v[112:113], v[144:145]
	s_waitcnt vmcnt(17)
	v_lshlrev_b32_e32 v133, 16, v124
	s_waitcnt vmcnt(16)
; __device__ __forceinline__ float bflo(unsigned w) { return __uint_as_float(w << 16); }
; __device__ __forceinline__ float bfhi(unsigned w) { return __uint_as_float(w & 0xffff0000u); }
; __device__ __forceinline__ void mixer_phase(LAS unsigned char* lds, const u16* z, u16* zg, u16* ya, const float* lbp, const u16* bbt, const u16* cm, const float* Dp,
;                                             const float* cw, const float* cb, int bid, int tid_in) {
;     ...
;         for (int i = 0; i < 8; ++i) {
;             const size_t row = (size_t)(R0 + i);
;             const u32x4 zb = zbv[i], zc = zcv[i], zv = zvv[i];
;             float v0[8], yv[8]; float ss = 0.f;
; #pragma unroll
;             for (int q = 0; q < 4; ++q) { v0[2 * q] = bflo(zc[q]) * bflo(zv[q]); v0[2 * q + 1] = bfhi(zc[q]) * bfhi(zv[q]); }
; #pragma unroll
;             for (int q = 0; q < 4; ++q) {
;                 const float y0 = w0[2 * q] * vm2[2 * q] + w1[2 * q] * vm1[2 * q] + w2[2 * q] * v0[2 * q] + bb[2 * q];
;                 const float y1 = w0[2 * q + 1] * vm2[2 * q + 1] + w1[2 * q + 1] * vm1[2 * q + 1] + w2[2 * q + 1] * v0[2 * q + 1] + bb[2 * q + 1];
;                 yv[2 * q] = bflo(zb[q]) * y0; yv[2 * q + 1] = bfhi(zb[q]) * y1;
;                 ss += yv[2 * q] * yv[2 * q] + yv[2 * q + 1] * yv[2 * q + 1];
;             }
;             ss = wave_sum(ss);
	v_lshlrev_b32_e32 v121, 16, v128
	v_and_b32_e32 v147, 0xffff0000, v124
	v_and_b32_e32 v141, 0xffff0000, v128
	v_lshlrev_b32_e32 v155, 16, v125
	v_lshlrev_b32_e32 v149, 16, v129
	v_and_b32_e32 v159, 0xffff0000, v125
	v_and_b32_e32 v157, 0xffff0000, v129
	v_pk_mul_f32 v[152:153], v[120:121], v[132:133]
	v_pk_mul_f32 v[150:151], v[140:141], v[146:147]
	v_pk_mul_f32 v[154:155], v[148:149], v[154:155]
	v_pk_mul_f32 v[140:141], v[156:157], v[158:159]
	v_mov_b32_e32 v124, v182
	v_mov_b32_e32 v125, v190
	v_mov_b32_e32 v190, v183
	v_mov_b32_e32 v132, v188
	v_mov_b32_e32 v133, v194
	v_mov_b32_e32 v194, v189
	v_lshlrev_b32_e32 v177, 16, v127
	v_lshlrev_b32_e32 v175, 16, v131
	v_and_b32_e32 v181, 0xffff0000, v127
	v_and_b32_e32 v179, 0xffff0000, v131
	v_mov_b32_e32 v127, v14
	v_mov_b32_e32 v129, v15
	v_mov_b32_e32 v120, v14
	v_mov_b32_e32 v121, v16
	v_mov_b32_e32 v131, v16
	v_pk_add_f32 v[124:125], v[124:125], v[190:191]
	v_pk_add_f32 v[132:133], v[132:133], v[194:195]
	v_mov_b32_e32 v158, v152
	v_mov_b32_e32 v159, v154
	v_mov_b32_e32 v16, v15
	v_mov_b32_e32 v14, v150
	v_mov_b32_e32 v15, v140
	v_lshlrev_b32_e32 v169, 16, v126
	v_lshlrev_b32_e32 v167, 16, v130
	v_and_b32_e32 v173, 0xffff0000, v126
	v_and_b32_e32 v171, 0xffff0000, v130
	v_mov_b32_e32 v126, v22
	v_mov_b32_e32 v130, v24
	v_pk_fma_f32 v[158:159], v[120:121], v[158:159], v[124:125]
	v_mov_b32_e32 v124, v6
	v_mov_b32_e32 v125, v8
	v_pk_fma_f32 v[14:15], v[16:17], v[14:15], v[132:133]
	v_mov_b32_e32 v8, v7
	v_pk_mul_f32 v[204:205], v[126:127], v[152:153]
	v_pk_mul_f32 v[148:149], v[130:131], v[154:155]
	v_lshlrev_b32_e32 v157, 16, v71
	v_lshlrev_b32_e32 v156, 16, v70
	v_and_b32_e32 v71, 0xffff0000, v71
	v_and_b32_e32 v70, 0xffff0000, v70
	v_pk_add_f32 v[158:159], v[124:125], v[158:159]
	v_pk_add_f32 v[6:7], v[8:9], v[14:15]
	v_lshlrev_b32_e32 v168, 16, v118
	v_and_b32_e32 v172, 0xffff0000, v118
	v_lshlrev_b32_e32 v176, 16, v119
	v_and_b32_e32 v180, 0xffff0000, v119
	v_mov_b32_e32 v118, v54
	v_mov_b32_e32 v119, v56
	v_pk_mul_f32 v[156:157], v[158:159], v[156:157]
	v_pk_mul_f32 v[158:159], v[6:7], v[70:71]
	v_mov_b32_e32 v123, v134
	v_mov_b32_e32 v14, v204
	v_mov_b32_e32 v15, v148
	v_mov_b32_e32 v128, v23
	v_pk_mul_f32 v[6:7], v[158:159], v[158:159]
	v_mov_b32_e32 v132, v25
	v_mov_b32_e32 v133, v17
	v_pk_fma_f32 v[14:15], v[118:119], v[122:123], v[14:15]
	v_mov_b32_e32 v148, v205
	v_mov_b32_e32 v112, v18
	v_mov_b32_e32 v113, v50
	v_pk_mul_f32 v[146:147], v[128:129], v[150:151]
	v_pk_fma_f32 v[70:71], v[156:157], v[156:157], v[6:7]
	v_pk_mul_f32 v[6:7], v[132:133], v[140:141]
	v_pk_add_f32 v[14:15], v[14:15], v[148:149]
	v_mov_b32_e32 v116, v55
	v_mov_b32_e32 v117, v57
	v_pk_mul_f32 v[196:197], v[112:113], v[106:107]
	v_mov_b32_e32 v112, v19
	v_mov_b32_e32 v113, v51
	v_pk_add_f32 v[134:135], v[124:125], v[14:15]
	v_mov_b32_e32 v143, v144
	v_mov_b32_e32 v14, v146
	v_mov_b32_e32 v15, v6
	v_pk_mul_f32 v[198:199], v[112:113], v[136:137]
	v_mov_b32_e32 v112, v20
	v_mov_b32_e32 v113, v52
	v_pk_fma_f32 v[14:15], v[116:117], v[142:143], v[14:15]
	v_mov_b32_e32 v6, v147
	v_lshlrev_b32_e32 v166, 16, v114
	v_lshlrev_b32_e32 v174, 16, v115
	v_pk_mul_f32 v[200:201], v[112:113], v[108:109]
	v_pk_add_f32 v[6:7], v[14:15], v[6:7]
	v_and_b32_e32 v170, 0xffff0000, v114
	v_pk_add_f32 v[182:183], v[8:9], v[6:7]
	v_pk_mul_f32 v[142:143], v[166:167], v[168:169]
	v_pk_mul_f32 v[148:149], v[174:175], v[176:177]
	v_mov_b32_e32 v6, v196
	v_mov_b32_e32 v7, v200
	v_mov_b32_e32 v200, v197
	v_pk_mul_f32 v[144:145], v[170:171], v[172:173]
	v_mov_b32_e32 v122, v10
	v_mov_b32_e32 v123, v12
	v_pk_add_f32 v[6:7], v[6:7], v[200:201]
	v_mov_b32_e32 v170, v142
	v_mov_b32_e32 v171, v148
	v_and_b32_e32 v178, 0xffff0000, v115
	v_pk_fma_f32 v[170:171], v[122:123], v[170:171], v[6:7]
	v_mov_b32_e32 v6, v2
	v_mov_b32_e32 v7, v4
	v_pk_mul_f32 v[146:147], v[178:179], v[180:181]
	v_mov_b32_e32 v166, v198
	v_mov_b32_e32 v167, v202
	v_mov_b32_e32 v202, v199
	v_lshlrev_b32_e32 v169, 16, v73
	v_lshlrev_b32_e32 v168, 16, v72
	v_pk_add_f32 v[170:171], v[6:7], v[170:171]
	v_mov_b32_e32 v15, v12
	v_pk_add_f32 v[166:167], v[166:167], v[202:203]
	v_pk_mul_f32 v[168:169], v[170:171], v[168:169]
	v_mov_b32_e32 v12, v11
	v_mov_b32_e32 v170, v144
	v_mov_b32_e32 v171, v146
	v_pk_fma_f32 v[166:167], v[12:13], v[170:171], v[166:167]
	v_mov_b32_e32 v4, v3
	v_and_b32_e32 v73, 0xffff0000, v73
	v_and_b32_e32 v72, 0xffff0000, v72
	v_pk_add_f32 v[2:3], v[4:5], v[166:167]
	v_add_f32_e32 v14, v70, v71
	v_pk_mul_f32 v[166:167], v[2:3], v[72:73]
	v_mov_b32_e32 v114, v50
	v_pk_mul_f32 v[2:3], v[166:167], v[166:167]
	v_mov_b32_e32 v115, v52
	v_pk_fma_f32 v[2:3], v[168:169], v[168:169], v[2:3]
	v_mov_b32_e32 v107, v108
	v_add_f32_e32 v2, v2, v14
	v_add_f32_e32 v14, v3, v2
	ds_bpermute_b32 v70, v165, v14
	v_lshlrev_b32_e32 v3, 16, v59
	v_lshlrev_b32_e32 v2, 16, v58
	v_pk_mul_f32 v[170:171], v[134:135], v[2:3]
	v_and_b32_e32 v3, 0xffff0000, v59
	s_waitcnt lgkmcnt(0)
	v_add_f32_e32 v14, v14, v70
	ds_bpermute_b32 v70, v164, v14
	v_and_b32_e32 v2, 0xffff0000, v58
	v_pk_mul_f32 v[172:173], v[182:183], v[2:3]
	v_mov_b32_e32 v134, v18
	v_pk_mul_f32 v[2:3], v[172:173], v[172:173]
	v_mov_b32_e32 v135, v10
	v_pk_fma_f32 v[58:59], v[170:171], v[170:171], v[2:3]
	s_waitcnt lgkmcnt(0)
	v_add_f32_e32 v2, v14, v70
	ds_bpermute_b32 v3, v162, v2
	v_mov_b32_e32 v14, v20
	v_pk_mul_f32 v[70:71], v[134:135], v[142:143]
	v_pk_mul_f32 v[174:175], v[14:15], v[148:149]
	v_mov_b32_e32 v10, v19
	s_waitcnt lgkmcnt(0)
	v_add_f32_e32 v2, v2, v3
	ds_bpermute_b32 v3, v163, v2
	v_mov_b32_e32 v108, v70
	v_mov_b32_e32 v109, v174
	v_pk_mul_f32 v[72:73], v[10:11], v[144:145]
	v_pk_fma_f32 v[106:107], v[114:115], v[106:107], v[108:109]
	s_waitcnt lgkmcnt(0)
; __device__ __forceinline__ unsigned pk2(float lo, float hi) { unsigned r; asm("v_cvt_pk_bf16_f32 %0, %1, %2" : "=v"(r) : "v"(lo), "v"(hi)); return r; }
; __device__ __forceinline__ float bflo(unsigned w) { return __uint_as_float(w << 16); }
; __device__ __forceinline__ float bfhi(unsigned w) { return __uint_as_float(w & 0xffff0000u); }
; __device__ __forceinline__ void mixer_phase(LAS unsigned char* lds, const u16* z, u16* zg, u16* ya, const float* lbp, const u16* bbt, const u16* cm, const float* Dp,
;                                             const float* cw, const float* cb, int bid, int tid_in) {
;     ...
;             for (int q = 0; q < 4; ++q) {
;                 const float y0 = w0[2 * q] * vm2[2 * q] + w1[2 * q] * vm1[2 * q] + w2[2 * q] * v0[2 * q] + bb[2 * q];
;                 const float y1 = w0[2 * q + 1] * vm2[2 * q + 1] + w1[2 * q + 1] * vm1[2 * q + 1] + w2[2 * q + 1] * v0[2 * q + 1] + bb[2 * q + 1];
;                 yv[2 * q] = bflo(zb[q]) * y0; yv[2 * q + 1] = bfhi(zb[q]) * y1;
;                 ss += yv[2 * q] * yv[2 * q] + yv[2 * q + 1] * yv[2 * q + 1];
;             }
;             ss = wave_sum(ss);
;             const float rstd = rsqrtf(ss * (1.0f / CW) + EPS);
;             u32x4 o;
; #pragma unroll
;             for (int q = 0; q < 4; ++q) o[q] = pk2(yv[2 * q] * rstd, yv[2 * q + 1] * rstd);
;             *(u32x4*)(ya + row * D + c0) = o;
	v_add_f32_e32 v178, v2, v3
	v_mov_b32_e32 v2, v21
	v_mov_b32_e32 v3, v13
	v_pk_mul_f32 v[176:177], v[2:3], v[146:147]
	v_mov_b32_e32 v174, v71
	v_mov_b32_e32 v112, v51
	v_mov_b32_e32 v113, v53
	v_pk_add_f32 v[70:71], v[106:107], v[174:175]
	v_mov_b32_e32 v137, v138
	v_mov_b32_e32 v106, v72
	v_mov_b32_e32 v107, v176
	v_pk_fma_f32 v[106:107], v[112:113], v[136:137], v[106:107]
	v_mov_b32_e32 v176, v73
	v_pk_add_f32 v[72:73], v[106:107], v[176:177]
	v_lshlrev_b32_e32 v107, 16, v61
	v_pk_add_f32 v[72:73], v[4:5], v[72:73]
	v_lshlrev_b32_e32 v106, 16, v60
	v_and_b32_e32 v61, 0xffff0000, v61
	v_and_b32_e32 v60, 0xffff0000, v60
	v_pk_add_f32 v[70:71], v[6:7], v[70:71]
	v_pk_mul_f32 v[138:139], v[72:73], v[60:61]
	v_pk_mul_f32 v[136:137], v[70:71], v[106:107]
	v_pk_mul_f32 v[60:61], v[138:139], v[138:139]
	v_add_f32_e32 v58, v58, v59
	v_pk_fma_f32 v[60:61], v[136:137], v[136:137], v[60:61]
	ds_bpermute_b32 v179, v160, v178
	v_add_f32_e32 v58, v60, v58
	v_add_f32_e32 v106, v61, v58
	ds_bpermute_b32 v107, v165, v106
	global_load_dwordx4 v[58:61], v0, vcc offset:1024 nt
	global_load_dwordx4 v[70:73], v0, vcc offset:2048 nt
	s_waitcnt lgkmcnt(1)
	v_add_f32_e32 v108, v178, v179
	ds_bpermute_b32 v109, v161, v108
	s_waitcnt lgkmcnt(1)
	v_add_f32_e32 v0, v106, v107
	ds_bpermute_b32 v106, v164, v0
	v_lshl_add_u64 v[174:175], v[110:111], 0, s[12:13]
	s_waitcnt vmcnt(15)
	v_and_b32_e32 v176, 0xffff0000, v104
	s_waitcnt lgkmcnt(1)
	v_add_f32_e32 v107, v108, v109
	v_fmamk_f32 v107, v107, 0x3b000000, v230
	s_waitcnt lgkmcnt(0)
	v_add_f32_e32 v0, v0, v106
	ds_bpermute_b32 v106, v162, v0
	v_cmp_gt_f32_e32 vcc, s35, v107
	v_mul_f32_e32 v108, 0x4b800000, v107
	v_lshlrev_b32_e32 v180, 16, v105
	v_cndmask_b32_e32 v107, v107, v108, vcc
	s_waitcnt lgkmcnt(0)
	v_add_f32_e32 v0, v0, v106
	v_rsq_f32_e32 v107, v107
	ds_bpermute_b32 v106, v163, v0
	v_and_b32_e32 v188, 0xffff0000, v105
	v_and_b32_e32 v178, 0xffff0000, v100
	v_mul_f32_e32 v108, 0x45800000, v107
	v_cndmask_b32_e32 v109, v107, v108, vcc
	s_waitcnt lgkmcnt(0)
	v_add_f32_e32 v0, v0, v106
	v_mul_f32_e32 v107, v156, v109
	ds_bpermute_b32 v156, v160, v0
	v_mul_f32_e32 v108, v158, v109
	v_cvt_pk_bf16_f32 v106, v107, v108
	v_mul_f32_e32 v107, v157, v109
	v_mul_f32_e32 v108, v159, v109
	s_waitcnt lgkmcnt(0)
	v_add_f32_e32 v0, v0, v156
	ds_bpermute_b32 v156, v161, v0
	v_cvt_pk_bf16_f32 v107, v107, v108
	v_mul_f32_e32 v108, v168, v109
	v_mul_f32_e32 v157, v166, v109
	v_cvt_pk_bf16_f32 v108, v108, v157
	s_waitcnt lgkmcnt(0)
	v_add_f32_e32 v0, v0, v156
	v_fmamk_f32 v0, v0, 0x3b000000, v230
	v_cmp_gt_f32_e32 vcc, s35, v0
	v_mul_f32_e32 v156, 0x4b800000, v0
	v_mul_f32_e32 v157, v169, v109
	v_cndmask_b32_e32 v0, v0, v156, vcc
	v_rsq_f32_e32 v0, v0
	v_mul_f32_e32 v109, v167, v109
	v_cvt_pk_bf16_f32 v109, v157, v109
	global_store_dwordx4 v[174:175], v[106:109], off sc1
	v_and_b32_e32 v156, 0xffff0000, v98
	v_lshlrev_b32_e32 v166, 16, v99
	v_mul_f32_e32 v106, 0x45800000, v0
	v_cndmask_b32_e32 v0, v0, v106, vcc
	v_mul_f32_e32 v106, v170, v0
	v_mul_f32_e32 v107, v172, v0
	v_cvt_pk_bf16_f32 v106, v106, v107
	v_mul_f32_e32 v107, v171, v0
	v_mul_f32_e32 v108, v173, v0
	v_cvt_pk_bf16_f32 v107, v107, v108
	v_mul_f32_e32 v108, v136, v0
	v_mul_f32_e32 v109, v138, v0
	v_lshlrev_b32_e32 v138, 16, v98
	v_and_b32_e32 v170, 0xffff0000, v99
	v_mov_b32_e32 v98, v54
	v_mov_b32_e32 v99, v22
	v_mov_b32_e32 v22, v55
	v_mov_b32_e32 v54, v56
	v_mov_b32_e32 v55, v24
	v_cvt_pk_bf16_f32 v108, v108, v109
	v_mul_f32_e32 v109, v137, v0
	v_mul_f32_e32 v0, v139, v0
	v_lshlrev_b32_e32 v136, 16, v102
	v_lshlrev_b32_e32 v158, 16, v103
	v_pk_mul_f32 v[194:195], v[98:99], v[152:153]
	v_pk_mul_f32 v[198:199], v[54:55], v[154:155]
	s_waitcnt vmcnt(14)
	v_lshlrev_b32_e32 v139, 16, v90
	s_waitcnt vmcnt(13)
	v_lshlrev_b32_e32 v137, 16, v94
	v_lshlrev_b32_e32 v167, 16, v91
	v_lshlrev_b32_e32 v159, 16, v95
	v_and_b32_e32 v102, 0xffff0000, v102
	v_and_b32_e32 v168, 0xffff0000, v103
	v_lshlrev_b32_e32 v172, 16, v104
	v_mov_b32_e32 v24, v57
	v_mov_b32_e32 v56, v50
	v_mov_b32_e32 v57, v18
	v_mov_b32_e32 v18, v51
	v_and_b32_e32 v157, 0xffff0000, v90
	v_and_b32_e32 v103, 0xffff0000, v94
	v_pk_mul_f32 v[104:105], v[136:137], v[138:139]
	v_pk_mul_f32 v[136:137], v[158:159], v[166:167]
	v_mov_b32_e32 v50, v194
	v_mov_b32_e32 v51, v198
	v_mov_b32_e32 v198, v195
	v_pk_mul_f32 v[102:103], v[102:103], v[156:157]
	v_pk_add_f32 v[50:51], v[50:51], v[198:199]
	v_mov_b32_e32 v156, v104
	v_mov_b32_e32 v157, v136
	v_pk_mul_f32 v[196:197], v[22:23], v[150:151]
	v_pk_mul_f32 v[200:201], v[24:25], v[140:141]
	v_and_b32_e32 v171, 0xffff0000, v91
	v_and_b32_e32 v169, 0xffff0000, v95
	v_pk_fma_f32 v[50:51], v[120:121], v[156:157], v[50:51]
	v_lshlrev_b32_e32 v174, 16, v100
	v_lshlrev_b32_e32 v182, 16, v101
	v_and_b32_e32 v190, 0xffff0000, v101
	v_mov_b32_e32 v100, v52
	v_mov_b32_e32 v101, v20
	v_mov_b32_e32 v20, v53
	v_lshlrev_b32_e32 v175, 16, v92
	v_lshlrev_b32_e32 v173, 16, v96
	v_and_b32_e32 v179, 0xffff0000, v92
	v_and_b32_e32 v177, 0xffff0000, v96
	v_lshlrev_b32_e32 v183, 16, v93
	v_lshlrev_b32_e32 v181, 16, v97
	v_and_b32_e32 v191, 0xffff0000, v93
	v_and_b32_e32 v189, 0xffff0000, v97
	v_pk_mul_f32 v[92:93], v[168:169], v[170:171]
	v_mov_b32_e32 v52, v196
	v_mov_b32_e32 v53, v200
	v_mov_b32_e32 v200, v197
	v_lshlrev_b32_e32 v97, 16, v87
	v_lshlrev_b32_e32 v96, 16, v86
	v_pk_add_f32 v[50:51], v[124:125], v[50:51]
	v_pk_add_f32 v[52:53], v[52:53], v[200:201]
	v_pk_mul_f32 v[50:51], v[50:51], v[96:97]
	v_mov_b32_e32 v96, v102
	v_mov_b32_e32 v97, v92
	v_pk_fma_f32 v[52:53], v[16:17], v[96:97], v[52:53]
	v_and_b32_e32 v87, 0xffff0000, v87
	v_and_b32_e32 v86, 0xffff0000, v86
; __device__ __forceinline__ unsigned pk2(float lo, float hi) { unsigned r; asm("v_cvt_pk_bf16_f32 %0, %1, %2" : "=v"(r) : "v"(lo), "v"(hi)); return r; }
; __device__ __forceinline__ float bflo(unsigned w) { return __uint_as_float(w << 16); }
; __device__ __forceinline__ float bfhi(unsigned w) { return __uint_as_float(w & 0xffff0000u); }
; __device__ __forceinline__ void mixer_phase(LAS unsigned char* lds, const u16* z, u16* zg, u16* ya, const float* lbp, const u16* bbt, const u16* cm, const float* Dp,
;                                             const float* cw, const float* cb, int bid, int tid_in) {
;     ...
;         for (int i = 0; i < 8; ++i) {
;             const size_t row = (size_t)(R0 + i);
;             const u32x4 zb = zbv[i], zc = zcv[i], zv = zvv[i];
;             float v0[8], yv[8]; float ss = 0.f;
; #pragma unroll
;             for (int q = 0; q < 4; ++q) { v0[2 * q] = bflo(zc[q]) * bflo(zv[q]); v0[2 * q + 1] = bfhi(zc[q]) * bfhi(zv[q]); }
; #pragma unroll
;             for (int q = 0; q < 4; ++q) {
;                 const float y0 = w0[2 * q] * vm2[2 * q] + w1[2 * q] * vm1[2 * q] + w2[2 * q] * v0[2 * q] + bb[2 * q];
;                 const float y1 = w0[2 * q + 1] * vm2[2 * q + 1] + w1[2 * q + 1] * vm1[2 * q + 1] + w2[2 * q + 1] * v0[2 * q + 1] + bb[2 * q + 1];
;                 yv[2 * q] = bflo(zb[q]) * y0; yv[2 * q + 1] = bfhi(zb[q]) * y1;
;                 ss += yv[2 * q] * yv[2 * q] + yv[2 * q + 1] * yv[2 * q + 1];
;             }
;             ss = wave_sum(ss);
;             const float rstd = rsqrtf(ss * (1.0f / CW) + EPS);
;             u32x4 o;
; #pragma unroll
;             for (int q = 0; q < 4; ++q) o[q] = pk2(yv[2 * q] * rstd, yv[2 * q + 1] * rstd);
;             *(u32x4*)(ya + row * D + c0) = o;
	v_pk_add_f32 v[52:53], v[8:9], v[52:53]
	v_pk_mul_f32 v[90:91], v[126:127], v[104:105]
	v_pk_mul_f32 v[52:53], v[52:53], v[86:87]
	v_pk_mul_f32 v[94:95], v[130:131], v[136:137]
	v_pk_mul_f32 v[86:87], v[52:53], v[52:53]
	v_pk_mul_f32 v[202:203], v[56:57], v[142:143]
	v_pk_mul_f32 v[206:207], v[100:101], v[148:149]
	v_pk_fma_f32 v[156:157], v[50:51], v[50:51], v[86:87]
	v_mov_b32_e32 v154, v153
	v_mov_b32_e32 v86, v90
	v_mov_b32_e32 v87, v94
	v_pk_fma_f32 v[86:87], v[118:119], v[154:155], v[86:87]
	v_mov_b32_e32 v94, v91
	v_pk_mul_f32 v[90:91], v[172:173], v[174:175]
	v_pk_mul_f32 v[96:97], v[180:181], v[182:183]
	v_mov_b32_e32 v154, v202
	v_mov_b32_e32 v155, v206
	v_mov_b32_e32 v206, v203
	v_pk_add_f32 v[154:155], v[154:155], v[206:207]
	v_mov_b32_e32 v170, v90
	v_mov_b32_e32 v171, v96
	v_pk_mul_f32 v[204:205], v[18:19], v[144:145]
	v_pk_mul_f32 v[208:209], v[20:21], v[146:147]
	v_pk_add_f32 v[86:87], v[86:87], v[94:95]
	v_pk_fma_f32 v[154:155], v[122:123], v[170:171], v[154:155]
	v_pk_add_f32 v[152:153], v[124:125], v[86:87]
	v_pk_mul_f32 v[86:87], v[176:177], v[178:179]
	v_pk_mul_f32 v[94:95], v[188:189], v[190:191]
	v_mov_b32_e32 v166, v204
	v_mov_b32_e32 v167, v208
	v_mov_b32_e32 v208, v205
	v_lshlrev_b32_e32 v169, 16, v89
	v_lshlrev_b32_e32 v168, 16, v88
	v_pk_add_f32 v[154:155], v[6:7], v[154:155]
	v_pk_add_f32 v[166:167], v[166:167], v[208:209]
	v_pk_mul_f32 v[154:155], v[154:155], v[168:169]
	v_mov_b32_e32 v168, v86
	v_mov_b32_e32 v169, v94
	v_pk_fma_f32 v[166:167], v[12:13], v[168:169], v[166:167]
	v_and_b32_e32 v89, 0xffff0000, v89
	v_and_b32_e32 v88, 0xffff0000, v88
	v_pk_add_f32 v[166:167], v[4:5], v[166:167]
	v_cvt_pk_bf16_f32 v109, v109, v0
	v_add_f32_e32 v0, v156, v157
	v_pk_mul_f32 v[88:89], v[166:167], v[88:89]
	v_pk_mul_f32 v[138:139], v[128:129], v[102:103]
	v_pk_mul_f32 v[166:167], v[88:89], v[88:89]
	v_pk_mul_f32 v[158:159], v[132:133], v[92:93]
	v_pk_fma_f32 v[166:167], v[154:155], v[154:155], v[166:167]
	v_mov_b32_e32 v140, v151
	v_add_f32_e32 v0, v166, v0
	v_add_f32_e32 v0, v167, v0
	ds_bpermute_b32 v142, v165, v0
	v_mov_b32_e32 v150, v138
	v_mov_b32_e32 v151, v158
	v_pk_fma_f32 v[140:141], v[116:117], v[140:141], v[150:151]
	v_mov_b32_e32 v158, v139
	s_waitcnt lgkmcnt(0)
	v_add_f32_e32 v0, v0, v142
	ds_bpermute_b32 v142, v164, v0
	v_pk_add_f32 v[138:139], v[140:141], v[158:159]
	v_lshlrev_b32_e32 v141, 16, v83
	v_lshlrev_b32_e32 v140, 16, v82
	v_pk_mul_f32 v[140:141], v[152:153], v[140:141]
	s_waitcnt lgkmcnt(0)
	v_add_f32_e32 v0, v0, v142
	ds_bpermute_b32 v142, v162, v0
	v_pk_mul_f32 v[152:153], v[10:11], v[86:87]
	v_pk_mul_f32 v[158:159], v[2:3], v[94:95]
	v_pk_mul_f32 v[150:151], v[134:135], v[90:91]
	v_pk_mul_f32 v[156:157], v[14:15], v[96:97]
	s_waitcnt lgkmcnt(0)
	v_add_f32_e32 v0, v0, v142
	ds_bpermute_b32 v142, v163, v0
	v_mov_b32_e32 v146, v145
	v_mov_b32_e32 v144, v152
	v_mov_b32_e32 v145, v158
	v_mov_b32_e32 v148, v143
	s_waitcnt lgkmcnt(0)
	v_add_f32_e32 v0, v0, v142
	v_mov_b32_e32 v142, v150
	v_mov_b32_e32 v143, v156
	v_pk_fma_f32 v[144:145], v[112:113], v[146:147], v[144:145]
	v_mov_b32_e32 v158, v153
	v_pk_add_f32 v[138:139], v[8:9], v[138:139]
	v_and_b32_e32 v83, 0xffff0000, v83
	v_and_b32_e32 v82, 0xffff0000, v82
	v_pk_fma_f32 v[142:143], v[114:115], v[148:149], v[142:143]
	v_mov_b32_e32 v156, v151
	v_pk_add_f32 v[144:145], v[144:145], v[158:159]
	v_pk_mul_f32 v[82:83], v[138:139], v[82:83]
	v_pk_add_f32 v[142:143], v[142:143], v[156:157]
	v_pk_add_f32 v[144:145], v[4:5], v[144:145]
	v_lshlrev_b32_e32 v147, 16, v85
	v_lshlrev_b32_e32 v146, 16, v84
	v_and_b32_e32 v85, 0xffff0000, v85
	v_and_b32_e32 v84, 0xffff0000, v84
	v_pk_mul_f32 v[138:139], v[82:83], v[82:83]
	v_pk_add_f32 v[142:143], v[6:7], v[142:143]
	v_pk_mul_f32 v[84:85], v[144:145], v[84:85]
	v_pk_fma_f32 v[138:139], v[140:141], v[140:141], v[138:139]
	v_pk_mul_f32 v[142:143], v[142:143], v[146:147]
	v_pk_mul_f32 v[144:145], v[84:85], v[84:85]
	v_add_f32_e32 v138, v138, v139
	v_pk_fma_f32 v[144:145], v[142:143], v[142:143], v[144:145]
	ds_bpermute_b32 v166, v160, v0
	v_add_f32_e32 v138, v144, v138
	v_add_f32_e32 v144, v145, v138
	ds_bpermute_b32 v145, v165, v144
	v_lshl_add_u64 v[138:139], v[110:111], 0, s[56:57]
	global_store_dwordx4 v[138:139], v[106:109], off sc1
	s_waitcnt lgkmcnt(1)
	v_add_f32_e32 v0, v0, v166
	ds_bpermute_b32 v146, v161, v0
	s_waitcnt lgkmcnt(1)
	v_add_f32_e32 v106, v144, v145
	ds_bpermute_b32 v107, v164, v106
	s_lshl_b64 s[12:13], s[58:59], 11
	s_waitcnt vmcnt(11)
	v_and_b32_e32 v144, 0xffff0000, v80
	s_waitcnt lgkmcnt(1)
	v_add_f32_e32 v0, v0, v146
	v_fmamk_f32 v0, v0, 0x3b000000, v230
	s_waitcnt lgkmcnt(0)
	v_add_f32_e32 v108, v106, v107
	ds_bpermute_b32 v109, v162, v108
	v_cmp_gt_f32_e32 vcc, s35, v0
	v_mul_f32_e32 v106, 0x4b800000, v0
	v_lshlrev_b32_e32 v148, 16, v81
	v_cndmask_b32_e32 v0, v0, v106, vcc
	s_waitcnt lgkmcnt(0)
	v_add_f32_e32 v108, v108, v109
	ds_bpermute_b32 v109, v163, v108
	v_rsq_f32_e32 v0, v0
	v_lshl_add_u64 v[106:107], v[110:111], 0, s[12:13]
	v_and_b32_e32 v152, 0xffff0000, v81
	v_pk_mul_f32 v[158:159], v[54:55], v[136:137]
	s_waitcnt lgkmcnt(0)
	v_add_f32_e32 v108, v108, v109
	ds_bpermute_b32 v109, v160, v108
	v_mul_f32_e32 v138, 0x45800000, v0
	v_cndmask_b32_e32 v0, v0, v138, vcc
	v_mul_f32_e32 v50, v50, v0
	v_mul_f32_e32 v52, v52, v0
	v_cvt_pk_bf16_f32 v50, v50, v52
	v_mul_f32_e32 v52, v53, v0
	s_waitcnt lgkmcnt(0)
	v_add_f32_e32 v53, v108, v109
	ds_bpermute_b32 v108, v161, v53
	v_mul_f32_e32 v51, v51, v0
	v_cvt_pk_bf16_f32 v51, v51, v52
	v_mul_f32_e32 v52, v154, v0
	v_mul_f32_e32 v88, v88, v0
	s_waitcnt lgkmcnt(0)
; __device__ __forceinline__ unsigned pk2(float lo, float hi) { unsigned r; asm("v_cvt_pk_bf16_f32 %0, %1, %2" : "=v"(r) : "v"(lo), "v"(hi)); return r; }
; __device__ __forceinline__ float bflo(unsigned w) { return __uint_as_float(w << 16); }
; __device__ __forceinline__ float bfhi(unsigned w) { return __uint_as_float(w & 0xffff0000u); }
; __device__ __forceinline__ void mixer_phase(LAS unsigned char* lds, const u16* z, u16* zg, u16* ya, const float* lbp, const u16* bbt, const u16* cm, const float* Dp,
;                                             const float* cw, const float* cb, int bid, int tid_in) {
;     ...
;         for (int i = 0; i < 8; ++i) {
;             const size_t row = (size_t)(R0 + i);
;             const u32x4 zb = zbv[i], zc = zcv[i], zv = zvv[i];
;             float v0[8], yv[8]; float ss = 0.f;
; #pragma unroll
;             for (int q = 0; q < 4; ++q) { v0[2 * q] = bflo(zc[q]) * bflo(zv[q]); v0[2 * q + 1] = bfhi(zc[q]) * bfhi(zv[q]); }
; #pragma unroll
;             for (int q = 0; q < 4; ++q) {
;                 const float y0 = w0[2 * q] * vm2[2 * q] + w1[2 * q] * vm1[2 * q] + w2[2 * q] * v0[2 * q] + bb[2 * q];
;                 const float y1 = w0[2 * q + 1] * vm2[2 * q + 1] + w1[2 * q + 1] * vm1[2 * q + 1] + w2[2 * q + 1] * v0[2 * q + 1] + bb[2 * q + 1];
;                 yv[2 * q] = bflo(zb[q]) * y0; yv[2 * q + 1] = bfhi(zb[q]) * y1;
;                 ss += yv[2 * q] * yv[2 * q] + yv[2 * q + 1] * yv[2 * q + 1];
;             }
;             ss = wave_sum(ss);
;             const float rstd = rsqrtf(ss * (1.0f / CW) + EPS);
;             u32x4 o;
; #pragma unroll
;             for (int q = 0; q < 4; ++q) o[q] = pk2(yv[2 * q] * rstd, yv[2 * q + 1] * rstd);
;             *(u32x4*)(ya + row * D + c0) = o;
	v_add_f32_e32 v53, v53, v108
	v_fmamk_f32 v53, v53, 0x3b000000, v230
	v_cmp_gt_f32_e32 vcc, s35, v53
	v_mul_f32_e32 v108, 0x4b800000, v53
	v_cvt_pk_bf16_f32 v52, v52, v88
	v_mul_f32_e32 v88, v155, v0
	v_cndmask_b32_e32 v53, v53, v108, vcc
	v_rsq_f32_e32 v108, v53
	v_mul_f32_e32 v0, v89, v0
	v_cvt_pk_bf16_f32 v53, v88, v0
	global_store_dwordx4 v[106:107], v[50:53], off sc1
	v_mul_f32_e32 v0, 0x45800000, v108
	v_cndmask_b32_e32 v0, v108, v0, vcc
	v_mul_f32_e32 v50, v140, v0
	v_mul_f32_e32 v51, v82, v0
	v_cvt_pk_bf16_f32 v50, v50, v51
	v_mul_f32_e32 v51, v141, v0
	v_mul_f32_e32 v52, v83, v0
	v_cvt_pk_bf16_f32 v51, v51, v52
	v_mul_f32_e32 v52, v142, v0
	v_mul_f32_e32 v53, v84, v0
	v_cvt_pk_bf16_f32 v52, v52, v53
	v_mul_f32_e32 v53, v143, v0
	v_mul_f32_e32 v0, v85, v0
	v_lshlrev_b32_e32 v82, 16, v78
	v_lshlrev_b32_e32 v84, 16, v74
	v_and_b32_e32 v78, 0xffff0000, v78
	v_and_b32_e32 v74, 0xffff0000, v74
	v_lshlrev_b32_e32 v88, 16, v79
	v_lshlrev_b32_e32 v106, 16, v75
	v_and_b32_e32 v108, 0xffff0000, v79
	v_and_b32_e32 v138, 0xffff0000, v75
	v_lshlrev_b32_e32 v140, 16, v80
	v_pk_mul_f32 v[80:81], v[98:99], v[104:105]
	s_waitcnt vmcnt(10)
	v_lshlrev_b32_e32 v85, 16, v62
	s_waitcnt vmcnt(9)
	v_lshlrev_b32_e32 v83, 16, v66
	v_and_b32_e32 v75, 0xffff0000, v62
	v_and_b32_e32 v79, 0xffff0000, v66
	v_lshlrev_b32_e32 v107, 16, v63
	v_lshlrev_b32_e32 v89, 16, v67
	v_lshlrev_b32_e32 v142, 16, v76
	v_and_b32_e32 v146, 0xffff0000, v76
	v_lshlrev_b32_e32 v150, 16, v77
	v_and_b32_e32 v154, 0xffff0000, v77
	v_and_b32_e32 v139, 0xffff0000, v63
	v_pk_mul_f32 v[76:77], v[82:83], v[84:85]
	v_pk_mul_f32 v[62:63], v[78:79], v[74:75]
	v_pk_mul_f32 v[78:79], v[88:89], v[106:107]
	v_mov_b32_e32 v74, v80
	v_mov_b32_e32 v75, v158
	v_mov_b32_e32 v158, v81
	v_pk_mul_f32 v[156:157], v[22:23], v[102:103]
	v_pk_mul_f32 v[166:167], v[24:25], v[92:93]
	v_pk_add_f32 v[74:75], v[74:75], v[158:159]
	v_mov_b32_e32 v88, v76
	v_mov_b32_e32 v89, v78
	v_and_b32_e32 v109, 0xffff0000, v67
	v_mov_b32_e32 v80, v156
	v_mov_b32_e32 v81, v166
	v_mov_b32_e32 v166, v157
	v_pk_fma_f32 v[74:75], v[120:121], v[88:89], v[74:75]
	v_lshlrev_b32_e32 v143, 16, v64
	v_and_b32_e32 v147, 0xffff0000, v64
	v_lshlrev_b32_e32 v151, 16, v65
	v_and_b32_e32 v155, 0xffff0000, v65
	v_pk_mul_f32 v[64:65], v[108:109], v[138:139]
	v_pk_add_f32 v[82:83], v[80:81], v[166:167]
	v_lshlrev_b32_e32 v81, 16, v47
	v_lshlrev_b32_e32 v80, 16, v46
	v_pk_add_f32 v[74:75], v[124:125], v[74:75]
	v_and_b32_e32 v47, 0xffff0000, v47
	v_pk_mul_f32 v[80:81], v[74:75], v[80:81]
	v_mov_b32_e32 v74, v62
	v_mov_b32_e32 v75, v64
	v_pk_fma_f32 v[74:75], v[16:17], v[74:75], v[82:83]
	v_and_b32_e32 v46, 0xffff0000, v46
	v_pk_add_f32 v[74:75], v[8:9], v[74:75]
	v_pk_mul_f32 v[168:169], v[56:57], v[90:91]
	v_pk_mul_f32 v[82:83], v[74:75], v[46:47]
	v_pk_mul_f32 v[172:173], v[100:101], v[96:97]
	v_lshlrev_b32_e32 v141, 16, v68
	v_and_b32_e32 v145, 0xffff0000, v68
	v_lshlrev_b32_e32 v149, 16, v69
	v_and_b32_e32 v153, 0xffff0000, v69
	v_pk_mul_f32 v[66:67], v[126:127], v[76:77]
	v_pk_mul_f32 v[68:69], v[130:131], v[78:79]
	v_pk_mul_f32 v[46:47], v[82:83], v[82:83]
	v_mov_b32_e32 v136, v105
	v_pk_fma_f32 v[88:89], v[80:81], v[80:81], v[46:47]
	v_mov_b32_e32 v46, v66
	v_mov_b32_e32 v47, v68
	v_mov_b32_e32 v68, v67
	v_pk_mul_f32 v[66:67], v[140:141], v[142:143]
	v_pk_mul_f32 v[74:75], v[148:149], v[150:151]
	v_mov_b32_e32 v108, v168
	v_mov_b32_e32 v109, v172
	v_mov_b32_e32 v172, v169
	v_pk_fma_f32 v[46:47], v[118:119], v[136:137], v[46:47]
	v_pk_add_f32 v[108:109], v[108:109], v[172:173]
	v_mov_b32_e32 v140, v66
	v_mov_b32_e32 v141, v74
	v_pk_mul_f32 v[170:171], v[18:19], v[86:87]
	v_pk_mul_f32 v[174:175], v[20:21], v[94:95]
	v_pk_add_f32 v[46:47], v[46:47], v[68:69]
	v_pk_fma_f32 v[108:109], v[122:123], v[140:141], v[108:109]
	v_pk_add_f32 v[104:105], v[124:125], v[46:47]
	v_pk_mul_f32 v[46:47], v[144:145], v[146:147]
	v_pk_mul_f32 v[68:69], v[152:153], v[154:155]
	v_mov_b32_e32 v136, v170
	v_mov_b32_e32 v137, v174
	v_mov_b32_e32 v174, v171
	v_lshlrev_b32_e32 v139, 16, v49
	v_lshlrev_b32_e32 v138, 16, v48
	v_pk_add_f32 v[108:109], v[6:7], v[108:109]
	v_pk_add_f32 v[136:137], v[136:137], v[174:175]
	v_pk_mul_f32 v[108:109], v[108:109], v[138:139]
	v_mov_b32_e32 v138, v46
	v_mov_b32_e32 v139, v68
	v_pk_fma_f32 v[136:137], v[12:13], v[138:139], v[136:137]
	v_and_b32_e32 v49, 0xffff0000, v49
	v_and_b32_e32 v48, 0xffff0000, v48
	v_pk_add_f32 v[136:137], v[4:5], v[136:137]
	v_cvt_pk_bf16_f32 v53, v53, v0
	v_add_f32_e32 v0, v88, v89
	v_pk_mul_f32 v[48:49], v[136:137], v[48:49]
	v_pk_mul_f32 v[84:85], v[128:129], v[62:63]
	v_pk_mul_f32 v[136:137], v[48:49], v[48:49]
	v_pk_mul_f32 v[106:107], v[132:133], v[64:65]
	v_pk_fma_f32 v[136:137], v[108:109], v[108:109], v[136:137]
	v_mov_b32_e32 v92, v103
	v_add_f32_e32 v0, v136, v0
	v_add_f32_e32 v0, v137, v0
	ds_bpermute_b32 v86, v165, v0
	v_mov_b32_e32 v102, v84
	v_mov_b32_e32 v103, v106
	v_pk_fma_f32 v[88:89], v[116:117], v[92:93], v[102:103]
	v_mov_b32_e32 v106, v85
	s_waitcnt lgkmcnt(0)
	v_add_f32_e32 v0, v0, v86
	ds_bpermute_b32 v86, v164, v0
	v_pk_add_f32 v[84:85], v[88:89], v[106:107]
	v_lshlrev_b32_e32 v89, 16, v43
	v_lshlrev_b32_e32 v88, 16, v42
	v_pk_mul_f32 v[102:103], v[10:11], v[46:47]
	s_waitcnt lgkmcnt(0)
	v_add_f32_e32 v0, v0, v86
	ds_bpermute_b32 v86, v162, v0
	v_pk_mul_f32 v[106:107], v[2:3], v[68:69]
	v_pk_mul_f32 v[88:89], v[104:105], v[88:89]
	v_pk_mul_f32 v[92:93], v[134:135], v[66:67]
	v_pk_mul_f32 v[104:105], v[14:15], v[74:75]
	s_waitcnt lgkmcnt(0)
	v_add_f32_e32 v0, v0, v86
	ds_bpermute_b32 v86, v163, v0
	v_mov_b32_e32 v94, v87
	v_mov_b32_e32 v87, v106
	v_mov_b32_e32 v96, v91
	v_mov_b32_e32 v90, v92
	s_waitcnt lgkmcnt(0)
; __device__ __forceinline__ unsigned pk2(float lo, float hi) { unsigned r; asm("v_cvt_pk_bf16_f32 %0, %1, %2" : "=v"(r) : "v"(lo), "v"(hi)); return r; }
; __device__ __forceinline__ float bflo(unsigned w) { return __uint_as_float(w << 16); }
; __device__ __forceinline__ float bfhi(unsigned w) { return __uint_as_float(w & 0xffff0000u); }
; __device__ __forceinline__ void mixer_phase(LAS unsigned char* lds, const u16* z, u16* zg, u16* ya, const float* lbp, const u16* bbt, const u16* cm, const float* Dp,
;                                             const float* cw, const float* cb, int bid, int tid_in) {
;     ...
;         for (int i = 0; i < 8; ++i) {
;             const size_t row = (size_t)(R0 + i);
;             const u32x4 zb = zbv[i], zc = zcv[i], zv = zvv[i];
;             float v0[8], yv[8]; float ss = 0.f;
; #pragma unroll
;             for (int q = 0; q < 4; ++q) { v0[2 * q] = bflo(zc[q]) * bflo(zv[q]); v0[2 * q + 1] = bfhi(zc[q]) * bfhi(zv[q]); }
; #pragma unroll
;             for (int q = 0; q < 4; ++q) {
;                 const float y0 = w0[2 * q] * vm2[2 * q] + w1[2 * q] * vm1[2 * q] + w2[2 * q] * v0[2 * q] + bb[2 * q];
;                 const float y1 = w0[2 * q + 1] * vm2[2 * q + 1] + w1[2 * q + 1] * vm1[2 * q + 1] + w2[2 * q + 1] * v0[2 * q + 1] + bb[2 * q + 1];
;                 yv[2 * q] = bflo(zb[q]) * y0; yv[2 * q + 1] = bfhi(zb[q]) * y1;
;                 ss += yv[2 * q] * yv[2 * q] + yv[2 * q + 1] * yv[2 * q + 1];
;             }
;             ss = wave_sum(ss);
;             const float rstd = rsqrtf(ss * (1.0f / CW) + EPS);
;             u32x4 o;
; #pragma unroll
;             for (int q = 0; q < 4; ++q) o[q] = pk2(yv[2 * q] * rstd, yv[2 * q + 1] * rstd);
;             *(u32x4*)(ya + row * D + c0) = o;
	v_add_f32_e32 v0, v0, v86
	v_mov_b32_e32 v86, v102
	v_mov_b32_e32 v91, v104
	v_pk_fma_f32 v[86:87], v[112:113], v[94:95], v[86:87]
	v_mov_b32_e32 v106, v103
	v_pk_add_f32 v[84:85], v[8:9], v[84:85]
	v_and_b32_e32 v43, 0xffff0000, v43
	v_and_b32_e32 v42, 0xffff0000, v42
	v_pk_fma_f32 v[90:91], v[114:115], v[96:97], v[90:91]
	v_mov_b32_e32 v104, v93
	v_pk_add_f32 v[86:87], v[86:87], v[106:107]
	v_pk_mul_f32 v[84:85], v[84:85], v[42:43]
	v_pk_add_f32 v[90:91], v[90:91], v[104:105]
	v_pk_add_f32 v[86:87], v[4:5], v[86:87]
	v_lshlrev_b32_e32 v93, 16, v45
	v_lshlrev_b32_e32 v92, 16, v44
	v_and_b32_e32 v45, 0xffff0000, v45
	v_and_b32_e32 v44, 0xffff0000, v44
	v_pk_mul_f32 v[42:43], v[84:85], v[84:85]
	v_pk_add_f32 v[90:91], v[6:7], v[90:91]
	v_pk_mul_f32 v[86:87], v[86:87], v[44:45]
	v_pk_fma_f32 v[42:43], v[88:89], v[88:89], v[42:43]
	v_pk_mul_f32 v[90:91], v[90:91], v[92:93]
	v_pk_mul_f32 v[44:45], v[86:87], v[86:87]
	v_add_f32_e32 v42, v42, v43
	v_pk_fma_f32 v[44:45], v[90:91], v[90:91], v[44:45]
	ds_bpermute_b32 v136, v160, v0
	v_add_f32_e32 v42, v44, v42
	v_add_f32_e32 v44, v45, v42
	ds_bpermute_b32 v45, v165, v44
	v_lshl_add_u64 v[42:43], v[110:111], 0, s[54:55]
	global_store_dwordx4 v[42:43], v[50:53], off sc1
	s_waitcnt lgkmcnt(1)
	v_add_f32_e32 v0, v0, v136
	ds_bpermute_b32 v92, v161, v0
	s_waitcnt lgkmcnt(1)
	v_add_f32_e32 v42, v44, v45
	ds_bpermute_b32 v43, v164, v42
	s_lshl_b64 s[12:13], s[44:45], 11
	v_lshl_add_u64 v[50:51], v[110:111], 0, s[12:13]
	s_waitcnt lgkmcnt(1)
	v_add_f32_e32 v0, v0, v92
	v_fmamk_f32 v0, v0, 0x3b000000, v230
	s_waitcnt lgkmcnt(0)
	v_add_f32_e32 v42, v42, v43
	ds_bpermute_b32 v43, v162, v42
	v_cmp_gt_f32_e32 vcc, s35, v0
	v_mul_f32_e32 v44, 0x4b800000, v0
	v_pk_mul_f32 v[98:99], v[98:99], v[76:77]
	v_cndmask_b32_e32 v0, v0, v44, vcc
	s_waitcnt lgkmcnt(0)
	v_add_f32_e32 v42, v42, v43
	ds_bpermute_b32 v43, v163, v42
	v_rsq_f32_e32 v0, v0
	v_pk_mul_f32 v[54:55], v[54:55], v[78:79]
	s_waitcnt vmcnt(8)
	v_lshlrev_b32_e32 v92, 16, v37
	v_and_b32_e32 v96, 0xffff0000, v37
	s_waitcnt lgkmcnt(0)
	v_add_f32_e32 v52, v42, v43
	ds_bpermute_b32 v53, v160, v52
	v_mul_f32_e32 v44, 0x45800000, v0
	v_cndmask_b32_e32 v0, v0, v44, vcc
	v_mul_f32_e32 v45, v82, v0
	v_mul_f32_e32 v44, v80, v0
	v_cvt_pk_bf16_f32 v42, v44, v45
	s_waitcnt lgkmcnt(0)
	v_add_f32_e32 v45, v52, v53
	ds_bpermute_b32 v52, v161, v45
	v_mul_f32_e32 v43, v81, v0
	v_mul_f32_e32 v44, v83, v0
	v_cvt_pk_bf16_f32 v43, v43, v44
	v_mul_f32_e32 v44, v108, v0
	s_waitcnt lgkmcnt(0)
	v_add_f32_e32 v45, v45, v52
	v_fmamk_f32 v45, v45, 0x3b000000, v230
	v_cmp_gt_f32_e32 vcc, s35, v45
	v_mul_f32_e32 v52, 0x4b800000, v45
	v_mul_f32_e32 v48, v48, v0
	v_cndmask_b32_e32 v45, v45, v52, vcc
	v_rsq_f32_e32 v52, v45
	v_cvt_pk_bf16_f32 v44, v44, v48
	v_mul_f32_e32 v48, v109, v0
	v_mul_f32_e32 v0, v49, v0
	v_cvt_pk_bf16_f32 v45, v48, v0
	v_mul_f32_e32 v0, 0x45800000, v52
	v_cndmask_b32_e32 v0, v52, v0, vcc
	global_store_dwordx4 v[50:51], v[42:45], off sc1
	s_waitcnt vmcnt(8)
	v_lshlrev_b32_e32 v48, 16, v38
	v_lshlrev_b32_e32 v50, 16, v34
	v_mul_f32_e32 v42, v88, v0
	v_mul_f32_e32 v43, v84, v0
	v_cvt_pk_bf16_f32 v42, v42, v43
	v_mul_f32_e32 v43, v89, v0
	v_mul_f32_e32 v44, v85, v0
	v_and_b32_e32 v38, 0xffff0000, v38
	v_and_b32_e32 v34, 0xffff0000, v34
	v_lshlrev_b32_e32 v52, 16, v39
	v_lshlrev_b32_e32 v80, 16, v35
	v_and_b32_e32 v82, 0xffff0000, v39
	v_and_b32_e32 v84, 0xffff0000, v35
	v_pk_mul_f32 v[22:23], v[22:23], v[62:63]
	v_pk_mul_f32 v[24:25], v[24:25], v[64:65]
	s_waitcnt vmcnt(6)
	v_and_b32_e32 v35, 0xffff0000, v58
	s_waitcnt vmcnt(5)
	v_and_b32_e32 v39, 0xffff0000, v70
	v_and_b32_e32 v85, 0xffff0000, v59
	v_and_b32_e32 v83, 0xffff0000, v71
	v_lshlrev_b32_e32 v89, 16, v60
	v_and_b32_e32 v37, 0xffff0000, v60
	v_lshlrev_b32_e32 v93, 16, v61
	v_and_b32_e32 v97, 0xffff0000, v61
	v_mov_b32_e32 v60, v98
	v_mov_b32_e32 v61, v54
	v_mov_b32_e32 v54, v99
	v_lshlrev_b32_e32 v51, 16, v58
	v_lshlrev_b32_e32 v81, 16, v59
	v_pk_mul_f32 v[34:35], v[38:39], v[34:35]
	v_pk_mul_f32 v[58:59], v[82:83], v[84:85]
	v_pk_add_f32 v[54:55], v[60:61], v[54:55]
	v_mov_b32_e32 v60, v22
	v_mov_b32_e32 v61, v24
	v_mov_b32_e32 v24, v23
	v_lshlrev_b32_e32 v49, 16, v70
	v_lshlrev_b32_e32 v53, 16, v71
	v_pk_mul_f32 v[38:39], v[128:129], v[34:35]
	v_pk_add_f32 v[22:23], v[60:61], v[24:25]
	v_mov_b32_e32 v35, v58
	v_pk_mul_f32 v[102:103], v[18:19], v[46:47]
	v_pk_mul_f32 v[18:19], v[48:49], v[50:51]
	v_pk_mul_f32 v[50:51], v[52:53], v[80:81]
	v_pk_fma_f32 v[16:17], v[16:17], v[34:35], v[22:23]
	v_pk_mul_f32 v[48:49], v[126:127], v[18:19]
	v_pk_mul_f32 v[52:53], v[130:131], v[50:51]
	v_lshlrev_b32_e32 v25, 16, v31
	v_lshlrev_b32_e32 v24, 16, v30
	v_and_b32_e32 v31, 0xffff0000, v31
	v_and_b32_e32 v30, 0xffff0000, v30
	v_pk_add_f32 v[16:17], v[8:9], v[16:17]
	v_cvt_pk_bf16_f32 v43, v43, v44
	v_mul_f32_e32 v44, v90, v0
	v_mul_f32_e32 v45, v86, v0
	v_lshlrev_b32_e32 v86, 16, v40
	v_lshlrev_b32_e32 v88, 16, v36
	v_and_b32_e32 v40, 0xffff0000, v40
	v_and_b32_e32 v36, 0xffff0000, v36
	v_lshlrev_b32_e32 v90, 16, v41
	v_and_b32_e32 v94, 0xffff0000, v41
	v_pk_mul_f32 v[20:21], v[20:21], v[68:69]
	v_and_b32_e32 v41, 0xffff0000, v72
	v_and_b32_e32 v95, 0xffff0000, v73
	v_mov_b32_e32 v19, v50
	v_pk_mul_f32 v[16:17], v[16:17], v[30:31]
	v_mov_b32_e32 v78, v77
	v_mov_b32_e32 v30, v48
	v_mov_b32_e32 v31, v52
	v_cvt_pk_bf16_f32 v44, v44, v45
	v_mul_f32_e32 v45, v91, v0
	v_mul_f32_e32 v0, v87, v0
	v_pk_mul_f32 v[56:57], v[56:57], v[66:67]
	v_pk_mul_f32 v[100:101], v[100:101], v[74:75]
	v_lshlrev_b32_e32 v87, 16, v72
	v_lshlrev_b32_e32 v91, 16, v73
	v_pk_fma_f32 v[18:19], v[120:121], v[18:19], v[54:55]
; __device__ __forceinline__ unsigned pk2(float lo, float hi) { unsigned r; asm("v_cvt_pk_bf16_f32 %0, %1, %2" : "=v"(r) : "v"(lo), "v"(hi)); return r; }
; __device__ __forceinline__ float bflo(unsigned w) { return __uint_as_float(w << 16); }
; __device__ __forceinline__ float bfhi(unsigned w) { return __uint_as_float(w & 0xffff0000u); }
; __device__ __forceinline__ void mixer_phase(LAS unsigned char* lds, const u16* z, u16* zg, u16* ya, const float* lbp, const u16* bbt, const u16* cm, const float* Dp,
;                                             const float* cw, const float* cb, int bid, int tid_in) {
;     ...
;         for (int i = 0; i < 8; ++i) {
;             const size_t row = (size_t)(R0 + i);
;             const u32x4 zb = zbv[i], zc = zcv[i], zv = zvv[i];
;             float v0[8], yv[8]; float ss = 0.f;
; #pragma unroll
;             for (int q = 0; q < 4; ++q) { v0[2 * q] = bflo(zc[q]) * bflo(zv[q]); v0[2 * q + 1] = bfhi(zc[q]) * bfhi(zv[q]); }
; #pragma unroll
;             for (int q = 0; q < 4; ++q) {
;                 const float y0 = w0[2 * q] * vm2[2 * q] + w1[2 * q] * vm1[2 * q] + w2[2 * q] * v0[2 * q] + bb[2 * q];
;                 const float y1 = w0[2 * q + 1] * vm2[2 * q + 1] + w1[2 * q + 1] * vm1[2 * q + 1] + w2[2 * q + 1] * v0[2 * q + 1] + bb[2 * q + 1];
;                 yv[2 * q] = bflo(zb[q]) * y0; yv[2 * q + 1] = bfhi(zb[q]) * y1;
;                 ss += yv[2 * q] * yv[2 * q] + yv[2 * q + 1] * yv[2 * q + 1];
;             }
;             ss = wave_sum(ss);
;             const float rstd = rsqrtf(ss * (1.0f / CW) + EPS);
;             u32x4 o;
; #pragma unroll
;             for (int q = 0; q < 4; ++q) o[q] = pk2(yv[2 * q] * rstd, yv[2 * q + 1] * rstd);
;             *(u32x4*)(ya + row * D + c0) = o;
; #pragma unroll
;             for (int j = 0; j < 8; ++j) { vm2[j] = vm1[j]; vm1[j] = v0[j]; }
;         }
; __global__ void __launch_bounds__(NTHR, 2) fwd_megakernel(Args a_unused) {
;     ...
;                     for (int task = bid; task < 256; task += G)
	v_pk_fma_f32 v[30:31], v[118:119], v[78:79], v[30:31]
	v_mov_b32_e32 v52, v49
	v_pk_mul_f32 v[36:37], v[40:41], v[36:37]
	v_pk_mul_f32 v[50:51], v[94:95], v[96:97]
	v_mov_b32_e32 v54, v102
	v_mov_b32_e32 v55, v20
	v_mov_b32_e32 v20, v103
	v_pk_add_f32 v[30:31], v[30:31], v[52:53]
	v_pk_mul_f32 v[34:35], v[86:87], v[88:89]
	v_pk_mul_f32 v[10:11], v[10:11], v[36:37]
	v_pk_mul_f32 v[40:41], v[90:91], v[92:93]
	v_mov_b32_e32 v52, v56
	v_mov_b32_e32 v53, v100
	v_mov_b32_e32 v100, v57
	v_pk_add_f32 v[20:21], v[54:55], v[20:21]
	v_mov_b32_e32 v37, v50
	v_pk_mul_f32 v[48:49], v[134:135], v[34:35]
	v_pk_add_f32 v[52:53], v[52:53], v[100:101]
	v_mov_b32_e32 v35, v40
	v_pk_fma_f32 v[12:13], v[12:13], v[36:37], v[20:21]
	v_pk_add_f32 v[18:19], v[124:125], v[18:19]
	v_lshlrev_b32_e32 v55, 16, v33
	v_lshlrev_b32_e32 v54, 16, v32
	v_and_b32_e32 v33, 0xffff0000, v33
	v_and_b32_e32 v32, 0xffff0000, v32
	v_pk_fma_f32 v[34:35], v[122:123], v[34:35], v[52:53]
	v_pk_add_f32 v[12:13], v[4:5], v[12:13]
	v_pk_mul_f32 v[18:19], v[18:19], v[24:25]
	v_pk_mul_f32 v[22:23], v[16:17], v[16:17]
	v_pk_add_f32 v[34:35], v[6:7], v[34:35]
	v_pk_mul_f32 v[12:13], v[12:13], v[32:33]
	v_pk_fma_f32 v[22:23], v[18:19], v[18:19], v[22:23]
	v_pk_mul_f32 v[34:35], v[34:35], v[54:55]
	v_pk_mul_f32 v[20:21], v[12:13], v[12:13]
	v_cvt_pk_bf16_f32 v45, v45, v0
	v_add_f32_e32 v0, v22, v23
	v_pk_fma_f32 v[20:21], v[34:35], v[34:35], v[20:21]
	v_pk_mul_f32 v[24:25], v[132:133], v[58:59]
	v_add_f32_e32 v0, v20, v0
	v_add_f32_e32 v0, v21, v0
	ds_bpermute_b32 v22, v165, v0
	v_mov_b32_e32 v64, v63
	v_mov_b32_e32 v20, v38
	v_mov_b32_e32 v21, v24
	v_pk_fma_f32 v[20:21], v[116:117], v[64:65], v[20:21]
	s_waitcnt lgkmcnt(0)
	v_add_f32_e32 v0, v0, v22
	ds_bpermute_b32 v22, v164, v0
	v_mov_b32_e32 v24, v39
	v_pk_add_f32 v[20:21], v[20:21], v[24:25]
	v_pk_mul_f32 v[14:15], v[14:15], v[40:41]
	v_mov_b32_e32 v74, v67
	s_waitcnt lgkmcnt(0)
	v_add_f32_e32 v0, v0, v22
	ds_bpermute_b32 v24, v162, v0
	v_mov_b32_e32 v25, v14
	v_mov_b32_e32 v14, v49
	v_pk_mul_f32 v[2:3], v[2:3], v[50:51]
	v_mov_b32_e32 v68, v47
	s_waitcnt lgkmcnt(0)
	v_add_f32_e32 v0, v0, v24
	ds_bpermute_b32 v24, v163, v0
	v_pk_add_f32 v[8:9], v[8:9], v[20:21]
	v_and_b32_e32 v23, 0xffff0000, v27
	v_and_b32_e32 v22, 0xffff0000, v26
	v_pk_add_f32 v[30:31], v[124:125], v[30:31]
	s_waitcnt lgkmcnt(0)
	v_add_f32_e32 v0, v0, v24
	v_mov_b32_e32 v24, v48
	v_pk_fma_f32 v[24:25], v[114:115], v[74:75], v[24:25]
	v_lshlrev_b32_e32 v21, 16, v27
	v_pk_add_f32 v[14:15], v[24:25], v[14:15]
	v_lshlrev_b32_e32 v20, 16, v26
	v_pk_add_f32 v[6:7], v[6:7], v[14:15]
	v_mov_b32_e32 v14, v10
	v_mov_b32_e32 v15, v2
	v_pk_fma_f32 v[14:15], v[112:113], v[68:69], v[14:15]
	v_mov_b32_e32 v2, v11
	v_pk_add_f32 v[2:3], v[14:15], v[2:3]
	v_pk_mul_f32 v[8:9], v[8:9], v[22:23]
	v_pk_add_f32 v[2:3], v[4:5], v[2:3]
	v_lshlrev_b32_e32 v5, 16, v29
	v_lshlrev_b32_e32 v4, 16, v28
	v_pk_mul_f32 v[6:7], v[6:7], v[4:5]
	v_and_b32_e32 v5, 0xffff0000, v29
	v_and_b32_e32 v4, 0xffff0000, v28
	v_pk_mul_f32 v[20:21], v[30:31], v[20:21]
	v_pk_mul_f32 v[22:23], v[8:9], v[8:9]
	v_pk_mul_f32 v[10:11], v[2:3], v[4:5]
	v_pk_fma_f32 v[22:23], v[20:21], v[20:21], v[22:23]
	v_pk_mul_f32 v[2:3], v[10:11], v[10:11]
	v_add_f32_e32 v4, v22, v23
	v_pk_fma_f32 v[2:3], v[6:7], v[6:7], v[2:3]
	ds_bpermute_b32 v26, v160, v0
	v_add_f32_e32 v2, v2, v4
	v_add_f32_e32 v4, v3, v2
	ds_bpermute_b32 v5, v165, v4
	v_lshl_add_u64 v[2:3], v[110:111], 0, s[42:43]
	global_store_dwordx4 v[2:3], v[42:45], off sc1
	s_waitcnt lgkmcnt(1)
	v_add_f32_e32 v0, v0, v26
	ds_bpermute_b32 v14, v161, v0
	s_waitcnt lgkmcnt(1)
	v_add_f32_e32 v2, v4, v5
	ds_bpermute_b32 v3, v164, v2
	s_lshl_b64 s[12:13], s[28:29], 11
	s_waitcnt lgkmcnt(1)
	v_add_f32_e32 v0, v0, v14
	v_fmamk_f32 v0, v0, 0x3b000000, v230
	s_waitcnt lgkmcnt(0)
	v_add_f32_e32 v2, v2, v3
	ds_bpermute_b32 v3, v162, v2
	v_cmp_gt_f32_e32 vcc, s35, v0
	v_mul_f32_e32 v4, 0x4b800000, v0
	v_lshl_add_u64 v[14:15], v[110:111], 0, s[12:13]
	v_cndmask_b32_e32 v0, v0, v4, vcc
	v_rsq_f32_e32 v0, v0
	s_waitcnt lgkmcnt(0)
	v_add_f32_e32 v2, v2, v3
	ds_bpermute_b32 v3, v163, v2
	s_lshl_b64 s[12:13], s[26:27], 11
	v_mul_f32_e32 v4, 0x45800000, v0
	v_cndmask_b32_e32 v0, v0, v4, vcc
	v_mul_f32_e32 v5, v16, v0
	s_waitcnt lgkmcnt(0)
	v_add_f32_e32 v16, v2, v3
	v_mul_f32_e32 v4, v18, v0
	ds_bpermute_b32 v18, v160, v16
	v_cvt_pk_bf16_f32 v2, v4, v5
	v_mul_f32_e32 v3, v19, v0
	v_mul_f32_e32 v4, v17, v0
	v_cvt_pk_bf16_f32 v3, v3, v4
	s_waitcnt lgkmcnt(0)
	v_add_f32_e32 v5, v16, v18
	ds_bpermute_b32 v16, v161, v5
	v_mul_f32_e32 v4, v34, v0
	v_mul_f32_e32 v12, v12, v0
	v_cvt_pk_bf16_f32 v4, v4, v12
	v_mul_f32_e32 v12, v35, v0
	s_waitcnt lgkmcnt(0)
	v_add_f32_e32 v5, v5, v16
	v_fmamk_f32 v5, v5, 0x3b000000, v230
	v_cmp_gt_f32_e32 vcc, s35, v5
	v_mul_f32_e32 v16, 0x4b800000, v5
	v_mul_f32_e32 v0, v13, v0
	v_cndmask_b32_e32 v5, v5, v16, vcc
	v_rsq_f32_e32 v16, v5
	v_cvt_pk_bf16_f32 v5, v12, v0
	global_store_dwordx4 v[14:15], v[2:5], off sc1
	v_mul_f32_e32 v0, 0x45800000, v16
	v_cndmask_b32_e32 v0, v16, v0, vcc
	v_mul_f32_e32 v2, v20, v0
	v_mul_f32_e32 v3, v8, v0
	v_cvt_pk_bf16_f32 v2, v2, v3
	v_mul_f32_e32 v3, v21, v0
	v_mul_f32_e32 v4, v9, v0
	v_cvt_pk_bf16_f32 v3, v3, v4
	v_mul_f32_e32 v4, v6, v0
	v_mul_f32_e32 v5, v10, v0
	v_cvt_pk_bf16_f32 v4, v4, v5
	v_mul_f32_e32 v5, v7, v0
	v_lshl_add_u64 v[6:7], v[110:111], 0, s[12:13]
	s_load_dwordx2 s[12:13], s[40:41], 0x108
	v_mul_f32_e32 v0, v11, v0
	v_cvt_pk_bf16_f32 v5, v5, v0
	global_store_dwordx4 v[6:7], v[2:5], off sc1
	s_waitcnt lgkmcnt(0)
	s_add_i32 s49, s49, s12
	s_cmpk_gt_i32 s49, 0xff
	s_cbranch_scc1 .LBB0_676

; #define LAS __attribute__((address_space(3)))
; __device__ __forceinline__ unsigned pk2n(float lo, float hi) { const f32x2 v = {lo, hi}; const bf16x2n b = __builtin_convertvector(v, bf16x2n); return __builtin_bit_cast(unsigned, b); }
; __device__ __forceinline__ float bflo(unsigned w) { return __uint_as_float(w << 16); }
; __device__ __forceinline__ float bfhi(unsigned w) { return __uint_as_float(w & 0xffff0000u); }
; #define CFENCE() asm volatile("" ::: "memory")
; template <bool OUT> ...
;     ...
;         for (int mt = 0; mt < 2; ++mt)
; #pragma unroll
;             for (int nt = 0; nt < 8; ++nt) {
;                 const f32x4 bu = __builtin_amdgcn_mfma_f32_16x16x32_bf16(bfrag[nt], ua[mt], (f32x4){0.f, 0.f, 0.f, 0.f}, 0, 0, 0);
;                 bwp[mt][nt].x = pk2n(bu.x, bu.y); bwp[mt][nt].y = pk2n(bu.z, bu.w);
;             }
;         __builtin_amdgcn_sched_barrier(0);
; #pragma unroll
;         for (int mt = 0; mt < 2; ++mt)
; #pragma unroll
;             for (int nt = 0; nt < 8; ++nt) *(LAS u32x2*)(wl + (16 * mt + fr) * 68 + 8 * nt + 2 * fq) = bwp[mt][nt];
;         DS_GUARD();
;         CFENCE();
;         {
;             f32x2 hv = {hr, hi}; const f32x2 L1 = {lr, lr}, L2 = {-li, li};
;             unsigned cur8[8], nxt8[8], hw8[8];
; #pragma unroll
;             for (int j = 0; j < 8; ++j) cur8[j] = wl[j * 68 + lane];
; #pragma unroll
;             for (int blk = 0; blk < 4; ++blk) {
;                 if (blk < 3) {
; #pragma unroll
;                     for (int j = 0; j < 8; ++j) nxt8[j] = wl[(8 * (blk + 1) + j) * 68 + lane];
;                 }
; #pragma unroll
;                 for (int j = 0; j < 8; ++j) {
;                     const unsigned bw = cur8[j];
;                     const f32x2 bv = {bflo(bw), bfhi(bw)};
;                     const f32x2 hs = __builtin_shufflevector(hv, hv, 1, 0);
;                     hv = __builtin_elementwise_fma(L1, hv, __builtin_elementwise_fma(L2, hs, bv));
;                     if (OUT) hw8[j] = pk2n(hv.x, hv.y);
;                 }
;                 if (OUT) {
;                     __builtin_amdgcn_sched_barrier(0);
; #pragma unroll
;                     for (int j = 0; j < 8; ++j) wl[(8 * blk + j) * 68 + lane] = hw8[j];
;                     DS_GUARD();
;                 }
.LBB0_671:
	s_or_b64 exec, exec, s[12:13]
	s_waitcnt lgkmcnt(1)
	v_mfma_f32_16x16x32_bf16 v[146:149], v[6:9], v[58:61], 0
	v_add_u32_e32 v68, 0x12200, v69
	ds_read_b64 v[68:69], v68
	v_mfma_f32_16x16x32_bf16 v[150:153], v[14:17], v[58:61], 0
	v_mfma_f32_16x16x32_bf16 v[154:157], v[2:5], v[58:61], 0
	v_mfma_f32_16x16x32_bf16 v[158:161], v[10:13], v[58:61], 0
	v_mfma_f32_16x16x32_bf16 v[162:165], v[18:21], v[58:61], 0
	v_mfma_f32_16x16x32_bf16 v[166:169], v[22:25], v[58:61], 0
	v_mfma_f32_16x16x32_bf16 v[170:173], v[26:29], v[58:61], 0
	v_mfma_f32_16x16x32_bf16 v[174:177], v[30:33], v[58:61], 0
	s_waitcnt lgkmcnt(1)
	v_mfma_f32_16x16x32_bf16 v[178:181], v[6:9], v[54:57], 0
	v_mfma_f32_16x16x32_bf16 v[182:185], v[2:5], v[54:57], 0
	v_mfma_f32_16x16x32_bf16 v[186:189], v[10:13], v[54:57], 0
	v_mfma_f32_16x16x32_bf16 v[190:193], v[14:17], v[54:57], 0
	v_mfma_f32_16x16x32_bf16 v[194:197], v[18:21], v[54:57], 0
	v_mfma_f32_16x16x32_bf16 v[198:201], v[22:25], v[54:57], 0
	v_mfma_f32_16x16x32_bf16 v[202:205], v[26:29], v[54:57], 0
	v_mfma_f32_16x16x32_bf16 v[206:209], v[30:33], v[54:57], 0
	v_cvt_pk_bf16_f32 v74, v146, v147
	v_cvt_pk_bf16_f32 v75, v148, v149
	v_cvt_pk_bf16_f32 v76, v154, v155
	v_cvt_pk_bf16_f32 v77, v156, v157
	v_cvt_pk_bf16_f32 v78, v158, v159
	v_cvt_pk_bf16_f32 v79, v160, v161
	v_cvt_pk_bf16_f32 v80, v150, v151
	v_cvt_pk_bf16_f32 v81, v152, v153
	v_cvt_pk_bf16_f32 v104, v162, v163
	v_cvt_pk_bf16_f32 v105, v164, v165
	v_cvt_pk_bf16_f32 v106, v166, v167
	v_cvt_pk_bf16_f32 v107, v168, v169
	v_cvt_pk_bf16_f32 v100, v170, v171
	v_cvt_pk_bf16_f32 v101, v172, v173
	v_cvt_pk_bf16_f32 v102, v174, v175
	v_cvt_pk_bf16_f32 v103, v176, v177
	v_cvt_pk_bf16_f32 v108, v178, v179
	v_cvt_pk_bf16_f32 v109, v180, v181
	v_cvt_pk_bf16_f32 v110, v182, v183
	v_cvt_pk_bf16_f32 v111, v184, v185
	v_cvt_pk_bf16_f32 v112, v186, v187
	v_cvt_pk_bf16_f32 v113, v188, v189
	v_cvt_pk_bf16_f32 v114, v190, v191
	v_cvt_pk_bf16_f32 v115, v192, v193
	v_cvt_pk_bf16_f32 v116, v194, v195
	v_cvt_pk_bf16_f32 v117, v196, v197
	v_cvt_pk_bf16_f32 v118, v198, v199
	v_cvt_pk_bf16_f32 v119, v200, v201
	v_cvt_pk_bf16_f32 v58, v202, v203
	v_cvt_pk_bf16_f32 v59, v204, v205
	v_cvt_pk_bf16_f32 v54, v206, v207
	v_cvt_pk_bf16_f32 v55, v208, v209
	ds_write2_b64 v85, v[74:75], v[76:77] offset1:4
	ds_write2_b64 v85, v[78:79], v[80:81] offset0:8 offset1:12
	ds_write2_b64 v85, v[104:105], v[106:107] offset0:16 offset1:20
	ds_write2_b64 v85, v[100:101], v[102:103] offset0:24 offset1:28
	ds_write2_b64 v86, v[108:109], v[110:111] offset0:32 offset1:36
	ds_write2_b64 v86, v[112:113], v[114:115] offset0:40 offset1:44
	ds_write2_b64 v86, v[116:117], v[118:119] offset0:48 offset1:52
	ds_write2_b64 v86, v[58:59], v[54:55] offset0:56 offset1:60
	s_waitcnt lgkmcnt(0)
	ds_read2_b32 v[54:55], v83 offset1:68
	ds_read2_b32 v[56:57], v83 offset0:136 offset1:204
	ds_read2_b32 v[58:59], v87 offset0:16 offset1:84
	ds_read2_b32 v[60:61], v87 offset0:152 offset1:220
	ds_read2_b32 v[74:75], v88 offset0:32 offset1:100
	ds_read2_b32 v[76:77], v88 offset0:168 offset1:236
	ds_read2_b32 v[78:79], v89 offset0:48 offset1:116
	ds_read2_b32 v[80:81], v89 offset0:184 offset1:252
	s_waitcnt lgkmcnt(7)
	v_lshlrev_b32_e32 v100, 16, v54
	v_and_b32_e32 v101, 0xffff0000, v54
	v_pk_fma_f32 v[100:101], v[66:67], v[72:73], v[100:101] op_sel:[0,1,0] op_sel_hi:[1,0,1]
	v_lshlrev_b32_e32 v54, 16, v55
	v_pk_fma_f32 v[72:73], v[64:65], v[72:73], v[100:101]
	v_and_b32_e32 v55, 0xffff0000, v55
	v_pk_fma_f32 v[54:55], v[66:67], v[72:73], v[54:55] op_sel:[0,1,0] op_sel_hi:[1,0,1]
	v_cvt_pk_bf16_f32 v99, v72, v73
	v_pk_fma_f32 v[54:55], v[64:65], v[72:73], v[54:55]
	s_waitcnt lgkmcnt(6)
	v_lshlrev_b32_e32 v72, 16, v56
	v_and_b32_e32 v73, 0xffff0000, v56
	v_pk_fma_f32 v[72:73], v[66:67], v[54:55], v[72:73] op_sel:[0,1,0] op_sel_hi:[1,0,1]
	v_cvt_pk_bf16_f32 v100, v54, v55
	v_pk_fma_f32 v[54:55], v[64:65], v[54:55], v[72:73]
	v_lshlrev_b32_e32 v56, 16, v57
	v_and_b32_e32 v57, 0xffff0000, v57
	v_pk_fma_f32 v[56:57], v[66:67], v[54:55], v[56:57] op_sel:[0,1,0] op_sel_hi:[1,0,1]
	v_cvt_pk_bf16_f32 v72, v54, v55
	v_pk_fma_f32 v[54:55], v[64:65], v[54:55], v[56:57]
	s_waitcnt lgkmcnt(5)
	v_lshlrev_b32_e32 v56, 16, v58
	v_and_b32_e32 v57, 0xffff0000, v58
	v_pk_fma_f32 v[56:57], v[66:67], v[54:55], v[56:57] op_sel:[0,1,0] op_sel_hi:[1,0,1]
	v_cvt_pk_bf16_f32 v73, v54, v55
	v_pk_fma_f32 v[54:55], v[64:65], v[54:55], v[56:57]
	v_lshlrev_b32_e32 v56, 16, v59
	v_and_b32_e32 v57, 0xffff0000, v59
	v_pk_fma_f32 v[56:57], v[66:67], v[54:55], v[56:57] op_sel:[0,1,0] op_sel_hi:[1,0,1]
	v_cvt_pk_bf16_f32 v58, v54, v55
	v_pk_fma_f32 v[54:55], v[64:65], v[54:55], v[56:57]
	s_waitcnt lgkmcnt(4)
	v_lshlrev_b32_e32 v56, 16, v60
	v_and_b32_e32 v57, 0xffff0000, v60
	v_pk_fma_f32 v[56:57], v[66:67], v[54:55], v[56:57] op_sel:[0,1,0] op_sel_hi:[1,0,1]
	v_cvt_pk_bf16_f32 v59, v54, v55
	v_pk_fma_f32 v[54:55], v[64:65], v[54:55], v[56:57]
	v_lshlrev_b32_e32 v56, 16, v61
	v_and_b32_e32 v57, 0xffff0000, v61
	v_pk_fma_f32 v[56:57], v[66:67], v[54:55], v[56:57] op_sel:[0,1,0] op_sel_hi:[1,0,1]
	v_cvt_pk_bf16_f32 v60, v54, v55
	v_pk_fma_f32 v[54:55], v[64:65], v[54:55], v[56:57]
	s_nop 0
	v_cvt_pk_bf16_f32 v56, v54, v55
	ds_write2_b32 v83, v99, v100 offset1:68
	ds_write2_b32 v83, v72, v73 offset0:136 offset1:204
	ds_write2_b32 v87, v58, v59 offset0:16 offset1:84
	ds_write2_b32 v87, v60, v56 offset0:152 offset1:220
	s_waitcnt lgkmcnt(0)
	s_waitcnt lgkmcnt(7)
; __device__ __forceinline__ unsigned pk2n(float lo, float hi) { const f32x2 v = {lo, hi}; const bf16x2n b = __builtin_convertvector(v, bf16x2n); return __builtin_bit_cast(unsigned, b); }
; __device__ __forceinline__ float bflo(unsigned w) { return __uint_as_float(w << 16); }
; __device__ __forceinline__ float bfhi(unsigned w) { return __uint_as_float(w & 0xffff0000u); }
; #define DS_GUARD() do { __builtin_amdgcn_sched_barrier(0); asm volatile("s_waitcnt lgkmcnt(0)" ::: "memory"); __builtin_amdgcn_sched_barrier(0); } while (0)
; template <bool OUT> ...
;     ...
;             for (int blk = 0; blk < 4; ++blk) {
;                 if (blk < 3) {
; #pragma unroll
;                     for (int j = 0; j < 8; ++j) nxt8[j] = wl[(8 * (blk + 1) + j) * 68 + lane];
;                 }
; #pragma unroll
;                 for (int j = 0; j < 8; ++j) {
;                     const unsigned bw = cur8[j];
;                     const f32x2 bv = {bflo(bw), bfhi(bw)};
;                     const f32x2 hs = __builtin_shufflevector(hv, hv, 1, 0);
;                     hv = __builtin_elementwise_fma(L1, hv, __builtin_elementwise_fma(L2, hs, bv));
;                     if (OUT) hw8[j] = pk2n(hv.x, hv.y);
;                 }
;                 if (OUT) {
;                     __builtin_amdgcn_sched_barrier(0);
; #pragma unroll
;                     for (int j = 0; j < 8; ++j) wl[(8 * blk + j) * 68 + lane] = hw8[j];
;                     DS_GUARD();
;                 }
; #pragma unroll
;                 for (int j = 0; j < 8; ++j) cur8[j] = nxt8[j];
	v_lshlrev_b32_e32 v100, 16, v74
	v_and_b32_e32 v101, 0xffff0000, v74
	v_pk_fma_f32 v[100:101], v[66:67], v[54:55], v[100:101] op_sel:[0,1,0] op_sel_hi:[1,0,1]
	v_lshlrev_b32_e32 v74, 16, v75
	v_pk_fma_f32 v[54:55], v[64:65], v[54:55], v[100:101]
	v_and_b32_e32 v75, 0xffff0000, v75
	v_pk_fma_f32 v[74:75], v[66:67], v[54:55], v[74:75] op_sel:[0,1,0] op_sel_hi:[1,0,1]
	v_cvt_pk_bf16_f32 v99, v54, v55
	v_pk_fma_f32 v[54:55], v[64:65], v[54:55], v[74:75]
	s_waitcnt lgkmcnt(6)
	v_lshlrev_b32_e32 v74, 16, v76
	v_and_b32_e32 v75, 0xffff0000, v76
	v_pk_fma_f32 v[74:75], v[66:67], v[54:55], v[74:75] op_sel:[0,1,0] op_sel_hi:[1,0,1]
	v_cvt_pk_bf16_f32 v100, v54, v55
	v_pk_fma_f32 v[54:55], v[64:65], v[54:55], v[74:75]
	v_lshlrev_b32_e32 v74, 16, v77
	v_and_b32_e32 v75, 0xffff0000, v77
	v_pk_fma_f32 v[74:75], v[66:67], v[54:55], v[74:75] op_sel:[0,1,0] op_sel_hi:[1,0,1]
	v_cvt_pk_bf16_f32 v76, v54, v55
	v_pk_fma_f32 v[54:55], v[64:65], v[54:55], v[74:75]
	s_waitcnt lgkmcnt(5)
	v_lshlrev_b32_e32 v74, 16, v78
	v_and_b32_e32 v75, 0xffff0000, v78
	v_pk_fma_f32 v[74:75], v[66:67], v[54:55], v[74:75] op_sel:[0,1,0] op_sel_hi:[1,0,1]
	ds_read2_b32 v[56:57], v90 offset0:64 offset1:132
	ds_read2_b32 v[58:59], v91 offset0:72 offset1:140
	ds_read2_b32 v[60:61], v92 offset0:80 offset1:148
	ds_read2_b32 v[72:73], v93 offset0:88 offset1:156
	v_cvt_pk_bf16_f32 v77, v54, v55
	v_pk_fma_f32 v[54:55], v[64:65], v[54:55], v[74:75]
	v_lshlrev_b32_e32 v74, 16, v79
	v_and_b32_e32 v75, 0xffff0000, v79
	v_pk_fma_f32 v[74:75], v[66:67], v[54:55], v[74:75] op_sel:[0,1,0] op_sel_hi:[1,0,1]
	v_cvt_pk_bf16_f32 v78, v54, v55
	v_pk_fma_f32 v[54:55], v[64:65], v[54:55], v[74:75]
	s_waitcnt lgkmcnt(8)
	v_lshlrev_b32_e32 v74, 16, v80
	v_and_b32_e32 v75, 0xffff0000, v80
	v_pk_fma_f32 v[74:75], v[66:67], v[54:55], v[74:75] op_sel:[0,1,0] op_sel_hi:[1,0,1]
	v_cvt_pk_bf16_f32 v79, v54, v55
	v_pk_fma_f32 v[54:55], v[64:65], v[54:55], v[74:75]
	v_lshlrev_b32_e32 v74, 16, v81
	v_and_b32_e32 v75, 0xffff0000, v81
	v_pk_fma_f32 v[74:75], v[66:67], v[54:55], v[74:75] op_sel:[0,1,0] op_sel_hi:[1,0,1]
	v_cvt_pk_bf16_f32 v80, v54, v55
	v_pk_fma_f32 v[54:55], v[64:65], v[54:55], v[74:75]
	s_nop 0
	v_cvt_pk_bf16_f32 v74, v54, v55
	ds_write2_b32 v88, v99, v100 offset0:32 offset1:100
	ds_write2_b32 v88, v76, v77 offset0:168 offset1:236
	ds_write2_b32 v89, v78, v79 offset0:48 offset1:116
	ds_write2_b32 v89, v80, v74 offset0:184 offset1:252
	s_waitcnt lgkmcnt(0)
	s_waitcnt lgkmcnt(7)
	v_lshlrev_b32_e32 v100, 16, v56
	v_and_b32_e32 v101, 0xffff0000, v56
	v_pk_fma_f32 v[100:101], v[66:67], v[54:55], v[100:101] op_sel:[0,1,0] op_sel_hi:[1,0,1]
	v_lshlrev_b32_e32 v56, 16, v57
	v_pk_fma_f32 v[54:55], v[64:65], v[54:55], v[100:101]
	v_and_b32_e32 v57, 0xffff0000, v57
	v_pk_fma_f32 v[56:57], v[66:67], v[54:55], v[56:57] op_sel:[0,1,0] op_sel_hi:[1,0,1]
	v_cvt_pk_bf16_f32 v99, v54, v55
	v_pk_fma_f32 v[54:55], v[64:65], v[54:55], v[56:57]
	s_waitcnt lgkmcnt(6)
	v_lshlrev_b32_e32 v56, 16, v58
	v_and_b32_e32 v57, 0xffff0000, v58
	v_pk_fma_f32 v[56:57], v[66:67], v[54:55], v[56:57] op_sel:[0,1,0] op_sel_hi:[1,0,1]
	v_cvt_pk_bf16_f32 v100, v54, v55
	v_pk_fma_f32 v[54:55], v[64:65], v[54:55], v[56:57]
	v_lshlrev_b32_e32 v56, 16, v59
	v_and_b32_e32 v57, 0xffff0000, v59
	v_pk_fma_f32 v[56:57], v[66:67], v[54:55], v[56:57] op_sel:[0,1,0] op_sel_hi:[1,0,1]
	v_cvt_pk_bf16_f32 v58, v54, v55
	v_pk_fma_f32 v[54:55], v[64:65], v[54:55], v[56:57]
	s_waitcnt lgkmcnt(5)
	v_lshlrev_b32_e32 v56, 16, v60
	v_and_b32_e32 v57, 0xffff0000, v60
	v_pk_fma_f32 v[56:57], v[66:67], v[54:55], v[56:57] op_sel:[0,1,0] op_sel_hi:[1,0,1]
	ds_read2_b32 v[74:75], v95 offset0:96 offset1:164
	ds_read2_b32 v[76:77], v97 offset0:104 offset1:172
	ds_read2_b32 v[78:79], v96 offset0:112 offset1:180
	ds_read2_b32 v[80:81], v94 offset0:120 offset1:188
	v_cvt_pk_bf16_f32 v59, v54, v55
	v_pk_fma_f32 v[54:55], v[64:65], v[54:55], v[56:57]
	v_lshlrev_b32_e32 v56, 16, v61
	v_and_b32_e32 v57, 0xffff0000, v61
	v_pk_fma_f32 v[56:57], v[66:67], v[54:55], v[56:57] op_sel:[0,1,0] op_sel_hi:[1,0,1]
	v_cvt_pk_bf16_f32 v60, v54, v55
	v_pk_fma_f32 v[54:55], v[64:65], v[54:55], v[56:57]
	s_waitcnt lgkmcnt(8)
	v_lshlrev_b32_e32 v56, 16, v72
	v_and_b32_e32 v57, 0xffff0000, v72
	v_pk_fma_f32 v[56:57], v[66:67], v[54:55], v[56:57] op_sel:[0,1,0] op_sel_hi:[1,0,1]
	v_cvt_pk_bf16_f32 v61, v54, v55
	v_pk_fma_f32 v[54:55], v[64:65], v[54:55], v[56:57]
	v_lshlrev_b32_e32 v56, 16, v73
	v_and_b32_e32 v57, 0xffff0000, v73
	v_pk_fma_f32 v[56:57], v[66:67], v[54:55], v[56:57] op_sel:[0,1,0] op_sel_hi:[1,0,1]
	v_cvt_pk_bf16_f32 v72, v54, v55
	v_pk_fma_f32 v[54:55], v[64:65], v[54:55], v[56:57]
	s_nop 0
	v_cvt_pk_bf16_f32 v56, v54, v55
	ds_write2_b32 v90, v99, v100 offset0:64 offset1:132
	ds_write2_b32 v91, v58, v59 offset0:72 offset1:140
	ds_write2_b32 v92, v60, v61 offset0:80 offset1:148
	ds_write2_b32 v93, v72, v56 offset0:88 offset1:156
	s_waitcnt lgkmcnt(0)
	s_waitcnt lgkmcnt(7)
	v_lshlrev_b32_e32 v56, 16, v74
	v_and_b32_e32 v57, 0xffff0000, v74
	v_pk_fma_f32 v[56:57], v[66:67], v[54:55], v[56:57] op_sel:[0,1,0] op_sel_hi:[1,0,1]
	s_nop 0
	v_pk_fma_f32 v[54:55], v[64:65], v[54:55], v[56:57]
	v_lshlrev_b32_e32 v56, 16, v75
	v_and_b32_e32 v57, 0xffff0000, v75
	v_pk_fma_f32 v[56:57], v[66:67], v[54:55], v[56:57] op_sel:[0,1,0] op_sel_hi:[1,0,1]
	v_cvt_pk_bf16_f32 v58, v54, v55
	v_pk_fma_f32 v[54:55], v[64:65], v[54:55], v[56:57]
	s_waitcnt lgkmcnt(6)
; #define LAS __attribute__((address_space(3)))
; __device__ __forceinline__ unsigned pk2n(float lo, float hi) { const f32x2 v = {lo, hi}; const bf16x2n b = __builtin_convertvector(v, bf16x2n); return __builtin_bit_cast(unsigned, b); }
; __device__ __forceinline__ float bflo(unsigned w) { return __uint_as_float(w << 16); }
; __device__ __forceinline__ float bfhi(unsigned w) { return __uint_as_float(w & 0xffff0000u); }
; template <bool OUT> ...
;     ...
;                 for (int j = 0; j < 8; ++j) {
;                     const unsigned bw = cur8[j];
;                     const f32x2 bv = {bflo(bw), bfhi(bw)};
;                     const f32x2 hs = __builtin_shufflevector(hv, hv, 1, 0);
;                     hv = __builtin_elementwise_fma(L1, hv, __builtin_elementwise_fma(L2, hs, bv));
;                     if (OUT) hw8[j] = pk2n(hv.x, hv.y);
;                 }
;                 if (OUT) {
;                     __builtin_amdgcn_sched_barrier(0);
; #pragma unroll
;                     for (int j = 0; j < 8; ++j) wl[(8 * blk + j) * 68 + lane] = hw8[j];
;                     DS_GUARD();
;                 }
; #pragma unroll
;                 for (int j = 0; j < 8; ++j) cur8[j] = nxt8[j];
;             }
;             hr = hv.x; hi = hv.y;
;         }
;         CFENCE();
;         if (OUT) {
;             f32x4 y[2]; bf16x8 hf[2][4];
; #pragma unroll
;             for (int mt = 0; mt < 2; ++mt)
; #pragma unroll
;                 for (int ks = 0; ks < 4; ++ks) hf[mt][ks] = *(const LAS bf16x8*)((const LAS char*)wl + (16 * mt + fr) * 272 + 64 * ks + 16 * fq);
;             y[0] = (f32x4){0.f, 0.f, 0.f, 0.f}; y[1] = y[0];
; #pragma unroll
;             for (int ks = 0; ks < 4; ++ks)
; #pragma unroll
;                 for (int mt = 0; mt < 2; ++mt) y[mt] = __builtin_amdgcn_mfma_f32_16x16x32_bf16(cfrag[ks], hf[mt][ks], y[mt], 0, 0, 0);
; #pragma unroll
;             for (int mt = 0; mt < 2; ++mt) {
;                 const size_t row = r0 + 16 * mt + fr;
;                 const float v0 = y[mt].x + Dv.x * bflo(uw[mt].x), v1 = y[mt].y + Dv.y * bfhi(uw[mt].x), v2 = y[mt].z + Dv.z * bflo(uw[mt].y), v3 = y[mt].w + Dv.w * bfhi(uw[mt].y);
;                 u32x2 o; o.x = pk2n(gelu_tanh(v0), gelu_tanh(v1)); o.y = pk2n(gelu_tanh(v2), gelu_tanh(v3));
;                 *(u32x2*)(zg + ((size_t)g * M + row) * 16 + 4 * fq) = o;
;             }
;             CFENCE();
;         }
	v_lshlrev_b32_e32 v56, 16, v76
	v_and_b32_e32 v57, 0xffff0000, v76
	v_pk_fma_f32 v[56:57], v[66:67], v[54:55], v[56:57] op_sel:[0,1,0] op_sel_hi:[1,0,1]
	v_cvt_pk_bf16_f32 v59, v54, v55
	v_pk_fma_f32 v[54:55], v[64:65], v[54:55], v[56:57]
	v_lshlrev_b32_e32 v56, 16, v77
	v_and_b32_e32 v57, 0xffff0000, v77
	v_pk_fma_f32 v[56:57], v[66:67], v[54:55], v[56:57] op_sel:[0,1,0] op_sel_hi:[1,0,1]
	v_cvt_pk_bf16_f32 v60, v54, v55
	v_pk_fma_f32 v[54:55], v[64:65], v[54:55], v[56:57]
	s_waitcnt lgkmcnt(5)
	v_lshlrev_b32_e32 v56, 16, v78
	v_and_b32_e32 v57, 0xffff0000, v78
	v_pk_fma_f32 v[56:57], v[66:67], v[54:55], v[56:57] op_sel:[0,1,0] op_sel_hi:[1,0,1]
	v_cvt_pk_bf16_f32 v61, v54, v55
	v_pk_fma_f32 v[54:55], v[64:65], v[54:55], v[56:57]
	v_lshlrev_b32_e32 v56, 16, v79
	v_and_b32_e32 v57, 0xffff0000, v79
	v_pk_fma_f32 v[56:57], v[66:67], v[54:55], v[56:57] op_sel:[0,1,0] op_sel_hi:[1,0,1]
	v_cvt_pk_bf16_f32 v74, v54, v55
	v_pk_fma_f32 v[54:55], v[64:65], v[54:55], v[56:57]
	s_waitcnt lgkmcnt(4)
	v_lshlrev_b32_e32 v56, 16, v80
	v_and_b32_e32 v57, 0xffff0000, v80
	v_pk_fma_f32 v[56:57], v[66:67], v[54:55], v[56:57] op_sel:[0,1,0] op_sel_hi:[1,0,1]
	v_cvt_pk_bf16_f32 v75, v54, v55
	v_pk_fma_f32 v[54:55], v[64:65], v[54:55], v[56:57]
	v_lshlrev_b32_e32 v56, 16, v81
	v_and_b32_e32 v57, 0xffff0000, v81
	v_pk_fma_f32 v[56:57], v[66:67], v[54:55], v[56:57] op_sel:[0,1,0] op_sel_hi:[1,0,1]
	v_cvt_pk_bf16_f32 v76, v54, v55
	v_pk_fma_f32 v[72:73], v[64:65], v[54:55], v[56:57]
	s_nop 0
	v_cvt_pk_bf16_f32 v54, v72, v73
	ds_write2_b32 v95, v58, v59 offset0:96 offset1:164
	ds_write2_b32 v97, v60, v61 offset0:104 offset1:172
	ds_write2_b32 v96, v74, v75 offset0:112 offset1:180
	ds_write2_b32 v94, v76, v54 offset0:120 offset1:188
	s_waitcnt lgkmcnt(0)
	ds_read_b128 v[54:57], v98
	ds_read_b128 v[74:77], v98 offset:64
	ds_read_b128 v[58:61], v98 offset:4352
	v_lshlrev_b32_e32 v104, 16, v70
	v_and_b32_e32 v105, 0xffff0000, v70
	s_waitcnt lgkmcnt(2)
	v_mfma_f32_16x16x32_bf16 v[54:57], v[34:37], v[54:57], 0
	s_addk_i32 s24, 0x400
	s_mov_b64 s[12:13], 0x400
	s_cmpk_lg_i32 s24, 0x2000
	s_waitcnt lgkmcnt(1)
	v_mfma_f32_16x16x32_bf16 v[54:57], v[38:41], v[74:77], v[54:57]
	ds_read_b128 v[74:77], v98 offset:128
	ds_read_b128 v[78:81], v98 offset:192
	s_waitcnt lgkmcnt(1)
	v_mfma_f32_16x16x32_bf16 v[54:57], v[42:45], v[74:77], v[54:57]
	ds_read_b128 v[74:77], v98 offset:4416
	s_waitcnt lgkmcnt(1)
	v_mfma_f32_16x16x32_bf16 v[54:57], v[46:49], v[78:81], v[54:57]
	ds_read_b128 v[78:81], v98 offset:4480
	ds_read_b128 v[100:103], v98 offset:4544
	v_mfma_f32_16x16x32_bf16 v[58:61], v[34:37], v[58:61], 0
	s_nop 4
	v_fma_f32 v104, v50, v104, v54
	v_fma_f32 v105, v51, v105, v55
	v_mul_f32_e32 v54, 0x3d372713, v104
	v_mul_f32_e32 v55, 0x3d372713, v105
	v_mul_f32_e32 v54, v104, v54
	v_mul_f32_e32 v55, v105, v55
	v_fma_f32 v54, v104, v54, v104
	v_fma_f32 v55, v105, v55, v105
	v_mul_f32_e32 v54, 0x3f4c422a, v54
	v_mul_f32_e32 v55, 0x3f4c422a, v55
	v_add_f32_e32 v54, v54, v54
	v_add_f32_e32 v55, v55, v55
	v_mul_f32_e32 v54, 0xbfb8aa3b, v54
	v_exp_f32_e32 v54, v54
	v_mul_f32_e32 v55, 0xbfb8aa3b, v55
	v_exp_f32_e32 v55, v55
	s_waitcnt lgkmcnt(2)
	v_mfma_f32_16x16x32_bf16 v[58:61], v[38:41], v[74:77], v[58:61]
	v_add_f32_e32 v54, 1.0, v54
	v_rcp_f32_e32 v70, v54
	v_add_f32_e32 v76, 1.0, v55
	v_lshlrev_b32_e32 v54, 16, v71
	v_and_b32_e32 v55, 0xffff0000, v71
	v_pk_fma_f32 v[74:75], v[52:53], v[54:55], v[56:57]
	s_waitcnt lgkmcnt(1)
	v_mfma_f32_16x16x32_bf16 v[58:61], v[42:45], v[78:81], v[58:61]
	v_mul_f32_e32 v54, 0x3d372713, v74
	v_mul_f32_e32 v54, v74, v54
	v_mul_f32_e32 v55, 0x3d372713, v75
	v_fma_f32 v54, v74, v54, v74
	v_mul_f32_e32 v55, v75, v55
	v_mul_f32_e32 v54, 0x3f4c422a, v54
	v_fma_f32 v55, v75, v55, v75
	v_add_f32_e32 v54, v54, v54
	v_mul_f32_e32 v55, 0x3f4c422a, v55
	v_mul_f32_e32 v54, 0xbfb8aa3b, v54
	v_add_f32_e32 v55, v55, v55
	v_exp_f32_e32 v54, v54
	v_mul_f32_e32 v55, 0xbfb8aa3b, v55
	v_exp_f32_e32 v55, v55
	v_rcp_f32_e32 v71, v76
	v_add_f32_e32 v54, 1.0, v54
	v_rcp_f32_e32 v76, v54
	v_add_f32_e32 v54, 1.0, v55
	v_rcp_f32_e32 v77, v54
	s_waitcnt lgkmcnt(0)
	v_mfma_f32_16x16x32_bf16 v[54:57], v[46:49], v[100:103], v[58:61]
	s_nop 2
	v_mul_f32_e64 v58, v104, v70
	v_mul_f32_e64 v59, v105, v71
	v_lshlrev_b32_e32 v70, 16, v68
	v_and_b32_e32 v71, 0xffff0000, v68
	s_nop 0
	v_pk_fma_f32 v[54:55], v[50:51], v[70:71], v[54:55]
	v_cvt_pk_bf16_f32 v58, v58, v59
	v_mul_f32_e32 v59, 0x3d372713, v54
	v_mul_f32_e32 v59, v54, v59
	v_fma_f32 v59, v54, v59, v54
	v_mul_f32_e32 v59, 0x3f4c422a, v59
	v_add_f32_e32 v59, v59, v59
	v_mul_f32_e32 v59, 0xbfb8aa3b, v59
	v_exp_f32_e32 v68, v59
	v_mul_f32_e32 v59, 0x3d372713, v55
	v_mul_f32_e32 v59, v55, v59
	v_fma_f32 v59, v55, v59, v55
	v_mul_f32_e32 v59, 0x3f4c422a, v59
	v_add_f32_e32 v59, v59, v59
	v_pk_mul_f32 v[60:61], v[74:75], v[76:77]
	v_mul_f32_e32 v59, 0xbfb8aa3b, v59
	v_exp_f32_e32 v70, v59
	v_cvt_pk_bf16_f32 v59, v60, v61
	v_add_f32_e32 v60, 1.0, v68
	v_lshlrev_b32_e32 v68, 16, v69
	v_and_b32_e32 v69, 0xffff0000, v69
	v_pk_fma_f32 v[56:57], v[52:53], v[68:69], v[56:57]
	v_add_f32_e32 v61, 1.0, v70
	v_mul_f32_e32 v68, 0x3d372713, v56
	v_mul_f32_e32 v69, 0x3d372713, v57
	v_mul_f32_e32 v68, v56, v68
	v_mul_f32_e32 v69, v57, v69
	v_fma_f32 v68, v56, v68, v56
	v_fma_f32 v69, v57, v69, v57
	v_mul_f32_e32 v68, 0x3f4c422a, v68
	v_mul_f32_e32 v69, 0x3f4c422a, v69
	v_add_f32_e32 v68, v68, v68
	v_add_f32_e32 v69, v69, v69
	v_mul_f32_e32 v68, 0xbfb8aa3b, v68
	v_mul_f32_e32 v69, 0xbfb8aa3b, v69
	v_exp_f32_e32 v68, v68
	v_exp_f32_e32 v69, v69
	v_rcp_f32_e32 v60, v60
	v_rcp_f32_e32 v61, v61
	v_add_f32_e32 v68, 1.0, v68
	v_add_f32_e32 v69, 1.0, v69
	v_rcp_f32_e32 v68, v68
	v_rcp_f32_e32 v69, v69
	v_pk_mul_f32 v[54:55], v[54:55], v[60:61]
	global_store_dwordx2 v[62:63], v[58:59], off sc1
	v_cvt_pk_bf16_f32 v54, v54, v55
	v_pk_mul_f32 v[56:57], v[56:57], v[68:69]
	s_nop 0
	v_cvt_pk_bf16_f32 v55, v56, v57
	global_store_dwordx2 v[62:63], v[54:55], off offset:512 sc1
	v_lshl_add_u64 v[62:63], v[62:63], 0, s[12:13]
	s_cbranch_scc0 .LBB0_640

; __device__ __forceinline__ unsigned pk2(float lo, float hi) { unsigned r; asm("v_cvt_pk_bf16_f32 %0, %1, %2" : "=v"(r) : "v"(lo), "v"(hi)); return r; }
; __device__ __forceinline__ float bflo(unsigned w) { return __uint_as_float(w << 16); }
; __device__ __forceinline__ float bfhi(unsigned w) { return __uint_as_float(w & 0xffff0000u); }
; __device__ __forceinline__ float sigmoidf_(float x) { return __builtin_amdgcn_rcpf(1.0f + __expf(-x)); }
;     __device__ __forceinline__ void operator()(const AccT& acc, const pg8::Unit& u, int ui, int wr, int wc, int fr, int fq) const {
;         const int row0 = u.pm * 256 + wr * 64 + fr, col0 = u.pn * 256 + wc * 32 + 8 * fq;
;         f32x4 bv[2][2];
; #pragma unroll
;         for (int bj = 0; bj < 2; ++bj)
; #pragma unroll
;             for (int n = 0; n < 2; ++n) bv[bj][n] = *(const f32x4*)(bias + col0 + 128 * bj + 4 * n);
; #pragma unroll
;         for (int ai = 0; ai < 2; ++ai) {
;             u32x4 zv[4][2];
; #pragma unroll
;             for (int m = 0; m < 4; ++m)
; #pragma unroll
;                 for (int bj = 0; bj < 2; ++bj) { const int col = col0 + 128 * bj; zv[m][bj] = *(const u32x4*)(zg + ((size_t)(col >> 4) * M + (row0 + ai * 128 + m * 16)) * 16 + (col & 15)); }
; #pragma unroll
;             for (int m = 0; m < 4; ++m) {
;                 const int r = row0 + ai * 128 + m * 16; float ss = 0.f;
; #pragma unroll
;                 for (int bj = 0; bj < 2; ++bj) {
;                     const u32x4 zw = zv[m][bj];
;                     const f32x4 p0 = acc[ai][bj][m][0] + bv[bj][0], p1 = acc[ai][bj][m][1] + bv[bj][1];
;                     const float o0 = bflo(zw.x) * sigmoidf_(p0.x), o1 = bfhi(zw.x) * sigmoidf_(p0.y), o2 = bflo(zw.y) * sigmoidf_(p0.z), o3 = bfhi(zw.y) * sigmoidf_(p0.w);
;                     const float o4 = bflo(zw.z) * sigmoidf_(p1.x), o5 = bfhi(zw.z) * sigmoidf_(p1.y), o6 = bflo(zw.w) * sigmoidf_(p1.z), o7 = bfhi(zw.w) * sigmoidf_(p1.w);
;                     ss += (o0 * o0 + o1 * o1) + (o2 * o2 + o3 * o3) + (o4 * o4 + o5 * o5) + (o6 * o6 + o7 * o7);
;                     u32x4 w; w.x = pk2(o0, o1); w.y = pk2(o2, o3); w.z = pk2(o4, o5); w.w = pk2(o6, o7);
;                     *(u32x4*)(ys + (size_t)r * ldy + col0 + 128 * bj) = w;
.LBB0_744:
	v_mov_b32_e32 v0, v234
	s_lshl_b32 s11, s62, 8
	s_or_b32 s11, s11, s20
	v_bfe_u32 v138, v0, 4, 2
	v_lshl_or_b32 v206, v138, 3, s11
	v_ashrrev_i32_e32 v207, 31, v206
	v_lshl_add_u64 v[62:63], v[206:207], 2, s[46:47]
	global_load_dwordx4 v[74:77], v[62:63], off offset:16
	global_load_dwordx4 v[78:81], v[62:63], off
	global_load_dwordx4 v[58:61], v[62:63], off offset:528
	s_nop 0
	global_load_dwordx4 v[62:65], v[62:63], off offset:512
	s_lshl_b32 s10, s86, 8
	s_add_i32 s10, s10, s38
	v_and_or_b32 v214, v0, 15, s10
	v_cmp_eq_u32_e32 vcc, 0, v138
	v_and_b32_e32 v0, 16, v0
	v_ashrrev_i32_e32 v138, 4, v206
	v_ashrrev_i32_e32 v215, 31, v214
	v_lshl_add_u64 v[208:209], s[0:1], 0, v[0:1]
	v_ashrrev_i32_e32 v139, 31, v138
	v_lshlrev_b64 v[228:229], 5, v[214:215]
	v_lshlrev_b64 v[210:211], 19, v[138:139]
	v_lshl_add_u64 v[140:141], v[208:209], 0, v[228:229]
	v_lshl_add_u64 v[142:143], v[140:141], 0, v[210:211]
	global_load_dwordx4 v[174:177], v[142:143], off
	v_or_b32_e32 v138, 8, v138
	v_ashrrev_i32_e32 v139, 31, v138
	v_lshlrev_b64 v[212:213], 19, v[138:139]
	v_lshl_add_u64 v[138:139], v[140:141], 0, v[212:213]
	global_load_dwordx4 v[170:173], v[138:139], off
	v_or_b32_e32 v226, 16, v214
	v_ashrrev_i32_e32 v227, 31, v226
	v_lshlrev_b64 v[224:225], 5, v[226:227]
	v_or_b32_e32 v222, 32, v214
	v_lshl_add_u64 v[138:139], v[208:209], 0, v[224:225]
	v_ashrrev_i32_e32 v223, 31, v222
	v_lshl_add_u64 v[140:141], v[138:139], 0, v[210:211]
	v_lshl_add_u64 v[138:139], v[138:139], 0, v[212:213]
	v_lshlrev_b64 v[220:221], 5, v[222:223]
	v_or_b32_e32 v218, 48, v214
	global_load_dwordx4 v[166:169], v[140:141], off
	global_load_dwordx4 v[154:157], v[138:139], off
	v_lshl_add_u64 v[138:139], v[208:209], 0, v[220:221]
	v_ashrrev_i32_e32 v219, 31, v218
	v_lshl_add_u64 v[140:141], v[138:139], 0, v[210:211]
	v_lshl_add_u64 v[138:139], v[138:139], 0, v[212:213]
	v_lshlrev_b64 v[216:217], 5, v[218:219]
	global_load_dwordx4 v[150:153], v[140:141], off
	global_load_dwordx4 v[146:149], v[138:139], off
	v_lshl_add_u64 v[138:139], v[208:209], 0, v[216:217]
	v_lshl_add_u64 v[140:141], v[138:139], 0, v[210:211]
	v_lshl_add_u64 v[138:139], v[138:139], 0, v[212:213]
	global_load_dwordx4 v[142:145], v[140:141], off
	s_lshl_b32 s54, s62, 2
	global_load_dwordx4 v[138:141], v[138:139], off
	s_ashr_i32 s55, s54, 31
	s_waitcnt vmcnt(0)
	v_pk_add_f32 v[158:159], v[158:159], v[74:75]
	v_pk_add_f32 v[162:163], v[162:163], v[78:79]
	v_pk_add_f32 v[164:165], v[164:165], v[80:81]
	v_mul_f32_e32 v162, 0xbfb8aa3b, v162
	v_exp_f32_e32 v162, v162
	v_mul_f32_e32 v163, 0xbfb8aa3b, v163
	v_exp_f32_e32 v163, v163
	v_mul_f32_e32 v164, 0xbfb8aa3b, v164
	v_exp_f32_e32 v164, v164
	v_mul_f32_e32 v165, 0xbfb8aa3b, v165
	v_exp_f32_e32 v165, v165
	v_mul_f32_e32 v158, 0xbfb8aa3b, v158
	v_pk_add_f32 v[160:161], v[160:161], v[76:77]
	v_add_f32_e32 v162, 1.0, v162
	v_exp_f32_e32 v158, v158
	v_mul_f32_e32 v159, 0xbfb8aa3b, v159
	v_rcp_f32_e32 v162, v162
	v_add_f32_e32 v163, 1.0, v163
	v_exp_f32_e32 v159, v159
	v_mul_f32_e32 v160, 0xbfb8aa3b, v160
	v_rcp_f32_e32 v163, v163
	v_add_f32_e32 v164, 1.0, v164
	v_exp_f32_e32 v160, v160
	v_mul_f32_e32 v161, 0xbfb8aa3b, v161
	v_rcp_f32_e32 v164, v164
	v_add_f32_e32 v165, 1.0, v165
	v_exp_f32_e32 v161, v161
	v_lshlrev_b32_e32 v0, 16, v174
	v_rcp_f32_e32 v165, v165
	v_add_f32_e32 v158, 1.0, v158
	v_mul_f32_e32 v0, v162, v0
	v_and_b32_e32 v162, 0xffff0000, v174
	v_rcp_f32_e32 v158, v158
	v_add_f32_e32 v159, 1.0, v159
	v_mul_f32_e32 v162, v163, v162
	v_lshlrev_b32_e32 v163, 16, v175
	v_rcp_f32_e32 v159, v159
	v_add_f32_e32 v160, 1.0, v160
	v_mul_f32_e32 v163, v164, v163
	v_and_b32_e32 v164, 0xffff0000, v175
	v_rcp_f32_e32 v160, v160
	v_add_f32_e32 v161, 1.0, v161
	v_mul_f32_e32 v164, v165, v164
	v_lshlrev_b32_e32 v165, 16, v176
	v_rcp_f32_e32 v161, v161
	v_pk_add_f32 v[134:135], v[134:135], v[62:63]
	v_mul_f32_e32 v158, v158, v165
	v_and_b32_e32 v165, 0xffff0000, v176
	v_mul_f32_e32 v134, 0xbfb8aa3b, v134
	v_mul_f32_e32 v159, v159, v165
	v_lshlrev_b32_e32 v165, 16, v177
	v_pk_add_f32 v[136:137], v[136:137], v[64:65]
	v_exp_f32_e32 v134, v134
	v_mul_f32_e32 v135, 0xbfb8aa3b, v135
	v_mul_f32_e32 v165, v160, v165
	v_and_b32_e32 v160, 0xffff0000, v177
	v_exp_f32_e32 v135, v135
	v_mul_f32_e32 v136, 0xbfb8aa3b, v136
	v_mul_f32_e32 v174, v161, v160
	v_mul_f32_e32 v160, v162, v162
	v_mul_f32_e32 v161, v164, v164
	v_pk_add_f32 v[130:131], v[130:131], v[58:59]
	v_exp_f32_e32 v136, v136
	v_mul_f32_e32 v137, 0xbfb8aa3b, v137
	v_fmac_f32_e32 v160, v0, v0
	v_fmac_f32_e32 v161, v163, v163
	v_exp_f32_e32 v137, v137
	v_mul_f32_e32 v130, 0xbfb8aa3b, v130
	v_add_f32_e32 v160, v160, v161
	v_mul_f32_e32 v161, v159, v159
	v_add_f32_e32 v134, 1.0, v134
	v_exp_f32_e32 v130, v130
	v_mul_f32_e32 v131, 0xbfb8aa3b, v131
	v_fmac_f32_e32 v161, v158, v158
	v_rcp_f32_e32 v134, v134
	v_add_f32_e32 v135, 1.0, v135
	v_exp_f32_e32 v131, v131
	v_add_f32_e32 v160, v161, v160
	v_mul_f32_e32 v161, v174, v174
	v_rcp_f32_e32 v135, v135
	v_add_f32_e32 v136, 1.0, v136
	v_fmac_f32_e32 v161, v165, v165
	v_rcp_f32_e32 v136, v136
	v_add_f32_e32 v137, 1.0, v137
	v_add_f32_e32 v175, v161, v160
	v_cvt_pk_bf16_f32 v160, v0, v162
	v_lshlrev_b32_e32 v0, 16, v170
	v_rcp_f32_e32 v137, v137
	v_add_f32_e32 v130, 1.0, v130
	v_mul_f32_e32 v0, v134, v0
	v_and_b32_e32 v134, 0xffff0000, v170
	v_rcp_f32_e32 v130, v130
	v_add_f32_e32 v131, 1.0, v131
	v_mul_f32_e32 v134, v135, v134
	v_lshlrev_b32_e32 v135, 16, v171
	v_rcp_f32_e32 v131, v131
	v_cvt_pk_bf16_f32 v162, v158, v159
	v_lshlrev_b64 v[158:159], 11, v[214:215]
	v_mul_f32_e32 v135, v136, v135
	v_and_b32_e32 v136, 0xffff0000, v171
	v_lshl_add_u64 v[158:159], s[70:71], 0, v[158:159]
; __device__ __forceinline__ unsigned pk2(float lo, float hi) { unsigned r; asm("v_cvt_pk_bf16_f32 %0, %1, %2" : "=v"(r) : "v"(lo), "v"(hi)); return r; }
; __device__ __forceinline__ float bflo(unsigned w) { return __uint_as_float(w << 16); }
; __device__ __forceinline__ float bfhi(unsigned w) { return __uint_as_float(w & 0xffff0000u); }
; __device__ __forceinline__ float sigmoidf_(float x) { return __builtin_amdgcn_rcpf(1.0f + __expf(-x)); }
;     __device__ __forceinline__ void operator()(const AccT& acc, const pg8::Unit& u, int ui, int wr, int wc, int fr, int fq) const {
;     ...
;             for (int m = 0; m < 4; ++m) {
;                 const int r = row0 + ai * 128 + m * 16; float ss = 0.f;
; #pragma unroll
;                 for (int bj = 0; bj < 2; ++bj) {
;                     const u32x4 zw = zv[m][bj];
;                     const f32x4 p0 = acc[ai][bj][m][0] + bv[bj][0], p1 = acc[ai][bj][m][1] + bv[bj][1];
;                     const float o0 = bflo(zw.x) * sigmoidf_(p0.x), o1 = bfhi(zw.x) * sigmoidf_(p0.y), o2 = bflo(zw.y) * sigmoidf_(p0.z), o3 = bfhi(zw.y) * sigmoidf_(p0.w);
;                     const float o4 = bflo(zw.z) * sigmoidf_(p1.x), o5 = bfhi(zw.z) * sigmoidf_(p1.y), o6 = bflo(zw.w) * sigmoidf_(p1.z), o7 = bfhi(zw.w) * sigmoidf_(p1.w);
;                     ss += (o0 * o0 + o1 * o1) + (o2 * o2 + o3 * o3) + (o4 * o4 + o5 * o5) + (o6 * o6 + o7 * o7);
;                     u32x4 w; w.x = pk2(o0, o1); w.y = pk2(o2, o3); w.z = pk2(o4, o5); w.w = pk2(o6, o7);
;                     *(u32x4*)(ys + (size_t)r * ldy + col0 + 128 * bj) = w;
;                 }
;                 ss += __shfl_xor(ss, 16); ss += __shfl_xor(ss, 32); if (fq == 0) part_s[(size_t)r * 8 + u.pn * 4 + wc] = ss;
	v_mul_f32_e32 v136, v137, v136
	v_lshlrev_b32_e32 v137, 16, v172
	v_lshl_add_u64 v[158:159], v[206:207], 1, v[158:159]
	v_pk_add_f32 v[132:133], v[132:133], v[60:61]
	v_mul_f32_e32 v137, v130, v137
	v_and_b32_e32 v130, 0xffff0000, v172
	v_cvt_pk_bf16_f32 v161, v163, v164
	v_cvt_pk_bf16_f32 v163, v165, v174
	global_store_dwordx4 v[158:159], v[160:163], off sc1
	s_nop 1
	v_mul_f32_e32 v160, v131, v130
	v_mul_f32_e32 v131, 0xbfb8aa3b, v132
	v_exp_f32_e32 v131, v131
	v_lshlrev_b32_e32 v130, 16, v173
	v_cvt_pk_bf16_f32 v132, v137, v160
	v_add_f32_e32 v131, 1.0, v131
	v_rcp_f32_e32 v131, v131
	s_nop 0
	v_mul_f32_e32 v161, v131, v130
	v_mul_f32_e32 v131, 0xbfb8aa3b, v133
	v_exp_f32_e32 v131, v131
	v_and_b32_e32 v130, 0xffff0000, v173
	v_add_f32_e32 v131, 1.0, v131
	v_rcp_f32_e32 v131, v131
	s_nop 0
	v_mul_f32_e32 v133, v131, v130
	v_mul_f32_e32 v130, v134, v134
	v_mul_f32_e32 v131, v136, v136
	v_fmac_f32_e32 v130, v0, v0
	v_fmac_f32_e32 v131, v135, v135
	v_add_f32_e32 v130, v130, v131
	v_mul_f32_e32 v131, v160, v160
	v_fmac_f32_e32 v131, v137, v137
	v_add_f32_e32 v130, v130, v131
	v_mul_f32_e32 v131, v133, v133
	v_fmac_f32_e32 v131, v161, v161
	v_add_f32_e32 v130, v131, v130
	v_add_f32_e32 v162, v175, v130
	v_cvt_pk_bf16_f32 v130, v0, v134
	v_cvt_pk_bf16_f32 v131, v135, v136
	v_cvt_pk_bf16_f32 v133, v161, v133
	global_store_dwordx4 v[158:159], v[130:133], off offset:256 sc1
	v_xor_b32_e32 v0, 16, v231
	s_nop 0
	v_and_b32_e32 v130, 64, v231
	v_add_u32_e32 v130, 64, v130
	v_cmp_lt_i32_e64 s[10:11], v0, v130
	v_xor_b32_e32 v132, 32, v231
	s_nop 0
	v_cndmask_b32_e64 v0, v231, v0, s[10:11]
	v_lshlrev_b32_e32 v0, 2, v0
	ds_bpermute_b32 v131, v0, v162
	v_cmp_lt_i32_e64 s[10:11], v132, v130
	s_waitcnt lgkmcnt(0)
	v_add_f32_e32 v131, v162, v131
	v_cndmask_b32_e64 v130, v231, v132, s[10:11]
	v_lshlrev_b32_e32 v130, 2, v130
	ds_bpermute_b32 v132, v130, v131
	s_and_saveexec_b64 s[10:11], vcc
	s_cbranch_execz .LBB0_746
	v_lshl_add_u64 v[134:135], s[78:79], 0, v[228:229]
	v_lshl_add_u64 v[134:135], s[54:55], 2, v[134:135]
	s_lshl_b32 s62, s85, 2
	v_lshl_add_u64 v[134:135], v[134:135], 0, s[62:63]
	s_waitcnt lgkmcnt(0)
	v_add_f32_e32 v131, v131, v132
	global_store_dword v[134:135], v131, off
.LBB0_746:
	s_or_b64 exec, exec, s[10:11]
	v_pk_add_f32 v[126:127], v[126:127], v[78:79]
	v_pk_add_f32 v[128:129], v[128:129], v[80:81]
	v_mul_f32_e32 v126, 0xbfb8aa3b, v126
	v_exp_f32_e32 v126, v126
	v_mul_f32_e32 v127, 0xbfb8aa3b, v127
	v_exp_f32_e32 v127, v127
	v_mul_f32_e32 v128, 0xbfb8aa3b, v128
	v_pk_add_f32 v[122:123], v[122:123], v[74:75]
	v_exp_f32_e32 v128, v128
	v_mul_f32_e32 v129, 0xbfb8aa3b, v129
	v_exp_f32_e32 v129, v129
	v_mul_f32_e32 v122, 0xbfb8aa3b, v122
	v_add_f32_e32 v126, 1.0, v126
	v_exp_f32_e32 v122, v122
	v_mul_f32_e32 v123, 0xbfb8aa3b, v123
	v_rcp_f32_e32 v126, v126
	v_add_f32_e32 v127, 1.0, v127
	v_exp_f32_e32 v123, v123
	v_rcp_f32_e32 v127, v127
	v_add_f32_e32 v128, 1.0, v128
	v_rcp_f32_e32 v128, v128
	v_add_f32_e32 v129, 1.0, v129
	v_pk_add_f32 v[124:125], v[124:125], v[76:77]
	v_lshlrev_b32_e32 v131, 16, v166
	v_rcp_f32_e32 v129, v129
	v_add_f32_e32 v122, 1.0, v122
	v_mul_f32_e32 v126, v126, v131
	v_and_b32_e32 v131, 0xffff0000, v166
	v_rcp_f32_e32 v122, v122
	v_add_f32_e32 v123, 1.0, v123
	v_mul_f32_e32 v124, 0xbfb8aa3b, v124
	v_mul_f32_e32 v127, v127, v131
	v_lshlrev_b32_e32 v131, 16, v167
	v_rcp_f32_e32 v123, v123
	v_exp_f32_e32 v124, v124
	v_mul_f32_e32 v125, 0xbfb8aa3b, v125
	v_mul_f32_e32 v128, v128, v131
	v_and_b32_e32 v131, 0xffff0000, v167
	v_exp_f32_e32 v125, v125
	v_mul_f32_e32 v129, v129, v131
	v_lshlrev_b32_e32 v131, 16, v168
	v_mul_f32_e32 v131, v122, v131
	v_and_b32_e32 v122, 0xffff0000, v168
	s_waitcnt lgkmcnt(0)
	v_mul_f32_e32 v132, v123, v122
	v_add_f32_e32 v122, 1.0, v124
	v_rcp_f32_e32 v122, v122
	v_add_f32_e32 v123, 1.0, v125
	v_rcp_f32_e32 v123, v123
	v_pk_add_f32 v[118:119], v[118:119], v[62:63]
	v_lshlrev_b32_e32 v124, 16, v169
	v_mul_f32_e32 v118, 0xbfb8aa3b, v118
	v_pk_add_f32 v[120:121], v[120:121], v[64:65]
	v_exp_f32_e32 v118, v118
	v_mul_f32_e32 v119, 0xbfb8aa3b, v119
	v_mul_f32_e32 v125, v122, v124
	v_and_b32_e32 v122, 0xffff0000, v169
	v_exp_f32_e32 v119, v119
	v_mul_f32_e32 v120, 0xbfb8aa3b, v120
	v_mul_f32_e32 v133, v123, v122
	v_mul_f32_e32 v122, v127, v127
	v_mul_f32_e32 v123, v129, v129
	v_pk_add_f32 v[114:115], v[114:115], v[58:59]
	v_exp_f32_e32 v120, v120
	v_mul_f32_e32 v121, 0xbfb8aa3b, v121
	v_fmac_f32_e32 v122, v126, v126
	v_fmac_f32_e32 v123, v128, v128
	v_exp_f32_e32 v121, v121
	v_mul_f32_e32 v114, 0xbfb8aa3b, v114
	v_add_f32_e32 v122, v122, v123
	v_mul_f32_e32 v123, v132, v132
	v_add_f32_e32 v118, 1.0, v118
	v_exp_f32_e32 v114, v114
	v_mul_f32_e32 v115, 0xbfb8aa3b, v115
	v_fmac_f32_e32 v123, v131, v131
	v_rcp_f32_e32 v118, v118
	v_add_f32_e32 v119, 1.0, v119
	v_exp_f32_e32 v115, v115
	v_add_f32_e32 v122, v123, v122
	v_mul_f32_e32 v123, v133, v133
	v_rcp_f32_e32 v119, v119
	v_add_f32_e32 v120, 1.0, v120
	v_fmac_f32_e32 v123, v125, v125
	v_rcp_f32_e32 v120, v120
	v_add_f32_e32 v121, 1.0, v121
	v_add_f32_e32 v134, v123, v122
	v_cvt_pk_bf16_f32 v123, v128, v129
	v_pk_add_f32 v[116:117], v[116:117], v[60:61]
	v_lshlrev_b32_e32 v128, 16, v154
	v_rcp_f32_e32 v121, v121
	v_add_f32_e32 v114, 1.0, v114
	v_mul_f32_e32 v118, v118, v128
	v_and_b32_e32 v128, 0xffff0000, v154
	v_rcp_f32_e32 v114, v114
	v_add_f32_e32 v115, 1.0, v115
	v_mul_f32_e32 v116, 0xbfb8aa3b, v116
	v_mul_f32_e32 v119, v119, v128
	v_lshlrev_b32_e32 v128, 16, v155
	v_rcp_f32_e32 v115, v115
	v_exp_f32_e32 v116, v116
	v_mul_f32_e32 v117, 0xbfb8aa3b, v117
	v_mul_f32_e32 v128, v120, v128
	v_and_b32_e32 v120, 0xffff0000, v155
	v_exp_f32_e32 v117, v117
	v_mul_f32_e32 v129, v121, v120
	v_lshlrev_b32_e32 v120, 16, v156
	v_cvt_pk_bf16_f32 v124, v131, v132
	v_mul_f32_e32 v131, v114, v120
	v_and_b32_e32 v114, 0xffff0000, v156
	v_mul_f32_e32 v132, v115, v114
	v_add_f32_e32 v114, 1.0, v116
	v_rcp_f32_e32 v114, v114
	v_add_f32_e32 v115, 1.0, v117
	v_rcp_f32_e32 v115, v115
	v_lshlrev_b32_e32 v116, 16, v157
	v_cvt_pk_bf16_f32 v125, v125, v133
	v_mul_f32_e32 v133, v114, v116
	v_and_b32_e32 v114, 0xffff0000, v157
	v_mul_f32_e32 v135, v115, v114
	v_mul_f32_e32 v114, v119, v119
	v_mul_f32_e32 v115, v129, v129
	v_fmac_f32_e32 v114, v118, v118
	v_fmac_f32_e32 v115, v128, v128
	v_add_f32_e32 v114, v114, v115
	v_mul_f32_e32 v115, v132, v132
	v_fmac_f32_e32 v115, v131, v131
	v_add_f32_e32 v114, v115, v114
	v_mul_f32_e32 v115, v135, v135
	v_fmac_f32_e32 v115, v133, v133
	v_add_f32_e32 v114, v115, v114
	v_add_f32_e32 v117, v134, v114
	ds_bpermute_b32 v134, v0, v117
	v_cvt_pk_bf16_f32 v122, v126, v127
	v_lshlrev_b64 v[126:127], 11, v[226:227]
	v_lshl_add_u64 v[114:115], s[70:71], 0, v[126:127]
	v_lshl_add_u64 v[120:121], v[206:207], 1, v[114:115]
	s_waitcnt lgkmcnt(0)
; __device__ __forceinline__ unsigned pk2(float lo, float hi) { unsigned r; asm("v_cvt_pk_bf16_f32 %0, %1, %2" : "=v"(r) : "v"(lo), "v"(hi)); return r; }
; __device__ __forceinline__ float bflo(unsigned w) { return __uint_as_float(w << 16); }
; __device__ __forceinline__ float bfhi(unsigned w) { return __uint_as_float(w & 0xffff0000u); }
; __device__ __forceinline__ float sigmoidf_(float x) { return __builtin_amdgcn_rcpf(1.0f + __expf(-x)); }
;     __device__ __forceinline__ void operator()(const AccT& acc, const pg8::Unit& u, int ui, int wr, int wc, int fr, int fq) const {
;     ...
;             for (int m = 0; m < 4; ++m) {
;                 const int r = row0 + ai * 128 + m * 16; float ss = 0.f;
; #pragma unroll
;                 for (int bj = 0; bj < 2; ++bj) {
;                     const u32x4 zw = zv[m][bj];
;                     const f32x4 p0 = acc[ai][bj][m][0] + bv[bj][0], p1 = acc[ai][bj][m][1] + bv[bj][1];
;                     const float o0 = bflo(zw.x) * sigmoidf_(p0.x), o1 = bfhi(zw.x) * sigmoidf_(p0.y), o2 = bflo(zw.y) * sigmoidf_(p0.z), o3 = bfhi(zw.y) * sigmoidf_(p0.w);
;                     const float o4 = bflo(zw.z) * sigmoidf_(p1.x), o5 = bfhi(zw.z) * sigmoidf_(p1.y), o6 = bflo(zw.w) * sigmoidf_(p1.z), o7 = bfhi(zw.w) * sigmoidf_(p1.w);
;                     ss += (o0 * o0 + o1 * o1) + (o2 * o2 + o3 * o3) + (o4 * o4 + o5 * o5) + (o6 * o6 + o7 * o7);
;                     u32x4 w; w.x = pk2(o0, o1); w.y = pk2(o2, o3); w.z = pk2(o4, o5); w.w = pk2(o6, o7);
;                     *(u32x4*)(ys + (size_t)r * ldy + col0 + 128 * bj) = w;
;                 }
;                 ss += __shfl_xor(ss, 16); ss += __shfl_xor(ss, 32); if (fq == 0) part_s[(size_t)r * 8 + u.pn * 4 + wc] = ss;
	v_add_f32_e32 v114, v117, v134
	ds_bpermute_b32 v115, v130, v114
	global_store_dwordx4 v[120:121], v[122:125], off sc1
	v_cvt_pk_bf16_f32 v116, v118, v119
	v_cvt_pk_bf16_f32 v117, v128, v129
	v_cvt_pk_bf16_f32 v118, v131, v132
	v_cvt_pk_bf16_f32 v119, v133, v135
	global_store_dwordx4 v[120:121], v[116:119], off offset:256 sc1
	s_and_saveexec_b64 s[10:11], vcc
	s_cbranch_execz .LBB0_748
	v_lshl_add_u64 v[116:117], s[78:79], 0, v[224:225]
	v_lshl_add_u64 v[116:117], s[54:55], 2, v[116:117]
	s_lshl_b32 s62, s85, 2
	v_lshl_add_u64 v[116:117], v[116:117], 0, s[62:63]
	s_waitcnt lgkmcnt(0)
	v_add_f32_e32 v114, v114, v115
	global_store_dword v[116:117], v114, off
.LBB0_748:
	s_or_b64 exec, exec, s[10:11]
	v_pk_add_f32 v[110:111], v[110:111], v[78:79]
	v_pk_add_f32 v[112:113], v[112:113], v[80:81]
	v_mul_f32_e32 v110, 0xbfb8aa3b, v110
	v_exp_f32_e32 v110, v110
	v_mul_f32_e32 v111, 0xbfb8aa3b, v111
	v_exp_f32_e32 v111, v111
	v_mul_f32_e32 v112, 0xbfb8aa3b, v112
	v_pk_add_f32 v[106:107], v[106:107], v[74:75]
	v_exp_f32_e32 v112, v112
	v_mul_f32_e32 v113, 0xbfb8aa3b, v113
	v_exp_f32_e32 v113, v113
	v_mul_f32_e32 v106, 0xbfb8aa3b, v106
	v_add_f32_e32 v110, 1.0, v110
	v_exp_f32_e32 v106, v106
	v_mul_f32_e32 v107, 0xbfb8aa3b, v107
	v_rcp_f32_e32 v110, v110
	v_add_f32_e32 v111, 1.0, v111
	v_exp_f32_e32 v107, v107
	v_rcp_f32_e32 v111, v111
	v_add_f32_e32 v112, 1.0, v112
	v_rcp_f32_e32 v112, v112
	v_add_f32_e32 v113, 1.0, v113
	v_pk_add_f32 v[108:109], v[108:109], v[76:77]
	v_lshlrev_b32_e32 v114, 16, v150
	v_rcp_f32_e32 v113, v113
	v_add_f32_e32 v106, 1.0, v106
	v_mul_f32_e32 v110, v110, v114
	v_and_b32_e32 v114, 0xffff0000, v150
	v_rcp_f32_e32 v106, v106
	v_add_f32_e32 v107, 1.0, v107
	v_mul_f32_e32 v108, 0xbfb8aa3b, v108
	v_mul_f32_e32 v111, v111, v114
	v_lshlrev_b32_e32 v114, 16, v151
	v_rcp_f32_e32 v107, v107
	v_exp_f32_e32 v108, v108
	v_mul_f32_e32 v109, 0xbfb8aa3b, v109
	v_mul_f32_e32 v112, v112, v114
	v_and_b32_e32 v114, 0xffff0000, v151
	v_exp_f32_e32 v109, v109
	v_mul_f32_e32 v113, v113, v114
	v_lshlrev_b32_e32 v114, 16, v152
	v_mul_f32_e32 v114, v106, v114
	v_and_b32_e32 v106, 0xffff0000, v152
	s_waitcnt lgkmcnt(0)
	v_mul_f32_e32 v115, v107, v106
	v_add_f32_e32 v106, 1.0, v108
	v_rcp_f32_e32 v106, v106
	v_add_f32_e32 v107, 1.0, v109
	v_rcp_f32_e32 v107, v107
	v_pk_add_f32 v[102:103], v[102:103], v[62:63]
	v_lshlrev_b32_e32 v108, 16, v153
	v_mul_f32_e32 v102, 0xbfb8aa3b, v102
	v_pk_add_f32 v[104:105], v[104:105], v[64:65]
	v_exp_f32_e32 v102, v102
	v_mul_f32_e32 v103, 0xbfb8aa3b, v103
	v_mul_f32_e32 v109, v106, v108
	v_and_b32_e32 v106, 0xffff0000, v153
	v_exp_f32_e32 v103, v103
	v_mul_f32_e32 v104, 0xbfb8aa3b, v104
	v_mul_f32_e32 v116, v107, v106
	v_mul_f32_e32 v106, v111, v111
	v_mul_f32_e32 v107, v113, v113
	v_pk_add_f32 v[98:99], v[98:99], v[58:59]
	v_exp_f32_e32 v104, v104
	v_mul_f32_e32 v105, 0xbfb8aa3b, v105
	v_fmac_f32_e32 v106, v110, v110
	v_fmac_f32_e32 v107, v112, v112
	v_exp_f32_e32 v105, v105
	v_mul_f32_e32 v98, 0xbfb8aa3b, v98
	v_add_f32_e32 v106, v106, v107
	v_mul_f32_e32 v107, v115, v115
	v_add_f32_e32 v102, 1.0, v102
	v_exp_f32_e32 v98, v98
	v_mul_f32_e32 v99, 0xbfb8aa3b, v99
	v_fmac_f32_e32 v107, v114, v114
	v_rcp_f32_e32 v102, v102
	v_add_f32_e32 v103, 1.0, v103
	v_exp_f32_e32 v99, v99
	v_add_f32_e32 v106, v107, v106
	v_mul_f32_e32 v107, v116, v116
	v_rcp_f32_e32 v103, v103
	v_add_f32_e32 v104, 1.0, v104
	v_fmac_f32_e32 v107, v109, v109
	v_rcp_f32_e32 v104, v104
	v_add_f32_e32 v105, 1.0, v105
	v_add_f32_e32 v117, v107, v106
	v_cvt_pk_bf16_f32 v107, v112, v113
	v_pk_add_f32 v[100:101], v[100:101], v[60:61]
	v_lshlrev_b32_e32 v112, 16, v146
	v_rcp_f32_e32 v105, v105
	v_add_f32_e32 v98, 1.0, v98
	v_mul_f32_e32 v102, v102, v112
	v_and_b32_e32 v112, 0xffff0000, v146
	v_rcp_f32_e32 v98, v98
	v_add_f32_e32 v99, 1.0, v99
	v_mul_f32_e32 v100, 0xbfb8aa3b, v100
	v_mul_f32_e32 v103, v103, v112
	v_lshlrev_b32_e32 v112, 16, v147
	v_rcp_f32_e32 v99, v99
	v_exp_f32_e32 v100, v100
	v_mul_f32_e32 v101, 0xbfb8aa3b, v101
	v_mul_f32_e32 v112, v104, v112
	v_and_b32_e32 v104, 0xffff0000, v147
	v_exp_f32_e32 v101, v101
	v_mul_f32_e32 v113, v105, v104
	v_lshlrev_b32_e32 v104, 16, v148
	v_cvt_pk_bf16_f32 v108, v114, v115
	v_mul_f32_e32 v114, v98, v104
	v_and_b32_e32 v98, 0xffff0000, v148
	v_mul_f32_e32 v115, v99, v98
	v_add_f32_e32 v98, 1.0, v100
	v_rcp_f32_e32 v98, v98
	v_add_f32_e32 v99, 1.0, v101
	v_rcp_f32_e32 v99, v99
	v_lshlrev_b32_e32 v100, 16, v149
	v_cvt_pk_bf16_f32 v109, v109, v116
	v_mul_f32_e32 v116, v98, v100
	v_and_b32_e32 v98, 0xffff0000, v149
	v_mul_f32_e32 v118, v99, v98
	v_mul_f32_e32 v98, v103, v103
	v_mul_f32_e32 v99, v113, v113
	v_fmac_f32_e32 v98, v102, v102
	v_fmac_f32_e32 v99, v112, v112
	v_add_f32_e32 v98, v98, v99
	v_mul_f32_e32 v99, v115, v115
	v_fmac_f32_e32 v99, v114, v114
	v_add_f32_e32 v98, v99, v98
	v_mul_f32_e32 v99, v118, v118
	v_fmac_f32_e32 v99, v116, v116
	v_add_f32_e32 v98, v99, v98
	v_add_f32_e32 v101, v117, v98
	ds_bpermute_b32 v117, v0, v101
	v_cvt_pk_bf16_f32 v106, v110, v111
	v_lshlrev_b64 v[110:111], 11, v[222:223]
	v_lshl_add_u64 v[98:99], s[70:71], 0, v[110:111]
	v_lshl_add_u64 v[104:105], v[206:207], 1, v[98:99]
	s_waitcnt lgkmcnt(0)
	v_add_f32_e32 v98, v101, v117
	ds_bpermute_b32 v99, v130, v98
	global_store_dwordx4 v[104:105], v[106:109], off sc1
	v_cvt_pk_bf16_f32 v100, v102, v103
	v_cvt_pk_bf16_f32 v101, v112, v113
	v_cvt_pk_bf16_f32 v102, v114, v115
	v_cvt_pk_bf16_f32 v103, v116, v118
	global_store_dwordx4 v[104:105], v[100:103], off offset:256 sc1
	s_and_saveexec_b64 s[10:11], vcc
	s_cbranch_execz .LBB0_750
	v_lshl_add_u64 v[100:101], s[78:79], 0, v[220:221]
	v_lshl_add_u64 v[100:101], s[54:55], 2, v[100:101]
	s_lshl_b32 s62, s85, 2
	v_lshl_add_u64 v[100:101], v[100:101], 0, s[62:63]
	s_waitcnt lgkmcnt(0)
	v_add_f32_e32 v98, v98, v99
	global_store_dword v[100:101], v98, off
; __device__ __forceinline__ unsigned pk2(float lo, float hi) { unsigned r; asm("v_cvt_pk_bf16_f32 %0, %1, %2" : "=v"(r) : "v"(lo), "v"(hi)); return r; }
; __device__ __forceinline__ float bflo(unsigned w) { return __uint_as_float(w << 16); }
; __device__ __forceinline__ float bfhi(unsigned w) { return __uint_as_float(w & 0xffff0000u); }
; __device__ __forceinline__ float sigmoidf_(float x) { return __builtin_amdgcn_rcpf(1.0f + __expf(-x)); }
;     __device__ __forceinline__ void operator()(const AccT& acc, const pg8::Unit& u, int ui, int wr, int wc, int fr, int fq) const {
;     ...
;             for (int m = 0; m < 4; ++m) {
;                 const int r = row0 + ai * 128 + m * 16; float ss = 0.f;
; #pragma unroll
;                 for (int bj = 0; bj < 2; ++bj) {
;                     const u32x4 zw = zv[m][bj];
;                     const f32x4 p0 = acc[ai][bj][m][0] + bv[bj][0], p1 = acc[ai][bj][m][1] + bv[bj][1];
;                     const float o0 = bflo(zw.x) * sigmoidf_(p0.x), o1 = bfhi(zw.x) * sigmoidf_(p0.y), o2 = bflo(zw.y) * sigmoidf_(p0.z), o3 = bfhi(zw.y) * sigmoidf_(p0.w);
;                     const float o4 = bflo(zw.z) * sigmoidf_(p1.x), o5 = bfhi(zw.z) * sigmoidf_(p1.y), o6 = bflo(zw.w) * sigmoidf_(p1.z), o7 = bfhi(zw.w) * sigmoidf_(p1.w);
;                     ss += (o0 * o0 + o1 * o1) + (o2 * o2 + o3 * o3) + (o4 * o4 + o5 * o5) + (o6 * o6 + o7 * o7);
;                     u32x4 w; w.x = pk2(o0, o1); w.y = pk2(o2, o3); w.z = pk2(o4, o5); w.w = pk2(o6, o7);
;                     *(u32x4*)(ys + (size_t)r * ldy + col0 + 128 * bj) = w;
;                 }
;                 ss += __shfl_xor(ss, 16); ss += __shfl_xor(ss, 32); if (fq == 0) part_s[(size_t)r * 8 + u.pn * 4 + wc] = ss;
.LBB0_750:
	s_or_b64 exec, exec, s[10:11]
	v_pk_add_f32 v[94:95], v[94:95], v[78:79]
	v_pk_add_f32 v[96:97], v[96:97], v[80:81]
	v_mul_f32_e32 v94, 0xbfb8aa3b, v94
	v_exp_f32_e32 v94, v94
	v_mul_f32_e32 v95, 0xbfb8aa3b, v95
	v_exp_f32_e32 v95, v95
	v_mul_f32_e32 v96, 0xbfb8aa3b, v96
	v_pk_add_f32 v[90:91], v[90:91], v[74:75]
	v_exp_f32_e32 v96, v96
	v_mul_f32_e32 v97, 0xbfb8aa3b, v97
	v_exp_f32_e32 v97, v97
	v_mul_f32_e32 v90, 0xbfb8aa3b, v90
	v_add_f32_e32 v94, 1.0, v94
	v_exp_f32_e32 v90, v90
	v_mul_f32_e32 v91, 0xbfb8aa3b, v91
	v_rcp_f32_e32 v94, v94
	v_add_f32_e32 v95, 1.0, v95
	v_exp_f32_e32 v91, v91
	v_rcp_f32_e32 v95, v95
	v_add_f32_e32 v96, 1.0, v96
	v_rcp_f32_e32 v96, v96
	v_add_f32_e32 v97, 1.0, v97
	v_pk_add_f32 v[92:93], v[92:93], v[76:77]
	v_lshlrev_b32_e32 v98, 16, v142
	v_rcp_f32_e32 v97, v97
	v_add_f32_e32 v90, 1.0, v90
	v_mul_f32_e32 v94, v94, v98
	v_and_b32_e32 v98, 0xffff0000, v142
	v_rcp_f32_e32 v90, v90
	v_add_f32_e32 v91, 1.0, v91
	v_mul_f32_e32 v92, 0xbfb8aa3b, v92
	v_mul_f32_e32 v95, v95, v98
	v_lshlrev_b32_e32 v98, 16, v143
	v_rcp_f32_e32 v91, v91
	v_exp_f32_e32 v92, v92
	v_mul_f32_e32 v93, 0xbfb8aa3b, v93
	v_mul_f32_e32 v96, v96, v98
	v_and_b32_e32 v98, 0xffff0000, v143
	v_exp_f32_e32 v93, v93
	v_mul_f32_e32 v97, v97, v98
	v_lshlrev_b32_e32 v98, 16, v144
	v_mul_f32_e32 v98, v90, v98
	v_and_b32_e32 v90, 0xffff0000, v144
	s_waitcnt lgkmcnt(0)
	v_mul_f32_e32 v99, v91, v90
	v_add_f32_e32 v90, 1.0, v92
	v_rcp_f32_e32 v90, v90
	v_add_f32_e32 v91, 1.0, v93
	v_rcp_f32_e32 v91, v91
	v_pk_add_f32 v[86:87], v[86:87], v[62:63]
	v_lshlrev_b32_e32 v92, 16, v145
	v_mul_f32_e32 v86, 0xbfb8aa3b, v86
	v_pk_add_f32 v[88:89], v[88:89], v[64:65]
	v_exp_f32_e32 v86, v86
	v_mul_f32_e32 v87, 0xbfb8aa3b, v87
	v_mul_f32_e32 v93, v90, v92
	v_and_b32_e32 v90, 0xffff0000, v145
	v_exp_f32_e32 v87, v87
	v_mul_f32_e32 v88, 0xbfb8aa3b, v88
	v_mul_f32_e32 v100, v91, v90
	v_mul_f32_e32 v90, v95, v95
	v_mul_f32_e32 v91, v97, v97
	v_pk_add_f32 v[82:83], v[82:83], v[58:59]
	v_exp_f32_e32 v88, v88
	v_mul_f32_e32 v89, 0xbfb8aa3b, v89
	v_fmac_f32_e32 v90, v94, v94
	v_fmac_f32_e32 v91, v96, v96
	v_exp_f32_e32 v89, v89
	v_mul_f32_e32 v82, 0xbfb8aa3b, v82
	v_add_f32_e32 v90, v90, v91
	v_mul_f32_e32 v91, v99, v99
	v_add_f32_e32 v86, 1.0, v86
	v_exp_f32_e32 v82, v82
	v_mul_f32_e32 v83, 0xbfb8aa3b, v83
	v_fmac_f32_e32 v91, v98, v98
	v_rcp_f32_e32 v86, v86
	v_add_f32_e32 v87, 1.0, v87
	v_exp_f32_e32 v83, v83
	v_add_f32_e32 v90, v91, v90
	v_mul_f32_e32 v91, v100, v100
	v_rcp_f32_e32 v87, v87
	v_add_f32_e32 v88, 1.0, v88
	v_fmac_f32_e32 v91, v93, v93
	v_rcp_f32_e32 v88, v88
	v_add_f32_e32 v89, 1.0, v89
	v_add_f32_e32 v101, v91, v90
	v_cvt_pk_bf16_f32 v91, v96, v97
	v_pk_add_f32 v[84:85], v[84:85], v[60:61]
	v_lshlrev_b32_e32 v96, 16, v138
	v_rcp_f32_e32 v89, v89
	v_add_f32_e32 v82, 1.0, v82
	v_mul_f32_e32 v86, v86, v96
	v_and_b32_e32 v96, 0xffff0000, v138
	v_rcp_f32_e32 v82, v82
	v_add_f32_e32 v83, 1.0, v83
	v_mul_f32_e32 v84, 0xbfb8aa3b, v84
	v_mul_f32_e32 v87, v87, v96
	v_lshlrev_b32_e32 v96, 16, v139
	v_rcp_f32_e32 v83, v83
	v_exp_f32_e32 v84, v84
	v_mul_f32_e32 v85, 0xbfb8aa3b, v85
	v_mul_f32_e32 v96, v88, v96
	v_and_b32_e32 v88, 0xffff0000, v139
	v_exp_f32_e32 v85, v85
	v_mul_f32_e32 v97, v89, v88
	v_lshlrev_b32_e32 v88, 16, v140
	v_cvt_pk_bf16_f32 v92, v98, v99
	v_mul_f32_e32 v98, v82, v88
	v_and_b32_e32 v82, 0xffff0000, v140
	v_mul_f32_e32 v99, v83, v82
	v_add_f32_e32 v82, 1.0, v84
	v_rcp_f32_e32 v82, v82
	v_add_f32_e32 v83, 1.0, v85
	v_rcp_f32_e32 v83, v83
	v_lshlrev_b32_e32 v84, 16, v141
	v_cvt_pk_bf16_f32 v93, v93, v100
	v_mul_f32_e32 v100, v82, v84
	v_and_b32_e32 v82, 0xffff0000, v141
	v_mul_f32_e32 v102, v83, v82
	v_mul_f32_e32 v82, v87, v87
	v_mul_f32_e32 v83, v97, v97
	v_fmac_f32_e32 v82, v86, v86
	v_fmac_f32_e32 v83, v96, v96
	v_add_f32_e32 v82, v82, v83
	v_mul_f32_e32 v83, v99, v99
	v_fmac_f32_e32 v83, v98, v98
	v_add_f32_e32 v82, v83, v82
	v_mul_f32_e32 v83, v102, v102
	v_fmac_f32_e32 v83, v100, v100
	v_add_f32_e32 v82, v83, v82
	v_add_f32_e32 v85, v101, v82
	ds_bpermute_b32 v101, v0, v85
	v_cvt_pk_bf16_f32 v90, v94, v95
	v_lshlrev_b64 v[94:95], 11, v[218:219]
	v_lshl_add_u64 v[82:83], s[70:71], 0, v[94:95]
	v_lshl_add_u64 v[88:89], v[206:207], 1, v[82:83]
	s_waitcnt lgkmcnt(0)
	v_add_f32_e32 v82, v85, v101
	ds_bpermute_b32 v83, v130, v82
	global_store_dwordx4 v[88:89], v[90:93], off sc1
	v_cvt_pk_bf16_f32 v84, v86, v87
	v_cvt_pk_bf16_f32 v85, v96, v97
	v_cvt_pk_bf16_f32 v86, v98, v99
	v_cvt_pk_bf16_f32 v87, v100, v102
	global_store_dwordx4 v[88:89], v[84:87], off offset:256 sc1
	s_and_saveexec_b64 s[10:11], vcc
	s_cbranch_execz .LBB0_752
	v_lshl_add_u64 v[84:85], s[78:79], 0, v[216:217]
	v_lshl_add_u64 v[84:85], s[54:55], 2, v[84:85]
	s_lshl_b32 s62, s85, 2
	v_lshl_add_u64 v[84:85], v[84:85], 0, s[62:63]
	s_waitcnt lgkmcnt(0)
	v_add_f32_e32 v82, v82, v83
	global_store_dword v[84:85], v82, off
; __device__ __forceinline__ unsigned pk2(float lo, float hi) { unsigned r; asm("v_cvt_pk_bf16_f32 %0, %1, %2" : "=v"(r) : "v"(lo), "v"(hi)); return r; }
; __device__ __forceinline__ float bflo(unsigned w) { return __uint_as_float(w << 16); }
; __device__ __forceinline__ float bfhi(unsigned w) { return __uint_as_float(w & 0xffff0000u); }
; __device__ __forceinline__ float sigmoidf_(float x) { return __builtin_amdgcn_rcpf(1.0f + __expf(-x)); }
;     __device__ __forceinline__ void operator()(const AccT& acc, const pg8::Unit& u, int ui, int wr, int wc, int fr, int fq) const {
;     ...
;         for (int ai = 0; ai < 2; ++ai) {
;             u32x4 zv[4][2];
; #pragma unroll
;             for (int m = 0; m < 4; ++m)
; #pragma unroll
;                 for (int bj = 0; bj < 2; ++bj) { const int col = col0 + 128 * bj; zv[m][bj] = *(const u32x4*)(zg + ((size_t)(col >> 4) * M + (row0 + ai * 128 + m * 16)) * 16 + (col & 15)); }
; #pragma unroll
;             for (int m = 0; m < 4; ++m) {
;                 const int r = row0 + ai * 128 + m * 16; float ss = 0.f;
; #pragma unroll
;                 for (int bj = 0; bj < 2; ++bj) {
;                     const u32x4 zw = zv[m][bj];
;                     const f32x4 p0 = acc[ai][bj][m][0] + bv[bj][0], p1 = acc[ai][bj][m][1] + bv[bj][1];
;                     const float o0 = bflo(zw.x) * sigmoidf_(p0.x), o1 = bfhi(zw.x) * sigmoidf_(p0.y), o2 = bflo(zw.y) * sigmoidf_(p0.z), o3 = bfhi(zw.y) * sigmoidf_(p0.w);
;                     const float o4 = bflo(zw.z) * sigmoidf_(p1.x), o5 = bfhi(zw.z) * sigmoidf_(p1.y), o6 = bflo(zw.w) * sigmoidf_(p1.z), o7 = bfhi(zw.w) * sigmoidf_(p1.w);
;                     ss += (o0 * o0 + o1 * o1) + (o2 * o2 + o3 * o3) + (o4 * o4 + o5 * o5) + (o6 * o6 + o7 * o7);
;                     u32x4 w; w.x = pk2(o0, o1); w.y = pk2(o2, o3); w.z = pk2(o4, o5); w.w = pk2(o6, o7);
;                     *(u32x4*)(ys + (size_t)r * ldy + col0 + 128 * bj) = w;
;                 }
;                 ss += __shfl_xor(ss, 16); ss += __shfl_xor(ss, 32); if (fq == 0) part_s[(size_t)r * 8 + u.pn * 4 + wc] = ss;
.LBB0_752:
	s_or_b64 exec, exec, s[10:11]
	v_add_u32_e32 v120, 0x80, v214
	v_ashrrev_i32_e32 v121, 31, v120
	v_lshlrev_b64 v[110:111], 5, v[120:121]
	s_waitcnt lgkmcnt(0)
	v_lshl_add_u64 v[82:83], v[208:209], 0, v[110:111]
	v_lshl_add_u64 v[84:85], v[82:83], 0, v[210:211]
	global_load_dwordx4 v[112:115], v[84:85], off
	v_pk_add_f32 v[66:67], v[66:67], v[74:75]
	v_add_u32_e32 v108, 0x90, v214
	v_mul_f32_e32 v84, 0xbfb8aa3b, v66
	v_mul_f32_e32 v85, 0xbfb8aa3b, v67
	v_lshl_add_u64 v[66:67], v[82:83], 0, v[212:213]
	global_load_dwordx4 v[116:119], v[66:67], off
	v_add_u32_e32 v104, 0xa0, v214
	v_add_u32_e32 v100, 0xb0, v214
	v_pk_add_f32 v[68:69], v[68:69], v[76:77]
	v_ashrrev_i32_e32 v109, 31, v108
	v_ashrrev_i32_e32 v105, 31, v104
	v_pk_add_f32 v[72:73], v[72:73], v[80:81]
	v_pk_add_f32 v[70:71], v[70:71], v[78:79]
	v_ashrrev_i32_e32 v101, 31, v100
	v_mul_f32_e32 v68, 0xbfb8aa3b, v68
	v_mul_f32_e32 v69, 0xbfb8aa3b, v69
	v_lshlrev_b64 v[106:107], 5, v[108:109]
	v_lshlrev_b64 v[102:103], 5, v[104:105]
	v_mul_f32_e32 v70, 0xbfb8aa3b, v70
	v_mul_f32_e32 v71, 0xbfb8aa3b, v71
	v_mul_f32_e32 v72, 0xbfb8aa3b, v72
	v_mul_f32_e32 v73, 0xbfb8aa3b, v73
	v_lshlrev_b64 v[98:99], 5, v[100:101]
	v_exp_f32_e32 v133, v68
	v_exp_f32_e32 v134, v69
	v_lshl_add_u64 v[66:67], v[208:209], 0, v[106:107]
	v_lshl_add_u64 v[68:69], v[208:209], 0, v[102:103]
	v_exp_f32_e32 v126, v70
	v_exp_f32_e32 v127, v71
	v_exp_f32_e32 v128, v72
	v_exp_f32_e32 v129, v73
	v_lshl_add_u64 v[70:71], v[208:209], 0, v[98:99]
	v_lshl_add_u64 v[72:73], v[66:67], 0, v[210:211]
	v_lshl_add_u64 v[66:67], v[66:67], 0, v[212:213]
	v_lshl_add_u64 v[82:83], v[68:69], 0, v[210:211]
	v_lshl_add_u64 v[68:69], v[68:69], 0, v[212:213]
	v_exp_f32_e32 v131, v84
	v_exp_f32_e32 v132, v85
	v_lshl_add_u64 v[122:123], v[70:71], 0, v[210:211]
	v_lshl_add_u64 v[124:125], v[70:71], 0, v[212:213]
	global_load_dwordx4 v[94:97], v[72:73], off
	global_load_dwordx4 v[90:93], v[66:67], off
	global_load_dwordx4 v[86:89], v[82:83], off
	s_nop 0
	global_load_dwordx4 v[82:85], v[68:69], off
	global_load_dwordx4 v[70:73], v[122:123], off
	s_nop 0
	global_load_dwordx4 v[66:69], v[124:125], off
	v_pk_add_f32 v[54:55], v[54:55], v[62:63]
	v_pk_add_f32 v[56:57], v[56:57], v[64:65]
	v_mul_f32_e32 v55, 0xbfb8aa3b, v55
	v_exp_f32_e32 v55, v55
	v_mul_f32_e32 v56, 0xbfb8aa3b, v56
	v_add_f32_e32 v123, 1.0, v127
	v_pk_add_f32 v[50:51], v[50:51], v[58:59]
	v_exp_f32_e32 v56, v56
	v_mul_f32_e32 v57, 0xbfb8aa3b, v57
	v_add_f32_e32 v122, 1.0, v126
	v_add_f32_e32 v124, 1.0, v128
	v_add_f32_e32 v126, 1.0, v131
	v_rcp_f32_e32 v123, v123
	v_mul_f32_e32 v54, 0xbfb8aa3b, v54
	v_exp_f32_e32 v57, v57
	v_mul_f32_e32 v50, 0xbfb8aa3b, v50
	v_rcp_f32_e32 v122, v122
	v_rcp_f32_e32 v124, v124
	v_rcp_f32_e32 v126, v126
	v_exp_f32_e32 v54, v54
	v_exp_f32_e32 v50, v50
	v_mul_f32_e32 v51, 0xbfb8aa3b, v51
	v_add_f32_e32 v55, 1.0, v55
	v_exp_f32_e32 v51, v51
	v_rcp_f32_e32 v55, v55
	v_add_f32_e32 v56, 1.0, v56
	v_add_f32_e32 v127, 1.0, v132
	v_add_f32_e32 v128, 1.0, v133
	v_rcp_f32_e32 v56, v56
	v_add_f32_e32 v57, 1.0, v57
	v_pk_add_f32 v[52:53], v[52:53], v[60:61]
	v_add_f32_e32 v54, 1.0, v54
	v_rcp_f32_e32 v57, v57
	v_add_f32_e32 v50, 1.0, v50
	v_rcp_f32_e32 v54, v54
	v_rcp_f32_e32 v50, v50
	v_add_f32_e32 v51, 1.0, v51
	v_mul_f32_e32 v52, 0xbfb8aa3b, v52
	s_waitcnt vmcnt(7)
	v_lshlrev_b32_e32 v131, 16, v112
	v_and_b32_e32 v112, 0xffff0000, v112
	v_lshlrev_b32_e32 v132, 16, v113
	v_lshlrev_b32_e32 v133, 16, v114
	v_mul_f32_e32 v112, v123, v112
	v_mul_f32_e32 v122, v122, v131
	v_mul_f32_e32 v123, v124, v132
	v_mul_f32_e32 v124, v126, v133
	v_mul_f32_e32 v126, v112, v112
	v_fmac_f32_e32 v126, v122, v122
	v_cvt_pk_bf16_f32 v112, v122, v112
	s_waitcnt vmcnt(6)
	v_lshlrev_b32_e32 v122, 16, v116
	v_and_b32_e32 v116, 0xffff0000, v116
	v_mul_f32_e32 v55, v55, v116
	v_lshlrev_b32_e32 v116, 16, v117
	v_rcp_f32_e32 v51, v51
	v_exp_f32_e32 v52, v52
	v_mul_f32_e32 v53, 0xbfb8aa3b, v53
	v_mul_f32_e32 v116, v56, v116
	v_and_b32_e32 v56, 0xffff0000, v117
	v_exp_f32_e32 v53, v53
	v_add_f32_e32 v125, 1.0, v129
	v_mul_f32_e32 v117, v57, v56
	v_lshlrev_b32_e32 v56, 16, v118
	v_rcp_f32_e32 v125, v125
	v_mul_f32_e32 v54, v54, v122
	v_mul_f32_e32 v122, v50, v56
	v_and_b32_e32 v50, 0xffff0000, v118
	v_rcp_f32_e32 v127, v127
	v_mul_f32_e32 v118, v51, v50
	v_add_f32_e32 v50, 1.0, v52
	v_rcp_f32_e32 v50, v50
	v_add_f32_e32 v51, 1.0, v53
	v_and_b32_e32 v113, 0xffff0000, v113
	v_rcp_f32_e32 v51, v51
	v_and_b32_e32 v114, 0xffff0000, v114
	v_mul_f32_e32 v113, v125, v113
	v_add_f32_e32 v129, 1.0, v134
	v_mul_f32_e32 v114, v127, v114
	v_mul_f32_e32 v127, v113, v113
	v_lshlrev_b32_e32 v52, 16, v119
	v_rcp_f32_e32 v128, v128
	v_rcp_f32_e32 v129, v129
	v_fmac_f32_e32 v127, v123, v123
	v_cvt_pk_bf16_f32 v113, v123, v113
	v_mul_f32_e32 v123, v50, v52
	v_and_b32_e32 v50, 0xffff0000, v119
	v_mul_f32_e32 v119, v51, v50
	v_mul_f32_e32 v50, v55, v55
	v_mul_f32_e32 v51, v117, v117
	v_fmac_f32_e32 v50, v54, v54
	v_fmac_f32_e32 v51, v116, v116
	v_lshlrev_b32_e32 v134, 16, v115
	v_and_b32_e32 v115, 0xffff0000, v115
	v_add_f32_e32 v50, v50, v51
	v_mul_f32_e32 v51, v118, v118
	v_mul_f32_e32 v125, v128, v134
	v_mul_f32_e32 v115, v129, v115
	v_mul_f32_e32 v128, v114, v114
	v_fmac_f32_e32 v51, v122, v122
	v_add_f32_e32 v126, v126, v127
	v_fmac_f32_e32 v128, v124, v124
	v_mul_f32_e32 v127, v115, v115
	v_add_f32_e32 v50, v51, v50
	v_mul_f32_e32 v51, v119, v119
	v_add_f32_e32 v126, v128, v126
	v_fmac_f32_e32 v127, v125, v125
	v_fmac_f32_e32 v51, v123, v123
	v_add_f32_e32 v126, v127, v126
	v_add_f32_e32 v50, v51, v50
	v_add_f32_e32 v53, v126, v50
	v_cvt_pk_bf16_f32 v114, v124, v114
	ds_bpermute_b32 v124, v0, v53
	v_lshlrev_b64 v[120:121], 11, v[120:121]
	v_lshl_add_u64 v[50:51], s[70:71], 0, v[120:121]
	v_lshl_add_u64 v[56:57], v[206:207], 1, v[50:51]
	v_cvt_pk_bf16_f32 v115, v125, v115
	s_waitcnt lgkmcnt(0)
	v_add_f32_e32 v50, v53, v124
	ds_bpermute_b32 v51, v130, v50
	global_store_dwordx4 v[56:57], v[112:115], off sc1
	v_cvt_pk_bf16_f32 v52, v54, v55
	v_cvt_pk_bf16_f32 v53, v116, v117
	v_cvt_pk_bf16_f32 v54, v122, v118
	v_cvt_pk_bf16_f32 v55, v123, v119
	global_store_dwordx4 v[56:57], v[52:55], off offset:256 sc1
	s_and_saveexec_b64 s[10:11], vcc
	s_cbranch_execz .LBB0_754
	v_lshl_add_u64 v[52:53], s[78:79], 0, v[110:111]
	v_lshl_add_u64 v[52:53], s[54:55], 2, v[52:53]
	s_lshl_b32 s62, s85, 2
	v_lshl_add_u64 v[52:53], v[52:53], 0, s[62:63]
	s_waitcnt lgkmcnt(0)
	v_add_f32_e32 v50, v50, v51
	global_store_dword v[52:53], v50, off
; __device__ __forceinline__ unsigned pk2(float lo, float hi) { unsigned r; asm("v_cvt_pk_bf16_f32 %0, %1, %2" : "=v"(r) : "v"(lo), "v"(hi)); return r; }
; __device__ __forceinline__ float bflo(unsigned w) { return __uint_as_float(w << 16); }
; __device__ __forceinline__ float bfhi(unsigned w) { return __uint_as_float(w & 0xffff0000u); }
; __device__ __forceinline__ float sigmoidf_(float x) { return __builtin_amdgcn_rcpf(1.0f + __expf(-x)); }
;     __device__ __forceinline__ void operator()(const AccT& acc, const pg8::Unit& u, int ui, int wr, int wc, int fr, int fq) const {
;     ...
;             for (int m = 0; m < 4; ++m) {
;                 const int r = row0 + ai * 128 + m * 16; float ss = 0.f;
; #pragma unroll
;                 for (int bj = 0; bj < 2; ++bj) {
;                     const u32x4 zw = zv[m][bj];
;                     const f32x4 p0 = acc[ai][bj][m][0] + bv[bj][0], p1 = acc[ai][bj][m][1] + bv[bj][1];
;                     const float o0 = bflo(zw.x) * sigmoidf_(p0.x), o1 = bfhi(zw.x) * sigmoidf_(p0.y), o2 = bflo(zw.y) * sigmoidf_(p0.z), o3 = bfhi(zw.y) * sigmoidf_(p0.w);
;                     const float o4 = bflo(zw.z) * sigmoidf_(p1.x), o5 = bfhi(zw.z) * sigmoidf_(p1.y), o6 = bflo(zw.w) * sigmoidf_(p1.z), o7 = bfhi(zw.w) * sigmoidf_(p1.w);
;                     ss += (o0 * o0 + o1 * o1) + (o2 * o2 + o3 * o3) + (o4 * o4 + o5 * o5) + (o6 * o6 + o7 * o7);
;                     u32x4 w; w.x = pk2(o0, o1); w.y = pk2(o2, o3); w.z = pk2(o4, o5); w.w = pk2(o6, o7);
;                     *(u32x4*)(ys + (size_t)r * ldy + col0 + 128 * bj) = w;
;                 }
;                 ss += __shfl_xor(ss, 16); ss += __shfl_xor(ss, 32); if (fq == 0) part_s[(size_t)r * 8 + u.pn * 4 + wc] = ss;
.LBB0_754:
	s_or_b64 exec, exec, s[10:11]
	v_pk_add_f32 v[46:47], v[46:47], v[78:79]
	v_pk_add_f32 v[48:49], v[48:49], v[80:81]
	v_mul_f32_e32 v46, 0xbfb8aa3b, v46
	v_exp_f32_e32 v46, v46
	v_mul_f32_e32 v47, 0xbfb8aa3b, v47
	v_exp_f32_e32 v47, v47
	v_mul_f32_e32 v48, 0xbfb8aa3b, v48
	v_pk_add_f32 v[42:43], v[42:43], v[74:75]
	v_exp_f32_e32 v48, v48
	v_mul_f32_e32 v49, 0xbfb8aa3b, v49
	v_exp_f32_e32 v49, v49
	v_mul_f32_e32 v42, 0xbfb8aa3b, v42
	v_add_f32_e32 v46, 1.0, v46
	v_exp_f32_e32 v42, v42
	v_mul_f32_e32 v43, 0xbfb8aa3b, v43
	v_rcp_f32_e32 v46, v46
	v_add_f32_e32 v47, 1.0, v47
	v_exp_f32_e32 v43, v43
	v_rcp_f32_e32 v47, v47
	v_add_f32_e32 v48, 1.0, v48
	v_rcp_f32_e32 v48, v48
	v_add_f32_e32 v49, 1.0, v49
	v_pk_add_f32 v[44:45], v[44:45], v[76:77]
	s_waitcnt vmcnt(7)
	v_lshlrev_b32_e32 v50, 16, v94
	v_rcp_f32_e32 v49, v49
	v_add_f32_e32 v42, 1.0, v42
	v_mul_f32_e32 v46, v46, v50
	v_and_b32_e32 v50, 0xffff0000, v94
	v_rcp_f32_e32 v42, v42
	v_add_f32_e32 v43, 1.0, v43
	v_mul_f32_e32 v44, 0xbfb8aa3b, v44
	v_mul_f32_e32 v47, v47, v50
	v_lshlrev_b32_e32 v50, 16, v95
	v_rcp_f32_e32 v43, v43
	v_exp_f32_e32 v44, v44
	v_mul_f32_e32 v45, 0xbfb8aa3b, v45
	v_mul_f32_e32 v48, v48, v50
	v_and_b32_e32 v50, 0xffff0000, v95
	v_exp_f32_e32 v45, v45
	v_mul_f32_e32 v49, v49, v50
	v_lshlrev_b32_e32 v50, 16, v96
	v_mul_f32_e32 v50, v42, v50
	v_and_b32_e32 v42, 0xffff0000, v96
	s_waitcnt lgkmcnt(0)
	v_mul_f32_e32 v51, v43, v42
	v_add_f32_e32 v42, 1.0, v44
	v_rcp_f32_e32 v42, v42
	v_add_f32_e32 v43, 1.0, v45
	v_rcp_f32_e32 v43, v43
	v_pk_add_f32 v[38:39], v[38:39], v[62:63]
	v_lshlrev_b32_e32 v44, 16, v97
	v_mul_f32_e32 v38, 0xbfb8aa3b, v38
	v_pk_add_f32 v[40:41], v[40:41], v[64:65]
	v_exp_f32_e32 v38, v38
	v_mul_f32_e32 v39, 0xbfb8aa3b, v39
	v_mul_f32_e32 v45, v42, v44
	v_and_b32_e32 v42, 0xffff0000, v97
	v_exp_f32_e32 v39, v39
	v_mul_f32_e32 v40, 0xbfb8aa3b, v40
	v_mul_f32_e32 v52, v43, v42
	v_mul_f32_e32 v42, v47, v47
	v_mul_f32_e32 v43, v49, v49
	v_pk_add_f32 v[34:35], v[34:35], v[58:59]
	v_exp_f32_e32 v40, v40
	v_mul_f32_e32 v41, 0xbfb8aa3b, v41
	v_fmac_f32_e32 v42, v46, v46
	v_fmac_f32_e32 v43, v48, v48
	v_exp_f32_e32 v41, v41
	v_mul_f32_e32 v34, 0xbfb8aa3b, v34
	v_add_f32_e32 v42, v42, v43
	v_mul_f32_e32 v43, v51, v51
	v_add_f32_e32 v38, 1.0, v38
	v_exp_f32_e32 v34, v34
	v_mul_f32_e32 v35, 0xbfb8aa3b, v35
	v_fmac_f32_e32 v43, v50, v50
	v_rcp_f32_e32 v38, v38
	v_add_f32_e32 v39, 1.0, v39
	v_exp_f32_e32 v35, v35
	v_add_f32_e32 v42, v43, v42
	v_mul_f32_e32 v43, v52, v52
	v_rcp_f32_e32 v39, v39
	v_add_f32_e32 v40, 1.0, v40
	v_fmac_f32_e32 v43, v45, v45
	v_rcp_f32_e32 v40, v40
	v_add_f32_e32 v41, 1.0, v41
	v_add_f32_e32 v53, v43, v42
	v_cvt_pk_bf16_f32 v43, v48, v49
	v_pk_add_f32 v[36:37], v[36:37], v[60:61]
	s_waitcnt vmcnt(6)
	v_lshlrev_b32_e32 v48, 16, v90
	v_rcp_f32_e32 v41, v41
	v_add_f32_e32 v34, 1.0, v34
	v_mul_f32_e32 v38, v38, v48
	v_and_b32_e32 v48, 0xffff0000, v90
	v_rcp_f32_e32 v34, v34
	v_add_f32_e32 v35, 1.0, v35
	v_mul_f32_e32 v36, 0xbfb8aa3b, v36
	v_mul_f32_e32 v39, v39, v48
	v_lshlrev_b32_e32 v48, 16, v91
	v_rcp_f32_e32 v35, v35
	v_exp_f32_e32 v36, v36
	v_mul_f32_e32 v37, 0xbfb8aa3b, v37
	v_mul_f32_e32 v48, v40, v48
	v_and_b32_e32 v40, 0xffff0000, v91
	v_exp_f32_e32 v37, v37
	v_mul_f32_e32 v49, v41, v40
	v_lshlrev_b32_e32 v40, 16, v92
	v_cvt_pk_bf16_f32 v44, v50, v51
	v_mul_f32_e32 v50, v34, v40
	v_and_b32_e32 v34, 0xffff0000, v92
	v_mul_f32_e32 v51, v35, v34
	v_add_f32_e32 v34, 1.0, v36
	v_rcp_f32_e32 v34, v34
	v_add_f32_e32 v35, 1.0, v37
	v_rcp_f32_e32 v35, v35
	v_lshlrev_b32_e32 v36, 16, v93
	v_cvt_pk_bf16_f32 v45, v45, v52
	v_mul_f32_e32 v52, v34, v36
	v_and_b32_e32 v34, 0xffff0000, v93
	v_mul_f32_e32 v54, v35, v34
	v_mul_f32_e32 v34, v39, v39
	v_mul_f32_e32 v35, v49, v49
	v_fmac_f32_e32 v34, v38, v38
	v_fmac_f32_e32 v35, v48, v48
	v_add_f32_e32 v34, v34, v35
	v_mul_f32_e32 v35, v51, v51
	v_fmac_f32_e32 v35, v50, v50
	v_add_f32_e32 v34, v35, v34
	v_mul_f32_e32 v35, v54, v54
	v_fmac_f32_e32 v35, v52, v52
	v_add_f32_e32 v34, v35, v34
	v_add_f32_e32 v37, v53, v34
	ds_bpermute_b32 v53, v0, v37
	v_cvt_pk_bf16_f32 v42, v46, v47
	v_lshlrev_b64 v[46:47], 11, v[108:109]
	v_lshl_add_u64 v[34:35], s[70:71], 0, v[46:47]
	v_lshl_add_u64 v[40:41], v[206:207], 1, v[34:35]
	s_waitcnt lgkmcnt(0)
	v_add_f32_e32 v34, v37, v53
	ds_bpermute_b32 v35, v130, v34
	global_store_dwordx4 v[40:41], v[42:45], off sc1
	v_cvt_pk_bf16_f32 v36, v38, v39
	v_cvt_pk_bf16_f32 v37, v48, v49
	v_cvt_pk_bf16_f32 v38, v50, v51
	v_cvt_pk_bf16_f32 v39, v52, v54
	global_store_dwordx4 v[40:41], v[36:39], off offset:256 sc1
	s_and_saveexec_b64 s[10:11], vcc
	s_cbranch_execz .LBB0_756
	v_lshl_add_u64 v[36:37], s[78:79], 0, v[106:107]
	v_lshl_add_u64 v[36:37], s[54:55], 2, v[36:37]
	s_lshl_b32 s62, s85, 2
	v_lshl_add_u64 v[36:37], v[36:37], 0, s[62:63]
	s_waitcnt lgkmcnt(0)
	v_add_f32_e32 v34, v34, v35
	global_store_dword v[36:37], v34, off
; __device__ __forceinline__ unsigned pk2(float lo, float hi) { unsigned r; asm("v_cvt_pk_bf16_f32 %0, %1, %2" : "=v"(r) : "v"(lo), "v"(hi)); return r; }
; __device__ __forceinline__ float bflo(unsigned w) { return __uint_as_float(w << 16); }
; __device__ __forceinline__ float bfhi(unsigned w) { return __uint_as_float(w & 0xffff0000u); }
; __device__ __forceinline__ float sigmoidf_(float x) { return __builtin_amdgcn_rcpf(1.0f + __expf(-x)); }
;     __device__ __forceinline__ void operator()(const AccT& acc, const pg8::Unit& u, int ui, int wr, int wc, int fr, int fq) const {
;     ...
;             for (int m = 0; m < 4; ++m) {
;                 const int r = row0 + ai * 128 + m * 16; float ss = 0.f;
; #pragma unroll
;                 for (int bj = 0; bj < 2; ++bj) {
;                     const u32x4 zw = zv[m][bj];
;                     const f32x4 p0 = acc[ai][bj][m][0] + bv[bj][0], p1 = acc[ai][bj][m][1] + bv[bj][1];
;                     const float o0 = bflo(zw.x) * sigmoidf_(p0.x), o1 = bfhi(zw.x) * sigmoidf_(p0.y), o2 = bflo(zw.y) * sigmoidf_(p0.z), o3 = bfhi(zw.y) * sigmoidf_(p0.w);
;                     const float o4 = bflo(zw.z) * sigmoidf_(p1.x), o5 = bfhi(zw.z) * sigmoidf_(p1.y), o6 = bflo(zw.w) * sigmoidf_(p1.z), o7 = bfhi(zw.w) * sigmoidf_(p1.w);
;                     ss += (o0 * o0 + o1 * o1) + (o2 * o2 + o3 * o3) + (o4 * o4 + o5 * o5) + (o6 * o6 + o7 * o7);
;                     u32x4 w; w.x = pk2(o0, o1); w.y = pk2(o2, o3); w.z = pk2(o4, o5); w.w = pk2(o6, o7);
;                     *(u32x4*)(ys + (size_t)r * ldy + col0 + 128 * bj) = w;
;                 }
;                 ss += __shfl_xor(ss, 16); ss += __shfl_xor(ss, 32); if (fq == 0) part_s[(size_t)r * 8 + u.pn * 4 + wc] = ss;
.LBB0_756:
	s_or_b64 exec, exec, s[10:11]
	v_pk_add_f32 v[30:31], v[30:31], v[78:79]
	v_pk_add_f32 v[32:33], v[32:33], v[80:81]
	v_mul_f32_e32 v30, 0xbfb8aa3b, v30
	v_exp_f32_e32 v30, v30
	v_mul_f32_e32 v31, 0xbfb8aa3b, v31
	v_exp_f32_e32 v31, v31
	v_mul_f32_e32 v32, 0xbfb8aa3b, v32
	v_pk_add_f32 v[26:27], v[26:27], v[74:75]
	v_exp_f32_e32 v32, v32
	v_mul_f32_e32 v33, 0xbfb8aa3b, v33
	v_exp_f32_e32 v33, v33
	v_mul_f32_e32 v26, 0xbfb8aa3b, v26
	v_add_f32_e32 v30, 1.0, v30
	v_exp_f32_e32 v26, v26
	v_mul_f32_e32 v27, 0xbfb8aa3b, v27
	v_rcp_f32_e32 v30, v30
	v_add_f32_e32 v31, 1.0, v31
	v_exp_f32_e32 v27, v27
	v_rcp_f32_e32 v31, v31
	v_add_f32_e32 v32, 1.0, v32
	v_rcp_f32_e32 v32, v32
	v_add_f32_e32 v33, 1.0, v33
	v_pk_add_f32 v[28:29], v[28:29], v[76:77]
	s_waitcnt vmcnt(7)
	v_lshlrev_b32_e32 v34, 16, v86
	v_rcp_f32_e32 v33, v33
	v_add_f32_e32 v26, 1.0, v26
	v_mul_f32_e32 v30, v30, v34
	v_and_b32_e32 v34, 0xffff0000, v86
	v_rcp_f32_e32 v26, v26
	v_add_f32_e32 v27, 1.0, v27
	v_mul_f32_e32 v28, 0xbfb8aa3b, v28
	v_mul_f32_e32 v31, v31, v34
	v_lshlrev_b32_e32 v34, 16, v87
	v_rcp_f32_e32 v27, v27
	v_exp_f32_e32 v28, v28
	v_mul_f32_e32 v29, 0xbfb8aa3b, v29
	v_mul_f32_e32 v32, v32, v34
	v_and_b32_e32 v34, 0xffff0000, v87
	v_exp_f32_e32 v29, v29
	v_mul_f32_e32 v33, v33, v34
	v_lshlrev_b32_e32 v34, 16, v88
	v_mul_f32_e32 v34, v26, v34
	v_and_b32_e32 v26, 0xffff0000, v88
	s_waitcnt lgkmcnt(0)
	v_mul_f32_e32 v35, v27, v26
	v_add_f32_e32 v26, 1.0, v28
	v_rcp_f32_e32 v26, v26
	v_add_f32_e32 v27, 1.0, v29
	v_rcp_f32_e32 v27, v27
	v_pk_add_f32 v[22:23], v[22:23], v[62:63]
	v_lshlrev_b32_e32 v28, 16, v89
	v_mul_f32_e32 v22, 0xbfb8aa3b, v22
	v_pk_add_f32 v[24:25], v[24:25], v[64:65]
	v_exp_f32_e32 v22, v22
	v_mul_f32_e32 v23, 0xbfb8aa3b, v23
	v_mul_f32_e32 v29, v26, v28
	v_and_b32_e32 v26, 0xffff0000, v89
	v_exp_f32_e32 v23, v23
	v_mul_f32_e32 v24, 0xbfb8aa3b, v24
	v_mul_f32_e32 v36, v27, v26
	v_mul_f32_e32 v26, v31, v31
	v_mul_f32_e32 v27, v33, v33
	v_pk_add_f32 v[18:19], v[18:19], v[58:59]
	v_exp_f32_e32 v24, v24
	v_mul_f32_e32 v25, 0xbfb8aa3b, v25
	v_fmac_f32_e32 v26, v30, v30
	v_fmac_f32_e32 v27, v32, v32
	v_exp_f32_e32 v25, v25
	v_mul_f32_e32 v18, 0xbfb8aa3b, v18
	v_add_f32_e32 v26, v26, v27
	v_mul_f32_e32 v27, v35, v35
	v_add_f32_e32 v22, 1.0, v22
	v_exp_f32_e32 v18, v18
	v_mul_f32_e32 v19, 0xbfb8aa3b, v19
	v_fmac_f32_e32 v27, v34, v34
	v_rcp_f32_e32 v22, v22
	v_add_f32_e32 v23, 1.0, v23
	v_exp_f32_e32 v19, v19
	v_add_f32_e32 v26, v27, v26
	v_mul_f32_e32 v27, v36, v36
	v_rcp_f32_e32 v23, v23
	v_add_f32_e32 v24, 1.0, v24
	v_fmac_f32_e32 v27, v29, v29
	v_rcp_f32_e32 v24, v24
	v_add_f32_e32 v25, 1.0, v25
	v_add_f32_e32 v37, v27, v26
	v_cvt_pk_bf16_f32 v27, v32, v33
	v_pk_add_f32 v[20:21], v[20:21], v[60:61]
	s_waitcnt vmcnt(6)
	v_lshlrev_b32_e32 v32, 16, v82
	v_rcp_f32_e32 v25, v25
	v_add_f32_e32 v18, 1.0, v18
	v_mul_f32_e32 v22, v22, v32
	v_and_b32_e32 v32, 0xffff0000, v82
	v_rcp_f32_e32 v18, v18
	v_add_f32_e32 v19, 1.0, v19
	v_mul_f32_e32 v20, 0xbfb8aa3b, v20
	v_mul_f32_e32 v23, v23, v32
	v_lshlrev_b32_e32 v32, 16, v83
	v_rcp_f32_e32 v19, v19
	v_exp_f32_e32 v20, v20
	v_mul_f32_e32 v21, 0xbfb8aa3b, v21
	v_mul_f32_e32 v32, v24, v32
	v_and_b32_e32 v24, 0xffff0000, v83
	v_exp_f32_e32 v21, v21
	v_mul_f32_e32 v33, v25, v24
	v_lshlrev_b32_e32 v24, 16, v84
	v_cvt_pk_bf16_f32 v28, v34, v35
	v_mul_f32_e32 v34, v18, v24
	v_and_b32_e32 v18, 0xffff0000, v84
	v_mul_f32_e32 v35, v19, v18
	v_add_f32_e32 v18, 1.0, v20
	v_rcp_f32_e32 v18, v18
	v_add_f32_e32 v19, 1.0, v21
	v_rcp_f32_e32 v19, v19
	v_lshlrev_b32_e32 v20, 16, v85
	v_cvt_pk_bf16_f32 v29, v29, v36
	v_mul_f32_e32 v36, v18, v20
	v_and_b32_e32 v18, 0xffff0000, v85
	v_mul_f32_e32 v38, v19, v18
	v_mul_f32_e32 v18, v23, v23
	v_mul_f32_e32 v19, v33, v33
	v_fmac_f32_e32 v18, v22, v22
	v_fmac_f32_e32 v19, v32, v32
	v_add_f32_e32 v18, v18, v19
	v_mul_f32_e32 v19, v35, v35
	v_fmac_f32_e32 v19, v34, v34
	v_add_f32_e32 v18, v19, v18
	v_mul_f32_e32 v19, v38, v38
	v_fmac_f32_e32 v19, v36, v36
	v_add_f32_e32 v18, v19, v18
	v_add_f32_e32 v21, v37, v18
	ds_bpermute_b32 v37, v0, v21
	v_cvt_pk_bf16_f32 v26, v30, v31
	v_lshlrev_b64 v[30:31], 11, v[104:105]
	v_lshl_add_u64 v[18:19], s[70:71], 0, v[30:31]
	v_lshl_add_u64 v[24:25], v[206:207], 1, v[18:19]
	s_waitcnt lgkmcnt(0)
	v_add_f32_e32 v18, v21, v37
	ds_bpermute_b32 v19, v130, v18
	global_store_dwordx4 v[24:25], v[26:29], off sc1
	v_cvt_pk_bf16_f32 v20, v22, v23
	v_cvt_pk_bf16_f32 v21, v32, v33
	v_cvt_pk_bf16_f32 v22, v34, v35
	v_cvt_pk_bf16_f32 v23, v36, v38
	global_store_dwordx4 v[24:25], v[20:23], off offset:256 sc1
	s_and_saveexec_b64 s[10:11], vcc
	s_cbranch_execz .LBB0_758
	v_lshl_add_u64 v[20:21], s[78:79], 0, v[102:103]
	v_lshl_add_u64 v[20:21], s[54:55], 2, v[20:21]
	s_lshl_b32 s62, s85, 2
	v_lshl_add_u64 v[20:21], v[20:21], 0, s[62:63]
	s_waitcnt lgkmcnt(0)
	v_add_f32_e32 v18, v18, v19
	global_store_dword v[20:21], v18, off
; __device__ __forceinline__ unsigned pk2(float lo, float hi) { unsigned r; asm("v_cvt_pk_bf16_f32 %0, %1, %2" : "=v"(r) : "v"(lo), "v"(hi)); return r; }
; __device__ __forceinline__ float bflo(unsigned w) { return __uint_as_float(w << 16); }
; __device__ __forceinline__ float bfhi(unsigned w) { return __uint_as_float(w & 0xffff0000u); }
; __device__ __forceinline__ float sigmoidf_(float x) { return __builtin_amdgcn_rcpf(1.0f + __expf(-x)); }
;     __device__ __forceinline__ void operator()(const AccT& acc, const pg8::Unit& u, int ui, int wr, int wc, int fr, int fq) const {
;     ...
;             for (int m = 0; m < 4; ++m) {
;                 const int r = row0 + ai * 128 + m * 16; float ss = 0.f;
; #pragma unroll
;                 for (int bj = 0; bj < 2; ++bj) {
;                     const u32x4 zw = zv[m][bj];
;                     const f32x4 p0 = acc[ai][bj][m][0] + bv[bj][0], p1 = acc[ai][bj][m][1] + bv[bj][1];
;                     const float o0 = bflo(zw.x) * sigmoidf_(p0.x), o1 = bfhi(zw.x) * sigmoidf_(p0.y), o2 = bflo(zw.y) * sigmoidf_(p0.z), o3 = bfhi(zw.y) * sigmoidf_(p0.w);
;                     const float o4 = bflo(zw.z) * sigmoidf_(p1.x), o5 = bfhi(zw.z) * sigmoidf_(p1.y), o6 = bflo(zw.w) * sigmoidf_(p1.z), o7 = bfhi(zw.w) * sigmoidf_(p1.w);
;                     ss += (o0 * o0 + o1 * o1) + (o2 * o2 + o3 * o3) + (o4 * o4 + o5 * o5) + (o6 * o6 + o7 * o7);
;                     u32x4 w; w.x = pk2(o0, o1); w.y = pk2(o2, o3); w.z = pk2(o4, o5); w.w = pk2(o6, o7);
;                     *(u32x4*)(ys + (size_t)r * ldy + col0 + 128 * bj) = w;
;                 }
;                 ss += __shfl_xor(ss, 16); ss += __shfl_xor(ss, 32); if (fq == 0) part_s[(size_t)r * 8 + u.pn * 4 + wc] = ss;
.LBB0_758:
	s_or_b64 exec, exec, s[10:11]
	v_pk_add_f32 v[14:15], v[14:15], v[78:79]
	v_pk_add_f32 v[16:17], v[16:17], v[80:81]
	v_mul_f32_e32 v14, 0xbfb8aa3b, v14
	v_exp_f32_e32 v14, v14
	v_mul_f32_e32 v15, 0xbfb8aa3b, v15
	v_exp_f32_e32 v15, v15
	v_mul_f32_e32 v16, 0xbfb8aa3b, v16
	v_pk_add_f32 v[10:11], v[10:11], v[74:75]
	v_exp_f32_e32 v16, v16
	v_mul_f32_e32 v17, 0xbfb8aa3b, v17
	v_exp_f32_e32 v17, v17
	v_mul_f32_e32 v10, 0xbfb8aa3b, v10
	v_add_f32_e32 v14, 1.0, v14
	v_exp_f32_e32 v10, v10
	v_mul_f32_e32 v11, 0xbfb8aa3b, v11
	v_rcp_f32_e32 v14, v14
	v_add_f32_e32 v15, 1.0, v15
	v_exp_f32_e32 v11, v11
	v_rcp_f32_e32 v15, v15
	v_add_f32_e32 v16, 1.0, v16
	v_rcp_f32_e32 v16, v16
	v_add_f32_e32 v17, 1.0, v17
	v_pk_add_f32 v[12:13], v[12:13], v[76:77]
	s_waitcnt vmcnt(7)
	v_lshlrev_b32_e32 v18, 16, v70
	v_rcp_f32_e32 v17, v17
	v_add_f32_e32 v10, 1.0, v10
	v_mul_f32_e32 v14, v14, v18
	v_and_b32_e32 v18, 0xffff0000, v70
	v_rcp_f32_e32 v10, v10
	v_add_f32_e32 v11, 1.0, v11
	v_mul_f32_e32 v12, 0xbfb8aa3b, v12
	v_mul_f32_e32 v15, v15, v18
	v_lshlrev_b32_e32 v18, 16, v71
	v_rcp_f32_e32 v11, v11
	v_exp_f32_e32 v12, v12
	v_mul_f32_e32 v13, 0xbfb8aa3b, v13
	v_mul_f32_e32 v16, v16, v18
	v_and_b32_e32 v18, 0xffff0000, v71
	v_exp_f32_e32 v13, v13
	v_mul_f32_e32 v17, v17, v18
	v_lshlrev_b32_e32 v18, 16, v72
	v_mul_f32_e32 v18, v10, v18
	v_and_b32_e32 v10, 0xffff0000, v72
	s_waitcnt lgkmcnt(0)
	v_mul_f32_e32 v19, v11, v10
	v_add_f32_e32 v10, 1.0, v12
	v_rcp_f32_e32 v10, v10
	v_add_f32_e32 v11, 1.0, v13
	v_rcp_f32_e32 v11, v11
	v_pk_add_f32 v[6:7], v[6:7], v[62:63]
	v_lshlrev_b32_e32 v12, 16, v73
	v_mul_f32_e32 v6, 0xbfb8aa3b, v6
	v_pk_add_f32 v[8:9], v[8:9], v[64:65]
	v_exp_f32_e32 v6, v6
	v_mul_f32_e32 v7, 0xbfb8aa3b, v7
	v_mul_f32_e32 v13, v10, v12
	v_and_b32_e32 v10, 0xffff0000, v73
	v_exp_f32_e32 v7, v7
	v_mul_f32_e32 v8, 0xbfb8aa3b, v8
	v_mul_f32_e32 v20, v11, v10
	v_mul_f32_e32 v10, v15, v15
	v_mul_f32_e32 v11, v17, v17
	v_pk_add_f32 v[2:3], v[2:3], v[58:59]
	v_exp_f32_e32 v8, v8
	v_mul_f32_e32 v9, 0xbfb8aa3b, v9
	v_fmac_f32_e32 v10, v14, v14
	v_fmac_f32_e32 v11, v16, v16
	v_exp_f32_e32 v9, v9
	v_mul_f32_e32 v2, 0xbfb8aa3b, v2
	v_add_f32_e32 v10, v10, v11
	v_mul_f32_e32 v11, v19, v19
	v_add_f32_e32 v6, 1.0, v6
	v_exp_f32_e32 v2, v2
	v_mul_f32_e32 v3, 0xbfb8aa3b, v3
	v_fmac_f32_e32 v11, v18, v18
	v_rcp_f32_e32 v6, v6
	v_add_f32_e32 v7, 1.0, v7
	v_exp_f32_e32 v3, v3
	v_add_f32_e32 v10, v11, v10
	v_mul_f32_e32 v11, v20, v20
	v_rcp_f32_e32 v7, v7
	v_add_f32_e32 v8, 1.0, v8
	v_fmac_f32_e32 v11, v13, v13
	v_rcp_f32_e32 v8, v8
	v_add_f32_e32 v9, 1.0, v9
	v_add_f32_e32 v21, v11, v10
	v_cvt_pk_bf16_f32 v11, v16, v17
	v_pk_add_f32 v[4:5], v[4:5], v[60:61]
	s_waitcnt vmcnt(6)
	v_lshlrev_b32_e32 v16, 16, v66
	v_rcp_f32_e32 v9, v9
	v_add_f32_e32 v2, 1.0, v2
	v_mul_f32_e32 v6, v6, v16
	v_and_b32_e32 v16, 0xffff0000, v66
	v_rcp_f32_e32 v2, v2
	v_add_f32_e32 v3, 1.0, v3
	v_mul_f32_e32 v4, 0xbfb8aa3b, v4
	v_mul_f32_e32 v7, v7, v16
	v_lshlrev_b32_e32 v16, 16, v67
	v_rcp_f32_e32 v3, v3
	v_exp_f32_e32 v4, v4
	v_mul_f32_e32 v5, 0xbfb8aa3b, v5
	v_mul_f32_e32 v16, v8, v16
	v_and_b32_e32 v8, 0xffff0000, v67
	v_exp_f32_e32 v5, v5
	v_mul_f32_e32 v17, v9, v8
	v_lshlrev_b32_e32 v8, 16, v68
	v_cvt_pk_bf16_f32 v12, v18, v19
	v_mul_f32_e32 v18, v2, v8
	v_and_b32_e32 v2, 0xffff0000, v68
	v_mul_f32_e32 v19, v3, v2
	v_add_f32_e32 v2, 1.0, v4
	v_rcp_f32_e32 v2, v2
	v_add_f32_e32 v3, 1.0, v5
	v_rcp_f32_e32 v3, v3
	v_lshlrev_b32_e32 v4, 16, v69
	v_cvt_pk_bf16_f32 v13, v13, v20
	v_mul_f32_e32 v20, v2, v4
	v_and_b32_e32 v2, 0xffff0000, v69
	v_mul_f32_e32 v22, v3, v2
	v_mul_f32_e32 v2, v7, v7
	v_mul_f32_e32 v3, v17, v17
	v_fmac_f32_e32 v2, v6, v6
	v_fmac_f32_e32 v3, v16, v16
	v_add_f32_e32 v2, v2, v3
	v_mul_f32_e32 v3, v19, v19
	v_fmac_f32_e32 v3, v18, v18
	v_add_f32_e32 v2, v3, v2
	v_mul_f32_e32 v3, v22, v22
	v_fmac_f32_e32 v3, v20, v20
	v_add_f32_e32 v2, v3, v2
	v_add_f32_e32 v5, v21, v2
	ds_bpermute_b32 v0, v0, v5
	v_cvt_pk_bf16_f32 v10, v14, v15
	v_lshlrev_b64 v[14:15], 11, v[100:101]
	v_lshl_add_u64 v[2:3], s[70:71], 0, v[14:15]
	v_lshl_add_u64 v[8:9], v[206:207], 1, v[2:3]
	s_waitcnt lgkmcnt(0)
	v_add_f32_e32 v0, v5, v0
	ds_bpermute_b32 v2, v130, v0
	global_store_dwordx4 v[8:9], v[10:13], off sc1
	v_cvt_pk_bf16_f32 v4, v6, v7
	v_cvt_pk_bf16_f32 v5, v16, v17
	v_cvt_pk_bf16_f32 v6, v18, v19
	v_cvt_pk_bf16_f32 v7, v20, v22
	global_store_dwordx4 v[8:9], v[4:7], off offset:256 sc1
	s_and_saveexec_b64 s[10:11], vcc
	s_cbranch_execz .LBB0_760
	v_lshl_add_u64 v[4:5], s[78:79], 0, v[98:99]
	v_lshl_add_u64 v[4:5], s[54:55], 2, v[4:5]
	s_lshl_b32 s62, s85, 2
	v_lshl_add_u64 v[4:5], v[4:5], 0, s[62:63]
	s_waitcnt lgkmcnt(0)
	v_add_f32_e32 v0, v0, v2
	global_store_dword v[4:5], v0, off

; __device__ __forceinline__ unsigned xb_add(unsigned* p, unsigned v) { return __hip_atomic_fetch_add(p, v, __ATOMIC_RELAXED, __HIP_MEMORY_SCOPE_AGENT); }
; __device__ __forceinline__ void xcd_barrier(unsigned* bar, volatile LAS unsigned* st) {
;     ...
;         const unsigned old = xb_add(&bar[XB_XSUB(x)], 1u);
;         const unsigned gen = old / nloc;
;         if (old + 1u == (gen + 1u) * nloc) {
;             __builtin_amdgcn_fence(__ATOMIC_RELEASE, "agent");
;             asm volatile("s_waitcnt vmcnt(0)" ::: "memory");
;             const unsigned og = xb_add(&bar[XB_TOP], 1u);
.LBB0_920:
	s_andn2_saveexec_b64 s[10:11], s[10:11]
	s_cbranch_execz .LBB0_195
	s_mov_b64 s[10:11], exec
	s_waitcnt lgkmcnt(0)
	s_cmp_lg_u32 s98, 0
	s_cbranch_scc1 .Lxl_nowb_wout
	buffer_wbl2 sc1
	s_waitcnt vmcnt(0)
.Lxl_nowb_wout:
	v_mbcnt_lo_u32_b32 v0, s10, 0
	v_mbcnt_hi_u32_b32 v0, s11, v0
	v_cmp_eq_u32_e32 vcc, 0, v0
	s_and_saveexec_b64 s[12:13], vcc
	s_cbranch_execz .LBB0_923
	s_bcnt1_i32_b64 s10, s[10:11]
	v_mov_b32_e32 v3, s10
	v_mov_b32_e32 v4, 0x12b93000
	global_atomic_add v3, v4, v3, s[6:7] offset:1024 sc0
